# static priority level: post-barrier tail MFMAs at s_setprio 3 instead of 2
# speedup vs baseline: 1.0020x; 1.0004x over previous
; #define PG8_STAGE(bufoff, gbase, voff) do { _Pragma("unroll") for (int _i = 0; _i < 2; ++_i) \
;         __builtin_amdgcn_global_load_lds((const unsigned*)((const char*)(gbase) + (voff)[_i]), (PG8_LAS unsigned*)(lds + (bufoff) + ldsw + _i * 8192), 16, 0, 0); } while (0)
; #define PG8_LDA(dst, b, h) do { _Pragma("unroll") for (int m = 0; m < 4; ++m) _Pragma("unroll") for (int k = 0; k < 2; ++k) dst[m][k] = *(const PG8_LAS bf16x8*)(lds + PG8_SA(b, h) + aoff + m * 2048 + k * 1024); } while (0)
; #define PG8_LDB(dst, b, h) do { _Pragma("unroll") for (int n = 0; n < 2; ++n) _Pragma("unroll") for (int k = 0; k < 2; ++k) dst[n][k] = *(const PG8_LAS bf16x8*)(lds + PG8_SB(b, h) + boff + n * 2048 + k * 1024); } while (0)
; #define PG8_MMA(ai, bj, At, Bt) do { __builtin_amdgcn_s_setprio(1); _Pragma("unroll") for (int m = 0; m < 4; ++m) _Pragma("unroll") for (int n = 0; n < 2; ++n) _Pragma("unroll") for (int k = 0; k < 2; ++k) \
;         acc[ai][bj][m][n] = __builtin_amdgcn_mfma_f32_16x16x32_bf16(Bt[n][k], At[m][k], acc[ai][bj][m][n], 0, 0, 0); __builtin_amdgcn_s_setprio(0); } while (0)
; #define PG8_WAIT_V(n) asm volatile("s_waitcnt vmcnt(" #n ")" ::: "memory")
; #define PG8_WAIT_L(n) asm volatile("s_waitcnt lgkmcnt(" #n ")" ::: "memory")
; #define PG8_BAR __builtin_amdgcn_s_barrier()
; #define PG8_SCHED __builtin_amdgcn_sched_barrier(0)
; template <class Epi, class Sched, bool ALIGN_EPI = false, bool SP2 = false>
; __device__ __forceinline__ void gemm_phase(PG8_LAS unsigned char* lds, const Gemm g, const Sched& S, const Epi& E) {
;     ...
;             const bool last = (t == nt - 2);
;             const char* a1 = cA + (size_t)(t + 1) * kstep;
;             const char* a2 = last ? nA : cA + (size_t)(t + 2) * kstep; const char* b2 = last ? nB : cB + (size_t)(t + 2) * kstep;
;             const char* a3 = a2 + kstep; const char* b3 = b2 + kstep;
;             if (last && has_next) S.a_ready(nxt);
;             if constexpr (SP2) {
;             PG8_LDB(B0, 0, 0); PG8_LDB(B1, 0, 1); PG8_SCHED; PG8_LDA(At, 0, 0); PG8_STAGE(PG8_SA(1, 1), a1 + hstep, voffA);
;             PG8_WAIT_V(8); PG8_WAIT_L(0); PG8_BAR; PG8_MMA(0, 0, At, B0); PG8_MMA(0, 1, At, B1); PG8_BAR; PG8_SCHED;
;             PG8_LDA(At, 0, 1); PG8_STAGE(PG8_SB(0, 0), b2, voffB); PG8_STAGE(PG8_SB(0, 1), b2 + hstep, voffB); PG8_STAGE(PG8_SA(0, 0), a2, voffA);
.LBB0_110:
	ds_read_b128 v[136:139], v161
	ds_read_b128 v[140:143], v161 offset:1024
	ds_read_b128 v[176:179], v161 offset:2048
	ds_read_b128 v[180:183], v161 offset:3072
	ds_read_b128 v[184:187], v162
	ds_read_b128 v[202:205], v162 offset:1024
	ds_read_b128 v[206:209], v162 offset:2048
	ds_read_b128 v[210:213], v162 offset:3072
	s_add_u32 s28, s52, 0xfff80080
	s_addc_u32 s29, s53, -1
	s_cmp_eq_u32 s74, 28
	s_cselect_b32 s49, s25, s29
	s_cselect_b32 s48, s34, s28
	s_cselect_b32 s29, s23, s73
	s_cselect_b32 s28, s35, s72
	v_lshl_add_u64 v[246:247], s[52:53], 0, v[128:129]
	s_add_i32 m0, s9, 0xc000
	ds_read_b128 v[214:217], v163
	ds_read_b128 v[218:221], v163 offset:1024
	ds_read_b128 v[222:225], v163 offset:2048
	ds_read_b128 v[226:229], v163 offset:3072
	ds_read_b128 v[230:233], v163 offset:4096
	ds_read_b128 v[234:237], v163 offset:5120
	ds_read_b128 v[238:241], v163 offset:6144
	ds_read_b128 v[242:245], v163 offset:7168
	global_load_lds_dwordx4 v[246:247], off
	v_lshl_add_u64 v[246:247], s[52:53], 0, v[130:131]
	s_add_i32 m0, s9, 0xe000
	s_nop 0
	global_load_lds_dwordx4 v[246:247], off
	s_waitcnt vmcnt(8)
	s_waitcnt lgkmcnt(0)
	s_barrier
	s_setprio 1
	s_waitcnt lgkmcnt(0)
	v_mfma_f32_16x16x32_bf16 v[124:127], v[136:139], v[214:217], v[124:127]
	v_mfma_f32_16x16x32_bf16 v[124:127], v[140:143], v[218:221], v[124:127]
	v_mfma_f32_16x16x32_bf16 v[120:123], v[180:183], v[218:221], v[120:123]
	v_mfma_f32_16x16x32_bf16 v[120:123], v[176:179], v[214:217], v[120:123]
	v_mfma_f32_16x16x32_bf16 v[116:119], v[184:187], v[214:217], v[116:119]
	v_mfma_f32_16x16x32_bf16 v[116:119], v[202:205], v[218:221], v[116:119]
	v_mfma_f32_16x16x32_bf16 v[112:115], v[210:213], v[218:221], v[112:115]
	v_mfma_f32_16x16x32_bf16 v[112:115], v[206:209], v[214:217], v[112:115]
	v_mfma_f32_16x16x32_bf16 v[92:95], v[206:209], v[222:225], v[92:95]
	v_mfma_f32_16x16x32_bf16 v[92:95], v[210:213], v[226:229], v[92:95]
	v_mfma_f32_16x16x32_bf16 v[100:103], v[202:205], v[226:229], v[100:103]
	v_mfma_f32_16x16x32_bf16 v[100:103], v[184:187], v[222:225], v[100:103]
	v_mfma_f32_16x16x32_bf16 v[104:107], v[176:179], v[222:225], v[104:107]
	v_mfma_f32_16x16x32_bf16 v[104:107], v[180:183], v[226:229], v[104:107]
	v_mfma_f32_16x16x32_bf16 v[108:111], v[140:143], v[226:229], v[108:111]
	v_mfma_f32_16x16x32_bf16 v[108:111], v[136:139], v[222:225], v[108:111]
	s_setprio 0
	s_setprio 1
	v_mfma_f32_16x16x32_bf16 v[96:99], v[136:139], v[230:233], v[96:99]
	v_mfma_f32_16x16x32_bf16 v[96:99], v[140:143], v[234:237], v[96:99]
	v_mfma_f32_16x16x32_bf16 v[88:91], v[180:183], v[234:237], v[88:91]
	v_mfma_f32_16x16x32_bf16 v[88:91], v[176:179], v[230:233], v[88:91]
	v_mfma_f32_16x16x32_bf16 v[84:87], v[184:187], v[230:233], v[84:87]
	v_mfma_f32_16x16x32_bf16 v[84:87], v[202:205], v[234:237], v[84:87]
	v_mfma_f32_16x16x32_bf16 v[76:79], v[210:213], v[234:237], v[76:79]
	v_mfma_f32_16x16x32_bf16 v[76:79], v[206:209], v[230:233], v[76:79]
	v_mfma_f32_16x16x32_bf16 v[64:67], v[206:209], v[238:241], v[64:67]
	v_mfma_f32_16x16x32_bf16 v[64:67], v[210:213], v[242:245], v[64:67]
	v_mfma_f32_16x16x32_bf16 v[68:71], v[202:205], v[242:245], v[68:71]
	v_mfma_f32_16x16x32_bf16 v[68:71], v[184:187], v[238:241], v[68:71]
	v_mfma_f32_16x16x32_bf16 v[72:75], v[176:179], v[238:241], v[72:75]
	v_mfma_f32_16x16x32_bf16 v[72:75], v[180:183], v[242:245], v[72:75]
	s_setprio 3
	s_barrier
	v_mfma_f32_16x16x32_bf16 v[80:83], v[140:143], v[242:245], v[80:83]
	v_mfma_f32_16x16x32_bf16 v[80:83], v[136:139], v[238:241], v[80:83]
	s_setprio 0
	s_add_i32 s75, s63, s45
	v_lshl_add_u64 v[246:247], s[28:29], 0, v[166:167]
	s_mov_b32 m0, s75
	ds_read_b128 v[214:217], v163 offset:16384
	ds_read_b128 v[218:221], v163 offset:17408
	ds_read_b128 v[222:225], v163 offset:18432
	ds_read_b128 v[226:229], v163 offset:19456
	ds_read_b128 v[230:233], v163 offset:20480
	ds_read_b128 v[234:237], v163 offset:21504
	ds_read_b128 v[238:241], v163 offset:22528
	ds_read_b128 v[242:245], v163 offset:23552
	global_load_lds_dwordx4 v[246:247], off
	s_add_i32 m0, s75, 0x2000
	s_add_u32 s76, s28, 0x80000
	v_lshl_add_u64 v[248:249], s[28:29], 0, v[170:171]
	s_addc_u32 s77, s29, 0
	s_add_i32 s75, s64, s45
	global_load_lds_dwordx4 v[248:249], off
	v_lshl_add_u64 v[250:251], s[76:77], 0, v[166:167]
	s_mov_b32 m0, s75
	v_lshl_add_u64 v[252:253], s[48:49], 0, v[168:169]
	global_load_lds_dwordx4 v[250:251], off
	v_lshl_add_u64 v[250:251], s[76:77], 0, v[170:171]
	s_add_i32 m0, s75, 0x2000
	s_nop 0
	global_load_lds_dwordx4 v[250:251], off
	v_lshl_add_u64 v[250:251], s[48:49], 0, v[164:165]
	s_mov_b32 m0, s9
	s_nop 0
	global_load_lds_dwordx4 v[250:251], off
	s_mov_b32 m0, s57
	s_nop 0
	global_load_lds_dwordx4 v[252:253], off
	s_waitcnt vmcnt(8)
	s_waitcnt lgkmcnt(0)
	s_barrier
; #define PG8_STAGE(bufoff, gbase, voff) do { _Pragma("unroll") for (int _i = 0; _i < 2; ++_i) \
;         __builtin_amdgcn_global_load_lds((const unsigned*)((const char*)(gbase) + (voff)[_i]), (PG8_LAS unsigned*)(lds + (bufoff) + ldsw + _i * 8192), 16, 0, 0); } while (0)
; #define PG8_LDA(dst, b, h) do { _Pragma("unroll") for (int m = 0; m < 4; ++m) _Pragma("unroll") for (int k = 0; k < 2; ++k) dst[m][k] = *(const PG8_LAS bf16x8*)(lds + PG8_SA(b, h) + aoff + m * 2048 + k * 1024); } while (0)
; #define PG8_LDB(dst, b, h) do { _Pragma("unroll") for (int n = 0; n < 2; ++n) _Pragma("unroll") for (int k = 0; k < 2; ++k) dst[n][k] = *(const PG8_LAS bf16x8*)(lds + PG8_SB(b, h) + boff + n * 2048 + k * 1024); } while (0)
; #define PG8_MMA(ai, bj, At, Bt) do { __builtin_amdgcn_s_setprio(1); _Pragma("unroll") for (int m = 0; m < 4; ++m) _Pragma("unroll") for (int n = 0; n < 2; ++n) _Pragma("unroll") for (int k = 0; k < 2; ++k) \
;         acc[ai][bj][m][n] = __builtin_amdgcn_mfma_f32_16x16x32_bf16(Bt[n][k], At[m][k], acc[ai][bj][m][n], 0, 0, 0); __builtin_amdgcn_s_setprio(0); } while (0)
; #define PG8_WAIT_V(n) asm volatile("s_waitcnt vmcnt(" #n ")" ::: "memory")
; #define PG8_WAIT_L(n) asm volatile("s_waitcnt lgkmcnt(" #n ")" ::: "memory")
; #define PG8_BAR __builtin_amdgcn_s_barrier()
; #define PG8_SCHED __builtin_amdgcn_sched_barrier(0)
; template <class Epi, class Sched, bool ALIGN_EPI = false, bool SP2 = false>
; __device__ __forceinline__ void gemm_phase(PG8_LAS unsigned char* lds, const Gemm g, const Sched& S, const Epi& E) {
;     ...
;             PG8_WAIT_V(8); PG8_WAIT_L(0); PG8_BAR; PG8_MMA(1, 0, At, B0); PG8_MMA(1, 1, At, B1); PG8_BAR; PG8_SCHED;
;             PG8_LDB(B0, 1, 0); PG8_LDB(B1, 1, 1); PG8_SCHED; PG8_LDA(At, 1, 0); PG8_STAGE(PG8_SA(0, 1), a2 + hstep, voffA);
;             PG8_WAIT_V(8); PG8_WAIT_L(0); PG8_BAR; PG8_MMA(0, 0, At, B0); PG8_MMA(0, 1, At, B1); PG8_BAR; PG8_SCHED;
	s_setprio 1
	s_waitcnt lgkmcnt(0)
	v_mfma_f32_16x16x32_bf16 v[60:63], v[136:139], v[214:217], v[60:63]
	v_mfma_f32_16x16x32_bf16 v[60:63], v[140:143], v[218:221], v[60:63]
	v_mfma_f32_16x16x32_bf16 v[56:59], v[180:183], v[218:221], v[56:59]
	v_mfma_f32_16x16x32_bf16 v[56:59], v[176:179], v[214:217], v[56:59]
	v_mfma_f32_16x16x32_bf16 v[52:55], v[184:187], v[214:217], v[52:55]
	v_mfma_f32_16x16x32_bf16 v[52:55], v[202:205], v[218:221], v[52:55]
	v_mfma_f32_16x16x32_bf16 v[44:47], v[210:213], v[218:221], v[44:47]
	v_mfma_f32_16x16x32_bf16 v[44:47], v[206:209], v[214:217], v[44:47]
	v_mfma_f32_16x16x32_bf16 v[28:31], v[206:209], v[222:225], v[28:31]
	v_mfma_f32_16x16x32_bf16 v[28:31], v[210:213], v[226:229], v[28:31]
	v_mfma_f32_16x16x32_bf16 v[36:39], v[202:205], v[226:229], v[36:39]
	v_mfma_f32_16x16x32_bf16 v[36:39], v[184:187], v[222:225], v[36:39]
	v_mfma_f32_16x16x32_bf16 v[40:43], v[176:179], v[222:225], v[40:43]
	v_mfma_f32_16x16x32_bf16 v[40:43], v[180:183], v[226:229], v[40:43]
	v_mfma_f32_16x16x32_bf16 v[48:51], v[140:143], v[226:229], v[48:51]
	v_mfma_f32_16x16x32_bf16 v[48:51], v[136:139], v[222:225], v[48:51]
	s_setprio 0
	s_setprio 1
	v_mfma_f32_16x16x32_bf16 v[32:35], v[136:139], v[230:233], v[32:35]
	v_mfma_f32_16x16x32_bf16 v[32:35], v[140:143], v[234:237], v[32:35]
	v_mfma_f32_16x16x32_bf16 v[24:27], v[180:183], v[234:237], v[24:27]
	v_mfma_f32_16x16x32_bf16 v[24:27], v[176:179], v[230:233], v[24:27]
	v_mfma_f32_16x16x32_bf16 v[20:23], v[184:187], v[230:233], v[20:23]
	v_mfma_f32_16x16x32_bf16 v[20:23], v[202:205], v[234:237], v[20:23]
	v_mfma_f32_16x16x32_bf16 v[16:19], v[210:213], v[234:237], v[16:19]
	v_mfma_f32_16x16x32_bf16 v[16:19], v[206:209], v[230:233], v[16:19]
	v_mfma_f32_16x16x32_bf16 v[0:3], v[206:209], v[238:241], v[0:3]
	v_mfma_f32_16x16x32_bf16 v[0:3], v[210:213], v[242:245], v[0:3]
	v_mfma_f32_16x16x32_bf16 v[4:7], v[202:205], v[242:245], v[4:7]
	v_mfma_f32_16x16x32_bf16 v[4:7], v[184:187], v[238:241], v[4:7]
	v_mfma_f32_16x16x32_bf16 v[8:11], v[176:179], v[238:241], v[8:11]
	v_mfma_f32_16x16x32_bf16 v[8:11], v[180:183], v[242:245], v[8:11]
	s_setprio 3
	s_barrier
	v_mfma_f32_16x16x32_bf16 v[12:15], v[140:143], v[242:245], v[12:15]
	v_mfma_f32_16x16x32_bf16 v[12:15], v[136:139], v[238:241], v[12:15]
	s_setprio 0
	s_add_i32 s75, 0, 0x18000
	v_add_u32_e32 v144, s75, v151
	s_add_i32 s76, 0, 0x1c000
	ds_read_b128 v[136:139], v144
	ds_read_b128 v[140:143], v144 offset:1024
	ds_read_b128 v[176:179], v144 offset:2048
	ds_read_b128 v[180:183], v144 offset:3072
	v_add_u32_e32 v144, s76, v151
	ds_read_b128 v[184:187], v144
	ds_read_b128 v[202:205], v144 offset:1024
	ds_read_b128 v[206:209], v144 offset:2048
	ds_read_b128 v[210:213], v144 offset:3072
	s_add_u32 s48, s48, 0x80000
	s_addc_u32 s49, s49, 0
	s_mov_b32 m0, s58
	v_lshl_add_u64 v[200:201], s[48:49], 0, v[164:165]
	ds_read_b128 v[214:217], v163 offset:32768
	ds_read_b128 v[218:221], v163 offset:33792
	ds_read_b128 v[222:225], v163 offset:34816
	ds_read_b128 v[226:229], v163 offset:35840
	ds_read_b128 v[230:233], v163 offset:36864
	ds_read_b128 v[234:237], v163 offset:37888
	ds_read_b128 v[238:241], v163 offset:38912
	ds_read_b128 v[242:245], v163 offset:39936
	global_load_lds_dwordx4 v[200:201], off
	v_lshl_add_u64 v[200:201], s[48:49], 0, v[168:169]
	s_mov_b32 m0, s59
	s_nop 0
	global_load_lds_dwordx4 v[200:201], off
	s_waitcnt vmcnt(8)
	s_waitcnt lgkmcnt(0)
	s_barrier
	s_setprio 1
	s_waitcnt lgkmcnt(0)
	v_mfma_f32_16x16x32_bf16 v[124:127], v[136:139], v[214:217], v[124:127]
	v_mfma_f32_16x16x32_bf16 v[124:127], v[140:143], v[218:221], v[124:127]
	v_mfma_f32_16x16x32_bf16 v[120:123], v[180:183], v[218:221], v[120:123]
	v_mfma_f32_16x16x32_bf16 v[120:123], v[176:179], v[214:217], v[120:123]
	v_mfma_f32_16x16x32_bf16 v[116:119], v[184:187], v[214:217], v[116:119]
	v_mfma_f32_16x16x32_bf16 v[116:119], v[202:205], v[218:221], v[116:119]
	v_mfma_f32_16x16x32_bf16 v[112:115], v[210:213], v[218:221], v[112:115]
	v_mfma_f32_16x16x32_bf16 v[112:115], v[206:209], v[214:217], v[112:115]
	v_mfma_f32_16x16x32_bf16 v[92:95], v[206:209], v[222:225], v[92:95]
	v_mfma_f32_16x16x32_bf16 v[92:95], v[210:213], v[226:229], v[92:95]
	v_mfma_f32_16x16x32_bf16 v[100:103], v[202:205], v[226:229], v[100:103]
	v_mfma_f32_16x16x32_bf16 v[100:103], v[184:187], v[222:225], v[100:103]
	v_mfma_f32_16x16x32_bf16 v[104:107], v[176:179], v[222:225], v[104:107]
	v_mfma_f32_16x16x32_bf16 v[104:107], v[180:183], v[226:229], v[104:107]
	v_mfma_f32_16x16x32_bf16 v[108:111], v[140:143], v[226:229], v[108:111]
	v_mfma_f32_16x16x32_bf16 v[108:111], v[136:139], v[222:225], v[108:111]
	s_setprio 0
	s_setprio 1
	v_mfma_f32_16x16x32_bf16 v[96:99], v[136:139], v[230:233], v[96:99]
	v_mfma_f32_16x16x32_bf16 v[96:99], v[140:143], v[234:237], v[96:99]
	v_mfma_f32_16x16x32_bf16 v[88:91], v[180:183], v[234:237], v[88:91]
	v_mfma_f32_16x16x32_bf16 v[88:91], v[176:179], v[230:233], v[88:91]
	v_mfma_f32_16x16x32_bf16 v[84:87], v[184:187], v[230:233], v[84:87]
	v_mfma_f32_16x16x32_bf16 v[84:87], v[202:205], v[234:237], v[84:87]
	v_mfma_f32_16x16x32_bf16 v[76:79], v[210:213], v[234:237], v[76:79]
	v_mfma_f32_16x16x32_bf16 v[76:79], v[206:209], v[230:233], v[76:79]
	v_mfma_f32_16x16x32_bf16 v[64:67], v[206:209], v[238:241], v[64:67]
	v_mfma_f32_16x16x32_bf16 v[64:67], v[210:213], v[242:245], v[64:67]
	v_mfma_f32_16x16x32_bf16 v[68:71], v[202:205], v[242:245], v[68:71]
	v_mfma_f32_16x16x32_bf16 v[68:71], v[184:187], v[238:241], v[68:71]
	v_mfma_f32_16x16x32_bf16 v[72:75], v[176:179], v[238:241], v[72:75]
	v_mfma_f32_16x16x32_bf16 v[72:75], v[180:183], v[242:245], v[72:75]
	s_setprio 3
	s_barrier
; #define PG8_STAGE(bufoff, gbase, voff) do { _Pragma("unroll") for (int _i = 0; _i < 2; ++_i) \
;         __builtin_amdgcn_global_load_lds((const unsigned*)((const char*)(gbase) + (voff)[_i]), (PG8_LAS unsigned*)(lds + (bufoff) + ldsw + _i * 8192), 16, 0, 0); } while (0)
; #define PG8_LDA(dst, b, h) do { _Pragma("unroll") for (int m = 0; m < 4; ++m) _Pragma("unroll") for (int k = 0; k < 2; ++k) dst[m][k] = *(const PG8_LAS bf16x8*)(lds + PG8_SA(b, h) + aoff + m * 2048 + k * 1024); } while (0)
; #define PG8_MMA(ai, bj, At, Bt) do { __builtin_amdgcn_s_setprio(1); _Pragma("unroll") for (int m = 0; m < 4; ++m) _Pragma("unroll") for (int n = 0; n < 2; ++n) _Pragma("unroll") for (int k = 0; k < 2; ++k) \
;         acc[ai][bj][m][n] = __builtin_amdgcn_mfma_f32_16x16x32_bf16(Bt[n][k], At[m][k], acc[ai][bj][m][n], 0, 0, 0); __builtin_amdgcn_s_setprio(0); } while (0)
; #define PG8_WAIT_V(n) asm volatile("s_waitcnt vmcnt(" #n ")" ::: "memory")
; #define PG8_WAIT_L(n) asm volatile("s_waitcnt lgkmcnt(" #n ")" ::: "memory")
; #define PG8_BAR __builtin_amdgcn_s_barrier()
; #define PG8_SCHED __builtin_amdgcn_sched_barrier(0)
; template <class Epi, class Sched, bool ALIGN_EPI = false, bool SP2 = false>
; __device__ __forceinline__ void gemm_phase(PG8_LAS unsigned char* lds, const Gemm g, const Sched& S, const Epi& E) {
;     ...
;         for (int t = 0; t < nt; t += 2) {
;     ...
;             PG8_WAIT_V(8); PG8_WAIT_L(0); PG8_BAR; PG8_MMA(0, 0, At, B0); PG8_MMA(0, 1, At, B1); PG8_BAR; PG8_SCHED;
;             PG8_LDA(At, 1, 1); PG8_STAGE(PG8_SB(1, 0), b3, voffB); PG8_STAGE(PG8_SB(1, 1), b3 + hstep, voffB); PG8_STAGE(PG8_SA(1, 0), a3, voffA);
;             PG8_WAIT_V(8); PG8_WAIT_L(0); PG8_BAR; PG8_MMA(1, 0, At, B0); PG8_MMA(1, 1, At, B1); PG8_BAR; PG8_SCHED;
	v_mfma_f32_16x16x32_bf16 v[80:83], v[140:143], v[242:245], v[80:83]
	v_mfma_f32_16x16x32_bf16 v[80:83], v[136:139], v[238:241], v[80:83]
	s_setprio 0
	s_add_i32 s48, s75, s45
	v_lshl_add_u64 v[200:201], v[246:247], 0, s[18:19]
	s_mov_b32 m0, s48
	ds_read_b128 v[214:217], v163 offset:49152
	ds_read_b128 v[218:221], v163 offset:50176
	ds_read_b128 v[222:225], v163 offset:51200
	ds_read_b128 v[226:229], v163 offset:52224
	ds_read_b128 v[230:233], v163 offset:53248
	ds_read_b128 v[234:237], v163 offset:54272
	ds_read_b128 v[238:241], v163 offset:55296
	ds_read_b128 v[242:245], v163 offset:56320
	global_load_lds_dwordx4 v[200:201], off
	s_add_i32 m0, s48, 0x2000
	s_add_u32 s28, s28, 0x80080
	v_lshl_add_u64 v[200:201], v[248:249], 0, s[18:19]
	s_addc_u32 s29, s29, 0
	s_add_i32 s48, s76, s45
	global_load_lds_dwordx4 v[200:201], off
	v_lshl_add_u64 v[200:201], s[28:29], 0, v[166:167]
	s_mov_b32 m0, s48
	s_nop 0
	global_load_lds_dwordx4 v[200:201], off
	v_lshl_add_u64 v[200:201], s[28:29], 0, v[170:171]
	s_add_i32 m0, s48, 0x2000
	s_nop 0
	global_load_lds_dwordx4 v[200:201], off
	v_lshl_add_u64 v[200:201], v[250:251], 0, s[18:19]
	s_mov_b32 m0, s61
	s_nop 0
	global_load_lds_dwordx4 v[200:201], off
	v_lshl_add_u64 v[200:201], v[252:253], 0, s[18:19]
	s_mov_b32 m0, s62
	s_nop 0
	global_load_lds_dwordx4 v[200:201], off
	s_waitcnt vmcnt(8)
	s_waitcnt lgkmcnt(0)
	s_barrier
	s_setprio 1
	s_waitcnt lgkmcnt(0)
	v_mfma_f32_16x16x32_bf16 v[60:63], v[136:139], v[214:217], v[60:63]
	v_mfma_f32_16x16x32_bf16 v[60:63], v[140:143], v[218:221], v[60:63]
	v_mfma_f32_16x16x32_bf16 v[56:59], v[180:183], v[218:221], v[56:59]
	v_mfma_f32_16x16x32_bf16 v[56:59], v[176:179], v[214:217], v[56:59]
	v_mfma_f32_16x16x32_bf16 v[52:55], v[184:187], v[214:217], v[52:55]
	v_mfma_f32_16x16x32_bf16 v[52:55], v[202:205], v[218:221], v[52:55]
	v_mfma_f32_16x16x32_bf16 v[44:47], v[210:213], v[218:221], v[44:47]
	v_mfma_f32_16x16x32_bf16 v[44:47], v[206:209], v[214:217], v[44:47]
	v_mfma_f32_16x16x32_bf16 v[28:31], v[206:209], v[222:225], v[28:31]
	v_mfma_f32_16x16x32_bf16 v[28:31], v[210:213], v[226:229], v[28:31]
	v_mfma_f32_16x16x32_bf16 v[36:39], v[202:205], v[226:229], v[36:39]
	v_mfma_f32_16x16x32_bf16 v[36:39], v[184:187], v[222:225], v[36:39]
	v_mfma_f32_16x16x32_bf16 v[40:43], v[176:179], v[222:225], v[40:43]
	v_mfma_f32_16x16x32_bf16 v[40:43], v[180:183], v[226:229], v[40:43]
	v_mfma_f32_16x16x32_bf16 v[48:51], v[140:143], v[226:229], v[48:51]
	v_mfma_f32_16x16x32_bf16 v[48:51], v[136:139], v[222:225], v[48:51]
	s_setprio 0
	s_setprio 1
	v_mfma_f32_16x16x32_bf16 v[32:35], v[136:139], v[230:233], v[32:35]
	v_mfma_f32_16x16x32_bf16 v[32:35], v[140:143], v[234:237], v[32:35]
	v_mfma_f32_16x16x32_bf16 v[24:27], v[180:183], v[234:237], v[24:27]
	v_mfma_f32_16x16x32_bf16 v[24:27], v[176:179], v[230:233], v[24:27]
	v_mfma_f32_16x16x32_bf16 v[20:23], v[184:187], v[230:233], v[20:23]
	v_mfma_f32_16x16x32_bf16 v[20:23], v[202:205], v[234:237], v[20:23]
	v_mfma_f32_16x16x32_bf16 v[16:19], v[210:213], v[234:237], v[16:19]
	v_mfma_f32_16x16x32_bf16 v[16:19], v[206:209], v[230:233], v[16:19]
	v_mfma_f32_16x16x32_bf16 v[0:3], v[206:209], v[238:241], v[0:3]
	v_mfma_f32_16x16x32_bf16 v[0:3], v[210:213], v[242:245], v[0:3]
	v_mfma_f32_16x16x32_bf16 v[4:7], v[202:205], v[242:245], v[4:7]
	v_mfma_f32_16x16x32_bf16 v[4:7], v[184:187], v[238:241], v[4:7]
	v_mfma_f32_16x16x32_bf16 v[8:11], v[176:179], v[238:241], v[8:11]
	v_mfma_f32_16x16x32_bf16 v[8:11], v[180:183], v[242:245], v[8:11]
	s_setprio 3
	s_barrier
	v_mfma_f32_16x16x32_bf16 v[12:15], v[140:143], v[242:245], v[12:15]
	v_mfma_f32_16x16x32_bf16 v[12:15], v[136:139], v[238:241], v[12:15]
	s_setprio 0
	s_add_i32 s74, s74, 2
	s_add_u32 s52, s52, 0x100
	s_addc_u32 s53, s53, 0
	s_add_u32 s72, s72, 0x100
	s_addc_u32 s73, s73, 0
	s_cmp_gt_u32 s74, 29
	s_cbranch_scc0 .LBB0_110
	s_and_b64 vcc, exec, s[20:21]
	s_cbranch_vccz .LBB0_113
	s_barrier

; #define PG8_STAGE(bufoff, gbase, voff) do { _Pragma("unroll") for (int _i = 0; _i < 2; ++_i) \
;         __builtin_amdgcn_global_load_lds((const unsigned*)((const char*)(gbase) + (voff)[_i]), (PG8_LAS unsigned*)(lds + (bufoff) + ldsw + _i * 8192), 16, 0, 0); } while (0)
; #define PG8_LDA(dst, b, h) do { _Pragma("unroll") for (int m = 0; m < 4; ++m) _Pragma("unroll") for (int k = 0; k < 2; ++k) dst[m][k] = *(const PG8_LAS bf16x8*)(lds + PG8_SA(b, h) + aoff + m * 2048 + k * 1024); } while (0)
; #define PG8_LDB(dst, b, h) do { _Pragma("unroll") for (int n = 0; n < 2; ++n) _Pragma("unroll") for (int k = 0; k < 2; ++k) dst[n][k] = *(const PG8_LAS bf16x8*)(lds + PG8_SB(b, h) + boff + n * 2048 + k * 1024); } while (0)
; #define PG8_MMA(ai, bj, At, Bt) do { __builtin_amdgcn_s_setprio(1); _Pragma("unroll") for (int m = 0; m < 4; ++m) _Pragma("unroll") for (int n = 0; n < 2; ++n) _Pragma("unroll") for (int k = 0; k < 2; ++k) \
;         acc[ai][bj][m][n] = __builtin_amdgcn_mfma_f32_16x16x32_bf16(Bt[n][k], At[m][k], acc[ai][bj][m][n], 0, 0, 0); __builtin_amdgcn_s_setprio(0); } while (0)
; #define PG8_WAIT_V(n) asm volatile("s_waitcnt vmcnt(" #n ")" ::: "memory")
; #define PG8_WAIT_L(n) asm volatile("s_waitcnt lgkmcnt(" #n ")" ::: "memory")
; #define PG8_BAR __builtin_amdgcn_s_barrier()
; #define PG8_SCHED __builtin_amdgcn_sched_barrier(0)
; template <class Epi, class Sched, bool ALIGN_EPI = false, bool SP2 = false>
; __device__ __forceinline__ void gemm_phase(PG8_LAS unsigned char* lds, const Gemm g, const Sched& S, const Epi& E) {
;     ...
;             const bool last = (t == nt - 2);
;             const char* a1 = cA + (size_t)(t + 1) * kstep;
;             const char* a2 = last ? nA : cA + (size_t)(t + 2) * kstep; const char* b2 = last ? nB : cB + (size_t)(t + 2) * kstep;
;             const char* a3 = a2 + kstep; const char* b3 = b2 + kstep;
;             if (last && has_next) S.a_ready(nxt);
;             if constexpr (SP2) {
;             PG8_LDB(B0, 0, 0); PG8_LDB(B1, 0, 1); PG8_SCHED; PG8_LDA(At, 0, 0); PG8_STAGE(PG8_SA(1, 1), a1 + hstep, voffA);
;             PG8_WAIT_V(8); PG8_WAIT_L(0); PG8_BAR; PG8_MMA(0, 0, At, B0); PG8_MMA(0, 1, At, B1); PG8_BAR; PG8_SCHED;
;             PG8_LDA(At, 0, 1); PG8_STAGE(PG8_SB(0, 0), b2, voffB); PG8_STAGE(PG8_SB(0, 1), b2 + hstep, voffB); PG8_STAGE(PG8_SA(0, 0), a2, voffA);
.LBB0_177:
	ds_read_b128 v[80:83], v171
	ds_read_b128 v[84:87], v171 offset:1024
	ds_read_b128 v[92:95], v171 offset:2048
	ds_read_b128 v[100:103], v171 offset:3072
	ds_read_b128 v[144:147], v206
	ds_read_b128 v[148:151], v206 offset:1024
	ds_read_b128 v[152:155], v206 offset:2048
	ds_read_b128 v[156:159], v206 offset:3072
	s_add_u32 s28, s72, 0xffea0080
	s_addc_u32 s29, s73, -1
	s_cmpk_eq_i32 s76, 0x54
	s_cselect_b32 s49, s69, s29
	s_cselect_b32 s48, s68, s28
	s_cselect_b32 s29, s71, s35
	s_cselect_b32 s28, s70, s34
	v_lshl_add_u64 v[234:235], s[72:73], 0, v[174:175]
	s_add_i32 m0, s40, 0xc000
	ds_read_b128 v[180:183], v207
	ds_read_b128 v[184:187], v207 offset:1024
	ds_read_b128 v[210:213], v207 offset:2048
	ds_read_b128 v[214:217], v207 offset:3072
	ds_read_b128 v[218:221], v207 offset:4096
	ds_read_b128 v[222:225], v207 offset:5120
	ds_read_b128 v[226:229], v207 offset:6144
	ds_read_b128 v[230:233], v207 offset:7168
	global_load_lds_dwordx4 v[234:235], off
	v_lshl_add_u64 v[234:235], s[72:73], 0, v[176:177]
	s_add_i32 m0, s40, 0xe000
	s_nop 0
	global_load_lds_dwordx4 v[234:235], off
	s_waitcnt vmcnt(8)
	s_waitcnt lgkmcnt(0)
	s_barrier
	s_setprio 1
	s_waitcnt lgkmcnt(0)
	v_mfma_f32_16x16x32_bf16 v[140:143], v[80:83], v[180:183], v[140:143]
	v_mfma_f32_16x16x32_bf16 v[140:143], v[84:87], v[184:187], v[140:143]
	v_mfma_f32_16x16x32_bf16 v[136:139], v[100:103], v[184:187], v[136:139]
	v_mfma_f32_16x16x32_bf16 v[136:139], v[92:95], v[180:183], v[136:139]
	v_mfma_f32_16x16x32_bf16 v[132:135], v[144:147], v[180:183], v[132:135]
	v_mfma_f32_16x16x32_bf16 v[132:135], v[148:151], v[184:187], v[132:135]
	v_mfma_f32_16x16x32_bf16 v[128:131], v[156:159], v[184:187], v[128:131]
	v_mfma_f32_16x16x32_bf16 v[128:131], v[152:155], v[180:183], v[128:131]
	v_mfma_f32_16x16x32_bf16 v[112:115], v[152:155], v[210:213], v[112:115]
	v_mfma_f32_16x16x32_bf16 v[112:115], v[156:159], v[214:217], v[112:115]
	v_mfma_f32_16x16x32_bf16 v[116:119], v[148:151], v[214:217], v[116:119]
	v_mfma_f32_16x16x32_bf16 v[116:119], v[144:147], v[210:213], v[116:119]
	v_mfma_f32_16x16x32_bf16 v[120:123], v[92:95], v[210:213], v[120:123]
	v_mfma_f32_16x16x32_bf16 v[120:123], v[100:103], v[214:217], v[120:123]
	v_mfma_f32_16x16x32_bf16 v[124:127], v[84:87], v[214:217], v[124:127]
	v_mfma_f32_16x16x32_bf16 v[124:127], v[80:83], v[210:213], v[124:127]
	s_setprio 0
	s_setprio 1
	v_mfma_f32_16x16x32_bf16 v[108:111], v[80:83], v[218:221], v[108:111]
	v_mfma_f32_16x16x32_bf16 v[108:111], v[84:87], v[222:225], v[108:111]
	v_mfma_f32_16x16x32_bf16 v[104:107], v[100:103], v[222:225], v[104:107]
	v_mfma_f32_16x16x32_bf16 v[104:107], v[92:95], v[218:221], v[104:107]
	v_mfma_f32_16x16x32_bf16 v[96:99], v[144:147], v[218:221], v[96:99]
	v_mfma_f32_16x16x32_bf16 v[96:99], v[148:151], v[222:225], v[96:99]
	v_mfma_f32_16x16x32_bf16 v[88:91], v[156:159], v[222:225], v[88:91]
	v_mfma_f32_16x16x32_bf16 v[88:91], v[152:155], v[218:221], v[88:91]
	v_mfma_f32_16x16x32_bf16 v[64:67], v[152:155], v[226:229], v[64:67]
	v_mfma_f32_16x16x32_bf16 v[64:67], v[156:159], v[230:233], v[64:67]
	v_mfma_f32_16x16x32_bf16 v[68:71], v[148:151], v[230:233], v[68:71]
	v_mfma_f32_16x16x32_bf16 v[68:71], v[144:147], v[226:229], v[68:71]
	v_mfma_f32_16x16x32_bf16 v[72:75], v[92:95], v[226:229], v[72:75]
	v_mfma_f32_16x16x32_bf16 v[72:75], v[100:103], v[230:233], v[72:75]
	s_setprio 3
	s_barrier
	v_mfma_f32_16x16x32_bf16 v[76:79], v[84:87], v[230:233], v[76:79]
	v_mfma_f32_16x16x32_bf16 v[76:79], v[80:83], v[226:229], v[76:79]
	s_setprio 0
	s_add_i32 s77, s61, s13
	v_lshl_add_u64 v[234:235], s[28:29], 0, v[160:161]
	s_mov_b32 m0, s77
	ds_read_b128 v[180:183], v207 offset:16384
	ds_read_b128 v[184:187], v207 offset:17408
	ds_read_b128 v[210:213], v207 offset:18432
	ds_read_b128 v[214:217], v207 offset:19456
	ds_read_b128 v[218:221], v207 offset:20480
	ds_read_b128 v[222:225], v207 offset:21504
	ds_read_b128 v[226:229], v207 offset:22528
	ds_read_b128 v[230:233], v207 offset:23552
	global_load_lds_dwordx4 v[234:235], off
	s_add_i32 m0, s77, 0x2000
	s_add_u32 s78, s28, 0x160000
	v_lshl_add_u64 v[236:237], s[28:29], 0, v[162:163]
	s_addc_u32 s79, s29, 0
	s_add_i32 s77, s62, s13
	global_load_lds_dwordx4 v[236:237], off
	v_lshl_add_u64 v[238:239], s[78:79], 0, v[160:161]
	s_mov_b32 m0, s77
	v_lshl_add_u64 v[240:241], s[48:49], 0, v[162:163]
	global_load_lds_dwordx4 v[238:239], off
	v_lshl_add_u64 v[238:239], s[78:79], 0, v[162:163]
	s_add_i32 m0, s77, 0x2000
	s_nop 0
	global_load_lds_dwordx4 v[238:239], off
	v_lshl_add_u64 v[238:239], s[48:49], 0, v[160:161]
	s_mov_b32 m0, s40
	s_nop 0
	global_load_lds_dwordx4 v[238:239], off
	s_mov_b32 m0, s41
	s_nop 0
	global_load_lds_dwordx4 v[240:241], off
	s_waitcnt vmcnt(8)
	s_waitcnt lgkmcnt(0)
	s_barrier
; #define PG8_STAGE(bufoff, gbase, voff) do { _Pragma("unroll") for (int _i = 0; _i < 2; ++_i) \
;         __builtin_amdgcn_global_load_lds((const unsigned*)((const char*)(gbase) + (voff)[_i]), (PG8_LAS unsigned*)(lds + (bufoff) + ldsw + _i * 8192), 16, 0, 0); } while (0)
; #define PG8_LDA(dst, b, h) do { _Pragma("unroll") for (int m = 0; m < 4; ++m) _Pragma("unroll") for (int k = 0; k < 2; ++k) dst[m][k] = *(const PG8_LAS bf16x8*)(lds + PG8_SA(b, h) + aoff + m * 2048 + k * 1024); } while (0)
; #define PG8_LDB(dst, b, h) do { _Pragma("unroll") for (int n = 0; n < 2; ++n) _Pragma("unroll") for (int k = 0; k < 2; ++k) dst[n][k] = *(const PG8_LAS bf16x8*)(lds + PG8_SB(b, h) + boff + n * 2048 + k * 1024); } while (0)
; #define PG8_MMA(ai, bj, At, Bt) do { __builtin_amdgcn_s_setprio(1); _Pragma("unroll") for (int m = 0; m < 4; ++m) _Pragma("unroll") for (int n = 0; n < 2; ++n) _Pragma("unroll") for (int k = 0; k < 2; ++k) \
;         acc[ai][bj][m][n] = __builtin_amdgcn_mfma_f32_16x16x32_bf16(Bt[n][k], At[m][k], acc[ai][bj][m][n], 0, 0, 0); __builtin_amdgcn_s_setprio(0); } while (0)
; #define PG8_WAIT_V(n) asm volatile("s_waitcnt vmcnt(" #n ")" ::: "memory")
; #define PG8_WAIT_L(n) asm volatile("s_waitcnt lgkmcnt(" #n ")" ::: "memory")
; #define PG8_BAR __builtin_amdgcn_s_barrier()
; #define PG8_SCHED __builtin_amdgcn_sched_barrier(0)
; template <class Epi, class Sched, bool ALIGN_EPI = false, bool SP2 = false>
; __device__ __forceinline__ void gemm_phase(PG8_LAS unsigned char* lds, const Gemm g, const Sched& S, const Epi& E) {
;     ...
;             PG8_WAIT_V(8); PG8_WAIT_L(0); PG8_BAR; PG8_MMA(1, 0, At, B0); PG8_MMA(1, 1, At, B1); PG8_BAR; PG8_SCHED;
;             PG8_LDB(B0, 1, 0); PG8_LDB(B1, 1, 1); PG8_SCHED; PG8_LDA(At, 1, 0); PG8_STAGE(PG8_SA(0, 1), a2 + hstep, voffA);
;             PG8_WAIT_V(8); PG8_WAIT_L(0); PG8_BAR; PG8_MMA(0, 0, At, B0); PG8_MMA(0, 1, At, B1); PG8_BAR; PG8_SCHED;
	s_setprio 1
	s_waitcnt lgkmcnt(0)
	v_mfma_f32_16x16x32_bf16 v[60:63], v[80:83], v[180:183], v[60:63]
	v_mfma_f32_16x16x32_bf16 v[60:63], v[84:87], v[184:187], v[60:63]
	v_mfma_f32_16x16x32_bf16 v[56:59], v[100:103], v[184:187], v[56:59]
	v_mfma_f32_16x16x32_bf16 v[56:59], v[92:95], v[180:183], v[56:59]
	v_mfma_f32_16x16x32_bf16 v[52:55], v[144:147], v[180:183], v[52:55]
	v_mfma_f32_16x16x32_bf16 v[52:55], v[148:151], v[184:187], v[52:55]
	v_mfma_f32_16x16x32_bf16 v[48:51], v[156:159], v[184:187], v[48:51]
	v_mfma_f32_16x16x32_bf16 v[48:51], v[152:155], v[180:183], v[48:51]
	v_mfma_f32_16x16x32_bf16 v[32:35], v[152:155], v[210:213], v[32:35]
	v_mfma_f32_16x16x32_bf16 v[32:35], v[156:159], v[214:217], v[32:35]
	v_mfma_f32_16x16x32_bf16 v[36:39], v[148:151], v[214:217], v[36:39]
	v_mfma_f32_16x16x32_bf16 v[36:39], v[144:147], v[210:213], v[36:39]
	v_mfma_f32_16x16x32_bf16 v[40:43], v[92:95], v[210:213], v[40:43]
	v_mfma_f32_16x16x32_bf16 v[40:43], v[100:103], v[214:217], v[40:43]
	v_mfma_f32_16x16x32_bf16 v[44:47], v[84:87], v[214:217], v[44:47]
	v_mfma_f32_16x16x32_bf16 v[44:47], v[80:83], v[210:213], v[44:47]
	s_setprio 0
	s_setprio 1
	v_mfma_f32_16x16x32_bf16 v[28:31], v[80:83], v[218:221], v[28:31]
	v_mfma_f32_16x16x32_bf16 v[28:31], v[84:87], v[222:225], v[28:31]
	v_mfma_f32_16x16x32_bf16 v[24:27], v[100:103], v[222:225], v[24:27]
	v_mfma_f32_16x16x32_bf16 v[24:27], v[92:95], v[218:221], v[24:27]
	v_mfma_f32_16x16x32_bf16 v[20:23], v[144:147], v[218:221], v[20:23]
	v_mfma_f32_16x16x32_bf16 v[20:23], v[148:151], v[222:225], v[20:23]
	v_mfma_f32_16x16x32_bf16 v[16:19], v[156:159], v[222:225], v[16:19]
	v_mfma_f32_16x16x32_bf16 v[16:19], v[152:155], v[218:221], v[16:19]
	v_mfma_f32_16x16x32_bf16 v[0:3], v[152:155], v[226:229], v[0:3]
	v_mfma_f32_16x16x32_bf16 v[0:3], v[156:159], v[230:233], v[0:3]
	v_mfma_f32_16x16x32_bf16 v[4:7], v[148:151], v[230:233], v[4:7]
	v_mfma_f32_16x16x32_bf16 v[4:7], v[144:147], v[226:229], v[4:7]
	v_mfma_f32_16x16x32_bf16 v[8:11], v[92:95], v[226:229], v[8:11]
	v_mfma_f32_16x16x32_bf16 v[8:11], v[100:103], v[230:233], v[8:11]
	s_setprio 3
	s_barrier
	v_mfma_f32_16x16x32_bf16 v[12:15], v[84:87], v[230:233], v[12:15]
	v_mfma_f32_16x16x32_bf16 v[12:15], v[80:83], v[226:229], v[12:15]
	s_setprio 0
	s_add_i32 s77, 0, 0x18000
	s_add_i32 s78, 0, 0x1c000
	v_add_u32_e32 v100, s77, v167
	v_add_u32_e32 v156, s78, v167
	ds_read_b128 v[80:83], v100
	ds_read_b128 v[84:87], v100 offset:1024
	ds_read_b128 v[92:95], v100 offset:2048
	ds_read_b128 v[100:103], v100 offset:3072
	ds_read_b128 v[144:147], v156
	ds_read_b128 v[148:151], v156 offset:1024
	ds_read_b128 v[152:155], v156 offset:2048
	ds_read_b128 v[156:159], v156 offset:3072
	s_add_u32 s48, s48, 0x160000
	s_addc_u32 s49, s49, 0
	s_mov_b32 m0, s44
	v_lshl_add_u64 v[242:243], s[48:49], 0, v[160:161]
	ds_read_b128 v[180:183], v207 offset:32768
	ds_read_b128 v[184:187], v207 offset:33792
	ds_read_b128 v[210:213], v207 offset:34816
	ds_read_b128 v[214:217], v207 offset:35840
	ds_read_b128 v[218:221], v207 offset:36864
	ds_read_b128 v[222:225], v207 offset:37888
	ds_read_b128 v[226:229], v207 offset:38912
	ds_read_b128 v[230:233], v207 offset:39936
	global_load_lds_dwordx4 v[242:243], off
	v_lshl_add_u64 v[242:243], s[48:49], 0, v[162:163]
	s_mov_b32 m0, s45
	s_nop 0
	global_load_lds_dwordx4 v[242:243], off
	s_waitcnt vmcnt(8)
	s_waitcnt lgkmcnt(0)
	s_barrier
	s_setprio 1
	s_waitcnt lgkmcnt(0)
	v_mfma_f32_16x16x32_bf16 v[140:143], v[80:83], v[180:183], v[140:143]
	v_mfma_f32_16x16x32_bf16 v[140:143], v[84:87], v[184:187], v[140:143]
	v_mfma_f32_16x16x32_bf16 v[136:139], v[100:103], v[184:187], v[136:139]
	v_mfma_f32_16x16x32_bf16 v[136:139], v[92:95], v[180:183], v[136:139]
	v_mfma_f32_16x16x32_bf16 v[132:135], v[144:147], v[180:183], v[132:135]
	v_mfma_f32_16x16x32_bf16 v[132:135], v[148:151], v[184:187], v[132:135]
	v_mfma_f32_16x16x32_bf16 v[128:131], v[156:159], v[184:187], v[128:131]
	v_mfma_f32_16x16x32_bf16 v[128:131], v[152:155], v[180:183], v[128:131]
	v_mfma_f32_16x16x32_bf16 v[112:115], v[152:155], v[210:213], v[112:115]
	v_mfma_f32_16x16x32_bf16 v[112:115], v[156:159], v[214:217], v[112:115]
	v_mfma_f32_16x16x32_bf16 v[116:119], v[148:151], v[214:217], v[116:119]
	v_mfma_f32_16x16x32_bf16 v[116:119], v[144:147], v[210:213], v[116:119]
	v_mfma_f32_16x16x32_bf16 v[120:123], v[92:95], v[210:213], v[120:123]
	v_mfma_f32_16x16x32_bf16 v[120:123], v[100:103], v[214:217], v[120:123]
	v_mfma_f32_16x16x32_bf16 v[124:127], v[84:87], v[214:217], v[124:127]
	v_mfma_f32_16x16x32_bf16 v[124:127], v[80:83], v[210:213], v[124:127]
	s_setprio 0
	s_setprio 1
	v_mfma_f32_16x16x32_bf16 v[108:111], v[80:83], v[218:221], v[108:111]
	v_mfma_f32_16x16x32_bf16 v[108:111], v[84:87], v[222:225], v[108:111]
	v_mfma_f32_16x16x32_bf16 v[104:107], v[100:103], v[222:225], v[104:107]
	v_mfma_f32_16x16x32_bf16 v[104:107], v[92:95], v[218:221], v[104:107]
	v_mfma_f32_16x16x32_bf16 v[96:99], v[144:147], v[218:221], v[96:99]
	v_mfma_f32_16x16x32_bf16 v[96:99], v[148:151], v[222:225], v[96:99]
	v_mfma_f32_16x16x32_bf16 v[88:91], v[156:159], v[222:225], v[88:91]
	v_mfma_f32_16x16x32_bf16 v[88:91], v[152:155], v[218:221], v[88:91]
	v_mfma_f32_16x16x32_bf16 v[64:67], v[152:155], v[226:229], v[64:67]
	v_mfma_f32_16x16x32_bf16 v[64:67], v[156:159], v[230:233], v[64:67]
	v_mfma_f32_16x16x32_bf16 v[68:71], v[148:151], v[230:233], v[68:71]
	v_mfma_f32_16x16x32_bf16 v[68:71], v[144:147], v[226:229], v[68:71]
	v_mfma_f32_16x16x32_bf16 v[72:75], v[92:95], v[226:229], v[72:75]
	v_mfma_f32_16x16x32_bf16 v[72:75], v[100:103], v[230:233], v[72:75]
	s_setprio 3
	s_barrier
; #define PG8_STAGE(bufoff, gbase, voff) do { _Pragma("unroll") for (int _i = 0; _i < 2; ++_i) \
;         __builtin_amdgcn_global_load_lds((const unsigned*)((const char*)(gbase) + (voff)[_i]), (PG8_LAS unsigned*)(lds + (bufoff) + ldsw + _i * 8192), 16, 0, 0); } while (0)
; #define PG8_LDA(dst, b, h) do { _Pragma("unroll") for (int m = 0; m < 4; ++m) _Pragma("unroll") for (int k = 0; k < 2; ++k) dst[m][k] = *(const PG8_LAS bf16x8*)(lds + PG8_SA(b, h) + aoff + m * 2048 + k * 1024); } while (0)
; #define PG8_MMA(ai, bj, At, Bt) do { __builtin_amdgcn_s_setprio(1); _Pragma("unroll") for (int m = 0; m < 4; ++m) _Pragma("unroll") for (int n = 0; n < 2; ++n) _Pragma("unroll") for (int k = 0; k < 2; ++k) \
;         acc[ai][bj][m][n] = __builtin_amdgcn_mfma_f32_16x16x32_bf16(Bt[n][k], At[m][k], acc[ai][bj][m][n], 0, 0, 0); __builtin_amdgcn_s_setprio(0); } while (0)
; #define PG8_WAIT_V(n) asm volatile("s_waitcnt vmcnt(" #n ")" ::: "memory")
; #define PG8_WAIT_L(n) asm volatile("s_waitcnt lgkmcnt(" #n ")" ::: "memory")
; #define PG8_BAR __builtin_amdgcn_s_barrier()
; #define PG8_SCHED __builtin_amdgcn_sched_barrier(0)
; template <class Epi, class Sched, bool ALIGN_EPI = false, bool SP2 = false>
; __device__ __forceinline__ void gemm_phase(PG8_LAS unsigned char* lds, const Gemm g, const Sched& S, const Epi& E) {
;     ...
;         for (int t = 0; t < nt; t += 2) {
;     ...
;             PG8_WAIT_V(8); PG8_WAIT_L(0); PG8_BAR; PG8_MMA(0, 0, At, B0); PG8_MMA(0, 1, At, B1); PG8_BAR; PG8_SCHED;
;             PG8_LDA(At, 1, 1); PG8_STAGE(PG8_SB(1, 0), b3, voffB); PG8_STAGE(PG8_SB(1, 1), b3 + hstep, voffB); PG8_STAGE(PG8_SA(1, 0), a3, voffA);
;             PG8_WAIT_V(8); PG8_WAIT_L(0); PG8_BAR; PG8_MMA(1, 0, At, B0); PG8_MMA(1, 1, At, B1); PG8_BAR; PG8_SCHED;
;     ...
;         if constexpr (ALIGN_EPI) { if (wr == 0) PG8_BAR; }
	v_mfma_f32_16x16x32_bf16 v[76:79], v[84:87], v[230:233], v[76:79]
	v_mfma_f32_16x16x32_bf16 v[76:79], v[80:83], v[226:229], v[76:79]
	s_setprio 0
	s_add_i32 s48, s77, s13
	v_lshl_add_u64 v[234:235], v[234:235], 0, s[50:51]
	s_mov_b32 m0, s48
	ds_read_b128 v[180:183], v207 offset:49152
	ds_read_b128 v[184:187], v207 offset:50176
	ds_read_b128 v[210:213], v207 offset:51200
	ds_read_b128 v[214:217], v207 offset:52224
	ds_read_b128 v[218:221], v207 offset:53248
	ds_read_b128 v[222:225], v207 offset:54272
	ds_read_b128 v[226:229], v207 offset:55296
	ds_read_b128 v[230:233], v207 offset:56320
	global_load_lds_dwordx4 v[234:235], off
	s_add_i32 m0, s48, 0x2000
	s_add_u32 s28, s28, 0x160080
	v_lshl_add_u64 v[234:235], v[236:237], 0, s[50:51]
	s_addc_u32 s29, s29, 0
	s_add_i32 s48, s78, s13
	global_load_lds_dwordx4 v[234:235], off
	v_lshl_add_u64 v[234:235], s[28:29], 0, v[160:161]
	s_mov_b32 m0, s48
	s_nop 0
	global_load_lds_dwordx4 v[234:235], off
	v_lshl_add_u64 v[234:235], s[28:29], 0, v[162:163]
	s_add_i32 m0, s48, 0x2000
	s_nop 0
	global_load_lds_dwordx4 v[234:235], off
	v_lshl_add_u64 v[234:235], v[238:239], 0, s[50:51]
	s_mov_b32 m0, s56
	s_nop 0
	global_load_lds_dwordx4 v[234:235], off
	v_lshl_add_u64 v[234:235], v[240:241], 0, s[50:51]
	s_mov_b32 m0, s57
	s_nop 0
	global_load_lds_dwordx4 v[234:235], off
	s_waitcnt vmcnt(8)
	s_waitcnt lgkmcnt(0)
	s_barrier
	s_setprio 1
	s_waitcnt lgkmcnt(0)
	v_mfma_f32_16x16x32_bf16 v[60:63], v[80:83], v[180:183], v[60:63]
	v_mfma_f32_16x16x32_bf16 v[60:63], v[84:87], v[184:187], v[60:63]
	v_mfma_f32_16x16x32_bf16 v[56:59], v[100:103], v[184:187], v[56:59]
	v_mfma_f32_16x16x32_bf16 v[56:59], v[92:95], v[180:183], v[56:59]
	v_mfma_f32_16x16x32_bf16 v[52:55], v[144:147], v[180:183], v[52:55]
	v_mfma_f32_16x16x32_bf16 v[52:55], v[148:151], v[184:187], v[52:55]
	v_mfma_f32_16x16x32_bf16 v[48:51], v[156:159], v[184:187], v[48:51]
	v_mfma_f32_16x16x32_bf16 v[48:51], v[152:155], v[180:183], v[48:51]
	v_mfma_f32_16x16x32_bf16 v[32:35], v[152:155], v[210:213], v[32:35]
	v_mfma_f32_16x16x32_bf16 v[32:35], v[156:159], v[214:217], v[32:35]
	v_mfma_f32_16x16x32_bf16 v[36:39], v[148:151], v[214:217], v[36:39]
	v_mfma_f32_16x16x32_bf16 v[36:39], v[144:147], v[210:213], v[36:39]
	v_mfma_f32_16x16x32_bf16 v[40:43], v[92:95], v[210:213], v[40:43]
	v_mfma_f32_16x16x32_bf16 v[40:43], v[100:103], v[214:217], v[40:43]
	v_mfma_f32_16x16x32_bf16 v[44:47], v[84:87], v[214:217], v[44:47]
	v_mfma_f32_16x16x32_bf16 v[44:47], v[80:83], v[210:213], v[44:47]
	s_setprio 0
	s_setprio 1
	v_mfma_f32_16x16x32_bf16 v[28:31], v[80:83], v[218:221], v[28:31]
	v_mfma_f32_16x16x32_bf16 v[28:31], v[84:87], v[222:225], v[28:31]
	v_mfma_f32_16x16x32_bf16 v[24:27], v[100:103], v[222:225], v[24:27]
	v_mfma_f32_16x16x32_bf16 v[24:27], v[92:95], v[218:221], v[24:27]
	v_mfma_f32_16x16x32_bf16 v[20:23], v[144:147], v[218:221], v[20:23]
	v_mfma_f32_16x16x32_bf16 v[20:23], v[148:151], v[222:225], v[20:23]
	v_mfma_f32_16x16x32_bf16 v[16:19], v[156:159], v[222:225], v[16:19]
	v_mfma_f32_16x16x32_bf16 v[16:19], v[152:155], v[218:221], v[16:19]
	v_mfma_f32_16x16x32_bf16 v[0:3], v[152:155], v[226:229], v[0:3]
	v_mfma_f32_16x16x32_bf16 v[0:3], v[156:159], v[230:233], v[0:3]
	v_mfma_f32_16x16x32_bf16 v[4:7], v[148:151], v[230:233], v[4:7]
	v_mfma_f32_16x16x32_bf16 v[4:7], v[144:147], v[226:229], v[4:7]
	v_mfma_f32_16x16x32_bf16 v[8:11], v[92:95], v[226:229], v[8:11]
	v_mfma_f32_16x16x32_bf16 v[8:11], v[100:103], v[230:233], v[8:11]
	s_setprio 3
	s_barrier
	v_mfma_f32_16x16x32_bf16 v[12:15], v[84:87], v[230:233], v[12:15]
	v_mfma_f32_16x16x32_bf16 v[12:15], v[80:83], v[226:229], v[12:15]
	s_setprio 0
	s_add_i32 s76, s76, 2
	s_add_u32 s72, s72, 0x100
	s_addc_u32 s73, s73, 0
	s_add_u32 s34, s34, 0x100
	s_addc_u32 s35, s35, 0
	s_cmpk_gt_u32 s76, 0x55
	s_cbranch_scc0 .LBB0_177
	s_and_b64 vcc, exec, s[52:53]
	s_cbranch_vccz .LBB0_180
	s_barrier

; #define PG8_STAGE(bufoff, gbase, voff) do { _Pragma("unroll") for (int _i = 0; _i < 2; ++_i) \
;         __builtin_amdgcn_global_load_lds((const unsigned*)((const char*)(gbase) + (voff)[_i]), (PG8_LAS unsigned*)(lds + (bufoff) + ldsw + _i * 8192), 16, 0, 0); } while (0)
; #define PG8_LDA(dst, b, h) do { _Pragma("unroll") for (int m = 0; m < 4; ++m) _Pragma("unroll") for (int k = 0; k < 2; ++k) dst[m][k] = *(const PG8_LAS bf16x8*)(lds + PG8_SA(b, h) + aoff + m * 2048 + k * 1024); } while (0)
; #define PG8_LDB(dst, b, h) do { _Pragma("unroll") for (int n = 0; n < 2; ++n) _Pragma("unroll") for (int k = 0; k < 2; ++k) dst[n][k] = *(const PG8_LAS bf16x8*)(lds + PG8_SB(b, h) + boff + n * 2048 + k * 1024); } while (0)
; #define PG8_MMA(ai, bj, At, Bt) do { __builtin_amdgcn_s_setprio(1); _Pragma("unroll") for (int m = 0; m < 4; ++m) _Pragma("unroll") for (int n = 0; n < 2; ++n) _Pragma("unroll") for (int k = 0; k < 2; ++k) \
;         acc[ai][bj][m][n] = __builtin_amdgcn_mfma_f32_16x16x32_bf16(Bt[n][k], At[m][k], acc[ai][bj][m][n], 0, 0, 0); __builtin_amdgcn_s_setprio(0); } while (0)
; #define PG8_WAIT_V(n) asm volatile("s_waitcnt vmcnt(" #n ")" ::: "memory")
; #define PG8_WAIT_L(n) asm volatile("s_waitcnt lgkmcnt(" #n ")" ::: "memory")
; template <class Epi, class Sched, bool ALIGN_EPI = false, bool SP2 = false>
; __device__ __forceinline__ void gemm_phase(PG8_LAS unsigned char* lds, const Gemm g, const Sched& S, const Epi& E) {
;     ...
;             const bool last = (t == nt - 2);
;             const char* a1 = cA + (size_t)(t + 1) * kstep;
;             const char* a2 = last ? nA : cA + (size_t)(t + 2) * kstep; const char* b2 = last ? nB : cB + (size_t)(t + 2) * kstep;
;             const char* a3 = a2 + kstep; const char* b3 = b2 + kstep;
;             if (last && has_next) S.a_ready(nxt);
;             if constexpr (SP2) {
;             PG8_LDB(B0, 0, 0); PG8_LDB(B1, 0, 1); PG8_SCHED; PG8_LDA(At, 0, 0); PG8_STAGE(PG8_SA(1, 1), a1 + hstep, voffA);
;             PG8_WAIT_V(8); PG8_WAIT_L(0); PG8_BAR; PG8_MMA(0, 0, At, B0); PG8_MMA(0, 1, At, B1); PG8_BAR; PG8_SCHED;
;             PG8_LDA(At, 0, 1); PG8_STAGE(PG8_SB(0, 0), b2, voffB); PG8_STAGE(PG8_SB(0, 1), b2 + hstep, voffB); PG8_STAGE(PG8_SA(0, 0), a2, voffA);
;             PG8_WAIT_V(8); PG8_WAIT_L(0); PG8_BAR; PG8_MMA(1, 0, At, B0); PG8_MMA(1, 1, At, B1); PG8_BAR; PG8_SCHED;
.LBB0_231:
	ds_read_b128 v[142:145], v153
	ds_read_b128 v[146:149], v153 offset:1024
	ds_read_b128 v[174:177], v153 offset:2048
	ds_read_b128 v[178:181], v153 offset:3072
	ds_read_b128 v[182:185], v154
	ds_read_b128 v[206:209], v154 offset:1024
	ds_read_b128 v[210:213], v154 offset:2048
	ds_read_b128 v[214:217], v154 offset:3072
	s_add_u32 s28, s84, 0xfff80080
	s_addc_u32 s29, s85, -1
	s_cmp_eq_u32 s97, 28
	s_cselect_b32 s49, s34, s29
	s_cselect_b32 s48, s35, s28
	s_cselect_b32 s29, s75, s96
	s_cselect_b32 s28, s77, s95
	v_lshl_add_u64 v[158:159], s[84:85], 0, v[134:135]
	s_add_i32 m0, s56, 0xc000
	ds_read_b128 v[218:221], v155
	ds_read_b128 v[222:225], v155 offset:1024
	ds_read_b128 v[226:229], v155 offset:2048
	ds_read_b128 v[230:233], v155 offset:3072
	ds_read_b128 v[234:237], v155 offset:4096
	ds_read_b128 v[238:241], v155 offset:5120
	ds_read_b128 v[242:245], v155 offset:6144
	ds_read_b128 v[246:249], v155 offset:7168
	global_load_lds_dwordx4 v[158:159], off
	v_lshl_add_u64 v[158:159], s[84:85], 0, v[136:137]
	s_add_i32 m0, s56, 0xe000
	s_nop 0
	global_load_lds_dwordx4 v[158:159], off
	s_waitcnt vmcnt(8)
	s_waitcnt lgkmcnt(0)
	s_barrier
	s_setprio 1
	s_waitcnt lgkmcnt(0)
	v_mfma_f32_16x16x32_bf16 v[124:127], v[142:145], v[218:221], v[124:127]
	v_mfma_f32_16x16x32_bf16 v[124:127], v[146:149], v[222:225], v[124:127]
	v_mfma_f32_16x16x32_bf16 v[120:123], v[178:181], v[222:225], v[120:123]
	v_mfma_f32_16x16x32_bf16 v[120:123], v[174:177], v[218:221], v[120:123]
	v_mfma_f32_16x16x32_bf16 v[116:119], v[182:185], v[218:221], v[116:119]
	v_mfma_f32_16x16x32_bf16 v[116:119], v[206:209], v[222:225], v[116:119]
	v_mfma_f32_16x16x32_bf16 v[112:115], v[214:217], v[222:225], v[112:115]
	v_mfma_f32_16x16x32_bf16 v[112:115], v[210:213], v[218:221], v[112:115]
	v_mfma_f32_16x16x32_bf16 v[96:99], v[210:213], v[226:229], v[96:99]
	v_mfma_f32_16x16x32_bf16 v[96:99], v[214:217], v[230:233], v[96:99]
	v_mfma_f32_16x16x32_bf16 v[100:103], v[206:209], v[230:233], v[100:103]
	v_mfma_f32_16x16x32_bf16 v[100:103], v[182:185], v[226:229], v[100:103]
	v_mfma_f32_16x16x32_bf16 v[104:107], v[174:177], v[226:229], v[104:107]
	v_mfma_f32_16x16x32_bf16 v[104:107], v[178:181], v[230:233], v[104:107]
	v_mfma_f32_16x16x32_bf16 v[108:111], v[146:149], v[230:233], v[108:111]
	v_mfma_f32_16x16x32_bf16 v[108:111], v[142:145], v[226:229], v[108:111]
	s_setprio 0
	s_setprio 1
	v_mfma_f32_16x16x32_bf16 v[92:95], v[142:145], v[234:237], v[92:95]
	v_mfma_f32_16x16x32_bf16 v[92:95], v[146:149], v[238:241], v[92:95]
	v_mfma_f32_16x16x32_bf16 v[88:91], v[178:181], v[238:241], v[88:91]
	v_mfma_f32_16x16x32_bf16 v[88:91], v[174:177], v[234:237], v[88:91]
	v_mfma_f32_16x16x32_bf16 v[84:87], v[182:185], v[234:237], v[84:87]
	v_mfma_f32_16x16x32_bf16 v[84:87], v[206:209], v[238:241], v[84:87]
	v_mfma_f32_16x16x32_bf16 v[80:83], v[214:217], v[238:241], v[80:83]
	v_mfma_f32_16x16x32_bf16 v[80:83], v[210:213], v[234:237], v[80:83]
	v_mfma_f32_16x16x32_bf16 v[64:67], v[210:213], v[242:245], v[64:67]
	v_mfma_f32_16x16x32_bf16 v[64:67], v[214:217], v[246:249], v[64:67]
	v_mfma_f32_16x16x32_bf16 v[68:71], v[206:209], v[246:249], v[68:71]
	v_mfma_f32_16x16x32_bf16 v[68:71], v[182:185], v[242:245], v[68:71]
	v_mfma_f32_16x16x32_bf16 v[72:75], v[174:177], v[242:245], v[72:75]
	v_mfma_f32_16x16x32_bf16 v[72:75], v[178:181], v[246:249], v[72:75]
	s_setprio 3
	s_barrier
	v_mfma_f32_16x16x32_bf16 v[76:79], v[146:149], v[246:249], v[76:79]
	v_mfma_f32_16x16x32_bf16 v[76:79], v[142:145], v[242:245], v[76:79]
	s_setprio 0
	s_add_i32 vcc_lo, s83, s13
	v_lshl_add_u64 v[158:159], s[28:29], 0, v[166:167]
	s_mov_b32 m0, vcc_lo
	ds_read_b128 v[218:221], v155 offset:16384
	ds_read_b128 v[222:225], v155 offset:17408
	ds_read_b128 v[226:229], v155 offset:18432
	ds_read_b128 v[230:233], v155 offset:19456
	ds_read_b128 v[234:237], v155 offset:20480
	ds_read_b128 v[238:241], v155 offset:21504
	ds_read_b128 v[242:245], v155 offset:22528
	ds_read_b128 v[246:249], v155 offset:23552
	global_load_lds_dwordx4 v[158:159], off
	s_add_i32 m0, vcc_lo, 0x2000
	s_add_u32 vcc_lo, s28, 0x80000
	v_lshl_add_u64 v[186:187], s[28:29], 0, v[170:171]
	s_addc_u32 vcc_hi, s29, 0
	s_add_i32 s44, s90, s13
	global_load_lds_dwordx4 v[186:187], off
	v_lshl_add_u64 v[250:251], vcc, 0, v[166:167]
	s_mov_b32 m0, s44
	v_lshl_add_u64 v[252:253], s[48:49], 0, v[168:169]
	global_load_lds_dwordx4 v[250:251], off
	v_lshl_add_u64 v[250:251], vcc, 0, v[170:171]
	s_add_i32 m0, s44, 0x2000
	s_nop 0
	global_load_lds_dwordx4 v[250:251], off
	v_lshl_add_u64 v[250:251], s[48:49], 0, v[164:165]
	s_mov_b32 m0, s56
	s_nop 0
	global_load_lds_dwordx4 v[250:251], off
	s_mov_b32 m0, s57
	s_nop 0
	global_load_lds_dwordx4 v[252:253], off
	s_waitcnt vmcnt(8)
	s_waitcnt lgkmcnt(0)
	s_barrier
; #define PG8_STAGE(bufoff, gbase, voff) do { _Pragma("unroll") for (int _i = 0; _i < 2; ++_i) \
;         __builtin_amdgcn_global_load_lds((const unsigned*)((const char*)(gbase) + (voff)[_i]), (PG8_LAS unsigned*)(lds + (bufoff) + ldsw + _i * 8192), 16, 0, 0); } while (0)
; #define PG8_LDA(dst, b, h) do { _Pragma("unroll") for (int m = 0; m < 4; ++m) _Pragma("unroll") for (int k = 0; k < 2; ++k) dst[m][k] = *(const PG8_LAS bf16x8*)(lds + PG8_SA(b, h) + aoff + m * 2048 + k * 1024); } while (0)
; #define PG8_LDB(dst, b, h) do { _Pragma("unroll") for (int n = 0; n < 2; ++n) _Pragma("unroll") for (int k = 0; k < 2; ++k) dst[n][k] = *(const PG8_LAS bf16x8*)(lds + PG8_SB(b, h) + boff + n * 2048 + k * 1024); } while (0)
; #define PG8_MMA(ai, bj, At, Bt) do { __builtin_amdgcn_s_setprio(1); _Pragma("unroll") for (int m = 0; m < 4; ++m) _Pragma("unroll") for (int n = 0; n < 2; ++n) _Pragma("unroll") for (int k = 0; k < 2; ++k) \
;         acc[ai][bj][m][n] = __builtin_amdgcn_mfma_f32_16x16x32_bf16(Bt[n][k], At[m][k], acc[ai][bj][m][n], 0, 0, 0); __builtin_amdgcn_s_setprio(0); } while (0)
; #define PG8_WAIT_V(n) asm volatile("s_waitcnt vmcnt(" #n ")" ::: "memory")
; #define PG8_WAIT_L(n) asm volatile("s_waitcnt lgkmcnt(" #n ")" ::: "memory")
; #define PG8_BAR __builtin_amdgcn_s_barrier()
; #define PG8_SCHED __builtin_amdgcn_sched_barrier(0)
; template <class Epi, class Sched, bool ALIGN_EPI = false, bool SP2 = false>
; __device__ __forceinline__ void gemm_phase(PG8_LAS unsigned char* lds, const Gemm g, const Sched& S, const Epi& E) {
;     ...
;             PG8_WAIT_V(8); PG8_WAIT_L(0); PG8_BAR; PG8_MMA(1, 0, At, B0); PG8_MMA(1, 1, At, B1); PG8_BAR; PG8_SCHED;
;             PG8_LDB(B0, 1, 0); PG8_LDB(B1, 1, 1); PG8_SCHED; PG8_LDA(At, 1, 0); PG8_STAGE(PG8_SA(0, 1), a2 + hstep, voffA);
;             PG8_WAIT_V(8); PG8_WAIT_L(0); PG8_BAR; PG8_MMA(0, 0, At, B0); PG8_MMA(0, 1, At, B1); PG8_BAR; PG8_SCHED;
	s_setprio 1
	s_waitcnt lgkmcnt(0)
	v_mfma_f32_16x16x32_bf16 v[60:63], v[142:145], v[218:221], v[60:63]
	v_mfma_f32_16x16x32_bf16 v[60:63], v[146:149], v[222:225], v[60:63]
	v_mfma_f32_16x16x32_bf16 v[56:59], v[178:181], v[222:225], v[56:59]
	v_mfma_f32_16x16x32_bf16 v[56:59], v[174:177], v[218:221], v[56:59]
	v_mfma_f32_16x16x32_bf16 v[52:55], v[182:185], v[218:221], v[52:55]
	v_mfma_f32_16x16x32_bf16 v[52:55], v[206:209], v[222:225], v[52:55]
	v_mfma_f32_16x16x32_bf16 v[48:51], v[214:217], v[222:225], v[48:51]
	v_mfma_f32_16x16x32_bf16 v[48:51], v[210:213], v[218:221], v[48:51]
	v_mfma_f32_16x16x32_bf16 v[32:35], v[210:213], v[226:229], v[32:35]
	v_mfma_f32_16x16x32_bf16 v[32:35], v[214:217], v[230:233], v[32:35]
	v_mfma_f32_16x16x32_bf16 v[36:39], v[206:209], v[230:233], v[36:39]
	v_mfma_f32_16x16x32_bf16 v[36:39], v[182:185], v[226:229], v[36:39]
	v_mfma_f32_16x16x32_bf16 v[40:43], v[174:177], v[226:229], v[40:43]
	v_mfma_f32_16x16x32_bf16 v[40:43], v[178:181], v[230:233], v[40:43]
	v_mfma_f32_16x16x32_bf16 v[44:47], v[146:149], v[230:233], v[44:47]
	v_mfma_f32_16x16x32_bf16 v[44:47], v[142:145], v[226:229], v[44:47]
	s_setprio 0
	s_setprio 1
	v_mfma_f32_16x16x32_bf16 v[28:31], v[142:145], v[234:237], v[28:31]
	v_mfma_f32_16x16x32_bf16 v[28:31], v[146:149], v[238:241], v[28:31]
	v_mfma_f32_16x16x32_bf16 v[24:27], v[178:181], v[238:241], v[24:27]
	v_mfma_f32_16x16x32_bf16 v[24:27], v[174:177], v[234:237], v[24:27]
	v_mfma_f32_16x16x32_bf16 v[20:23], v[182:185], v[234:237], v[20:23]
	v_mfma_f32_16x16x32_bf16 v[20:23], v[206:209], v[238:241], v[20:23]
	v_mfma_f32_16x16x32_bf16 v[16:19], v[214:217], v[238:241], v[16:19]
	v_mfma_f32_16x16x32_bf16 v[16:19], v[210:213], v[234:237], v[16:19]
	v_mfma_f32_16x16x32_bf16 v[0:3], v[210:213], v[242:245], v[0:3]
	v_mfma_f32_16x16x32_bf16 v[0:3], v[214:217], v[246:249], v[0:3]
	v_mfma_f32_16x16x32_bf16 v[4:7], v[206:209], v[246:249], v[4:7]
	v_mfma_f32_16x16x32_bf16 v[4:7], v[182:185], v[242:245], v[4:7]
	v_mfma_f32_16x16x32_bf16 v[8:11], v[174:177], v[242:245], v[8:11]
	v_mfma_f32_16x16x32_bf16 v[8:11], v[178:181], v[246:249], v[8:11]
	s_setprio 3
	s_barrier
	v_mfma_f32_16x16x32_bf16 v[12:15], v[146:149], v[246:249], v[12:15]
	v_mfma_f32_16x16x32_bf16 v[12:15], v[142:145], v[242:245], v[12:15]
	s_setprio 0
	s_add_i32 s44, 0, 0x18000
	v_add_u32_e32 v161, s44, v151
	s_add_i32 s45, 0, 0x1c000
	ds_read_b128 v[142:145], v161
	ds_read_b128 v[146:149], v161 offset:1024
	ds_read_b128 v[174:177], v161 offset:2048
	ds_read_b128 v[178:181], v161 offset:3072
	v_add_u32_e32 v161, s45, v151
	ds_read_b128 v[182:185], v161
	ds_read_b128 v[206:209], v161 offset:1024
	ds_read_b128 v[210:213], v161 offset:2048
	ds_read_b128 v[214:217], v161 offset:3072
	s_add_u32 s48, s48, 0x80000
	s_addc_u32 s49, s49, 0
	s_mov_b32 m0, s60
	v_lshl_add_u64 v[200:201], s[48:49], 0, v[164:165]
	ds_read_b128 v[218:221], v155 offset:32768
	ds_read_b128 v[222:225], v155 offset:33792
	ds_read_b128 v[226:229], v155 offset:34816
	ds_read_b128 v[230:233], v155 offset:35840
	ds_read_b128 v[234:237], v155 offset:36864
	ds_read_b128 v[238:241], v155 offset:37888
	ds_read_b128 v[242:245], v155 offset:38912
	ds_read_b128 v[246:249], v155 offset:39936
	global_load_lds_dwordx4 v[200:201], off
	v_lshl_add_u64 v[200:201], s[48:49], 0, v[168:169]
	s_mov_b32 m0, s61
	s_nop 0
	global_load_lds_dwordx4 v[200:201], off
	s_waitcnt vmcnt(8)
	s_waitcnt lgkmcnt(0)
	s_barrier
	s_setprio 1
	s_waitcnt lgkmcnt(0)
	v_mfma_f32_16x16x32_bf16 v[124:127], v[142:145], v[218:221], v[124:127]
	v_mfma_f32_16x16x32_bf16 v[124:127], v[146:149], v[222:225], v[124:127]
	v_mfma_f32_16x16x32_bf16 v[120:123], v[178:181], v[222:225], v[120:123]
	v_mfma_f32_16x16x32_bf16 v[120:123], v[174:177], v[218:221], v[120:123]
	v_mfma_f32_16x16x32_bf16 v[116:119], v[182:185], v[218:221], v[116:119]
	v_mfma_f32_16x16x32_bf16 v[116:119], v[206:209], v[222:225], v[116:119]
	v_mfma_f32_16x16x32_bf16 v[112:115], v[214:217], v[222:225], v[112:115]
	v_mfma_f32_16x16x32_bf16 v[112:115], v[210:213], v[218:221], v[112:115]
	v_mfma_f32_16x16x32_bf16 v[96:99], v[210:213], v[226:229], v[96:99]
	v_mfma_f32_16x16x32_bf16 v[96:99], v[214:217], v[230:233], v[96:99]
	v_mfma_f32_16x16x32_bf16 v[100:103], v[206:209], v[230:233], v[100:103]
	v_mfma_f32_16x16x32_bf16 v[100:103], v[182:185], v[226:229], v[100:103]
	v_mfma_f32_16x16x32_bf16 v[104:107], v[174:177], v[226:229], v[104:107]
	v_mfma_f32_16x16x32_bf16 v[104:107], v[178:181], v[230:233], v[104:107]
	v_mfma_f32_16x16x32_bf16 v[108:111], v[146:149], v[230:233], v[108:111]
	v_mfma_f32_16x16x32_bf16 v[108:111], v[142:145], v[226:229], v[108:111]
	s_setprio 0
	s_setprio 1
	v_mfma_f32_16x16x32_bf16 v[92:95], v[142:145], v[234:237], v[92:95]
	v_mfma_f32_16x16x32_bf16 v[92:95], v[146:149], v[238:241], v[92:95]
	v_mfma_f32_16x16x32_bf16 v[88:91], v[178:181], v[238:241], v[88:91]
	v_mfma_f32_16x16x32_bf16 v[88:91], v[174:177], v[234:237], v[88:91]
	v_mfma_f32_16x16x32_bf16 v[84:87], v[182:185], v[234:237], v[84:87]
	v_mfma_f32_16x16x32_bf16 v[84:87], v[206:209], v[238:241], v[84:87]
	v_mfma_f32_16x16x32_bf16 v[80:83], v[214:217], v[238:241], v[80:83]
	v_mfma_f32_16x16x32_bf16 v[80:83], v[210:213], v[234:237], v[80:83]
	v_mfma_f32_16x16x32_bf16 v[64:67], v[210:213], v[242:245], v[64:67]
	v_mfma_f32_16x16x32_bf16 v[64:67], v[214:217], v[246:249], v[64:67]
	v_mfma_f32_16x16x32_bf16 v[68:71], v[206:209], v[246:249], v[68:71]
	v_mfma_f32_16x16x32_bf16 v[68:71], v[182:185], v[242:245], v[68:71]
	v_mfma_f32_16x16x32_bf16 v[72:75], v[174:177], v[242:245], v[72:75]
	v_mfma_f32_16x16x32_bf16 v[72:75], v[178:181], v[246:249], v[72:75]
	s_setprio 3
	s_barrier
; #define PG8_STAGE(bufoff, gbase, voff) do { _Pragma("unroll") for (int _i = 0; _i < 2; ++_i) \
;         __builtin_amdgcn_global_load_lds((const unsigned*)((const char*)(gbase) + (voff)[_i]), (PG8_LAS unsigned*)(lds + (bufoff) + ldsw + _i * 8192), 16, 0, 0); } while (0)
; #define PG8_LDA(dst, b, h) do { _Pragma("unroll") for (int m = 0; m < 4; ++m) _Pragma("unroll") for (int k = 0; k < 2; ++k) dst[m][k] = *(const PG8_LAS bf16x8*)(lds + PG8_SA(b, h) + aoff + m * 2048 + k * 1024); } while (0)
; #define PG8_MMA(ai, bj, At, Bt) do { __builtin_amdgcn_s_setprio(1); _Pragma("unroll") for (int m = 0; m < 4; ++m) _Pragma("unroll") for (int n = 0; n < 2; ++n) _Pragma("unroll") for (int k = 0; k < 2; ++k) \
;         acc[ai][bj][m][n] = __builtin_amdgcn_mfma_f32_16x16x32_bf16(Bt[n][k], At[m][k], acc[ai][bj][m][n], 0, 0, 0); __builtin_amdgcn_s_setprio(0); } while (0)
; #define PG8_WAIT_V(n) asm volatile("s_waitcnt vmcnt(" #n ")" ::: "memory")
; #define PG8_WAIT_L(n) asm volatile("s_waitcnt lgkmcnt(" #n ")" ::: "memory")
; #define PG8_BAR __builtin_amdgcn_s_barrier()
; #define PG8_SCHED __builtin_amdgcn_sched_barrier(0)
;     __device__ __forceinline__ void operator()(const f32x4 (&acc)[2][2][4][2], const Unit& u, int wr, int wc, int fr, int fq) const {
;         const int row0 = u.pm * BM + wr * 64 + fr;
;         if (u.pn < 8) {
; template <class Epi, class Sched, bool ALIGN_EPI = false, bool SP2 = false>
; __device__ __forceinline__ void gemm_phase(PG8_LAS unsigned char* lds, const Gemm g, const Sched& S, const Epi& E) {
;     ...
;             PG8_WAIT_V(8); PG8_WAIT_L(0); PG8_BAR; PG8_MMA(0, 0, At, B0); PG8_MMA(0, 1, At, B1); PG8_BAR; PG8_SCHED;
;             PG8_LDA(At, 1, 1); PG8_STAGE(PG8_SB(1, 0), b3, voffB); PG8_STAGE(PG8_SB(1, 1), b3 + hstep, voffB); PG8_STAGE(PG8_SA(1, 0), a3, voffA);
;             PG8_WAIT_V(8); PG8_WAIT_L(0); PG8_BAR; PG8_MMA(1, 0, At, B0); PG8_MMA(1, 1, At, B1); PG8_BAR; PG8_SCHED;
;     ...
;         if constexpr (ALIGN_EPI) { if (wr == 0) PG8_BAR; }
	v_mfma_f32_16x16x32_bf16 v[76:79], v[146:149], v[246:249], v[76:79]
	v_mfma_f32_16x16x32_bf16 v[76:79], v[142:145], v[242:245], v[76:79]
	s_setprio 0
	s_add_i32 s44, s44, s13
	v_lshl_add_u64 v[158:159], v[158:159], 0, s[52:53]
	s_mov_b32 m0, s44
	ds_read_b128 v[218:221], v155 offset:49152
	ds_read_b128 v[222:225], v155 offset:50176
	ds_read_b128 v[226:229], v155 offset:51200
	ds_read_b128 v[230:233], v155 offset:52224
	ds_read_b128 v[234:237], v155 offset:53248
	ds_read_b128 v[238:241], v155 offset:54272
	ds_read_b128 v[242:245], v155 offset:55296
	ds_read_b128 v[246:249], v155 offset:56320
	global_load_lds_dwordx4 v[158:159], off
	s_add_i32 m0, s44, 0x2000
	s_add_u32 s28, s28, 0x80080
	v_lshl_add_u64 v[158:159], v[186:187], 0, s[52:53]
	s_addc_u32 s29, s29, 0
	s_add_i32 s44, s45, s13
	global_load_lds_dwordx4 v[158:159], off
	v_lshl_add_u64 v[158:159], s[28:29], 0, v[166:167]
	s_mov_b32 m0, s44
	s_nop 0
	global_load_lds_dwordx4 v[158:159], off
	v_lshl_add_u64 v[158:159], s[28:29], 0, v[170:171]
	s_add_i32 m0, s44, 0x2000
	s_nop 0
	global_load_lds_dwordx4 v[158:159], off
	v_lshl_add_u64 v[158:159], v[250:251], 0, s[52:53]
	s_mov_b32 m0, s62
	s_nop 0
	global_load_lds_dwordx4 v[158:159], off
	v_lshl_add_u64 v[158:159], v[252:253], 0, s[52:53]
	s_mov_b32 m0, s63
	s_nop 0
	global_load_lds_dwordx4 v[158:159], off
	s_waitcnt vmcnt(8)
	s_waitcnt lgkmcnt(0)
	s_barrier
	s_setprio 1
	s_waitcnt lgkmcnt(0)
	v_mfma_f32_16x16x32_bf16 v[60:63], v[142:145], v[218:221], v[60:63]
	v_mfma_f32_16x16x32_bf16 v[60:63], v[146:149], v[222:225], v[60:63]
	v_mfma_f32_16x16x32_bf16 v[56:59], v[178:181], v[222:225], v[56:59]
	v_mfma_f32_16x16x32_bf16 v[56:59], v[174:177], v[218:221], v[56:59]
	v_mfma_f32_16x16x32_bf16 v[52:55], v[182:185], v[218:221], v[52:55]
	v_mfma_f32_16x16x32_bf16 v[52:55], v[206:209], v[222:225], v[52:55]
	v_mfma_f32_16x16x32_bf16 v[48:51], v[214:217], v[222:225], v[48:51]
	v_mfma_f32_16x16x32_bf16 v[48:51], v[210:213], v[218:221], v[48:51]
	v_mfma_f32_16x16x32_bf16 v[32:35], v[210:213], v[226:229], v[32:35]
	v_mfma_f32_16x16x32_bf16 v[32:35], v[214:217], v[230:233], v[32:35]
	v_mfma_f32_16x16x32_bf16 v[36:39], v[206:209], v[230:233], v[36:39]
	v_mfma_f32_16x16x32_bf16 v[36:39], v[182:185], v[226:229], v[36:39]
	v_mfma_f32_16x16x32_bf16 v[40:43], v[174:177], v[226:229], v[40:43]
	v_mfma_f32_16x16x32_bf16 v[40:43], v[178:181], v[230:233], v[40:43]
	v_mfma_f32_16x16x32_bf16 v[44:47], v[146:149], v[230:233], v[44:47]
	v_mfma_f32_16x16x32_bf16 v[44:47], v[142:145], v[226:229], v[44:47]
	s_setprio 0
	s_setprio 1
	v_mfma_f32_16x16x32_bf16 v[28:31], v[142:145], v[234:237], v[28:31]
	v_mfma_f32_16x16x32_bf16 v[28:31], v[146:149], v[238:241], v[28:31]
	v_mfma_f32_16x16x32_bf16 v[24:27], v[178:181], v[238:241], v[24:27]
	v_mfma_f32_16x16x32_bf16 v[24:27], v[174:177], v[234:237], v[24:27]
	v_mfma_f32_16x16x32_bf16 v[20:23], v[182:185], v[234:237], v[20:23]
	v_mfma_f32_16x16x32_bf16 v[20:23], v[206:209], v[238:241], v[20:23]
	v_mfma_f32_16x16x32_bf16 v[16:19], v[214:217], v[238:241], v[16:19]
	v_mfma_f32_16x16x32_bf16 v[16:19], v[210:213], v[234:237], v[16:19]
	v_mfma_f32_16x16x32_bf16 v[0:3], v[210:213], v[242:245], v[0:3]
	v_mfma_f32_16x16x32_bf16 v[0:3], v[214:217], v[246:249], v[0:3]
	v_mfma_f32_16x16x32_bf16 v[4:7], v[206:209], v[246:249], v[4:7]
	v_mfma_f32_16x16x32_bf16 v[4:7], v[182:185], v[242:245], v[4:7]
	v_mfma_f32_16x16x32_bf16 v[8:11], v[174:177], v[242:245], v[8:11]
	v_mfma_f32_16x16x32_bf16 v[8:11], v[178:181], v[246:249], v[8:11]
	s_setprio 3
	s_barrier
	v_mfma_f32_16x16x32_bf16 v[12:15], v[146:149], v[246:249], v[12:15]
	v_mfma_f32_16x16x32_bf16 v[12:15], v[142:145], v[242:245], v[12:15]
	s_setprio 0
	s_add_i32 s97, s97, 2
	s_add_u32 s84, s84, 0x100
	s_addc_u32 s85, s85, 0
	s_add_u32 s95, s95, 0x100
	s_addc_u32 s96, s96, 0
	s_cmp_gt_u32 s97, 29
	s_cbranch_scc0 .LBB0_231
	s_and_b64 vcc, exec, s[72:73]
	s_cbranch_vccz .LBB0_236
	s_barrier
	v_lshl_add_u32 v142, s82, 8, v150
	s_cmp_gt_i32 s94, 7
	s_mov_b64 s[28:29], -1
	s_cbranch_scc1 .LBB0_237

; #define PG8_STAGE(bufoff, gbase, voff) do { _Pragma("unroll") for (int _i = 0; _i < 2; ++_i) \
;         __builtin_amdgcn_global_load_lds((const unsigned*)((const char*)(gbase) + (voff)[_i]), (PG8_LAS unsigned*)(lds + (bufoff) + ldsw + _i * 8192), 16, 0, 0); } while (0)
; #define PG8_LDA(dst, b, h) do { _Pragma("unroll") for (int m = 0; m < 4; ++m) _Pragma("unroll") for (int k = 0; k < 2; ++k) dst[m][k] = *(const PG8_LAS bf16x8*)(lds + PG8_SA(b, h) + aoff + m * 2048 + k * 1024); } while (0)
; #define PG8_LDB(dst, b, h) do { _Pragma("unroll") for (int n = 0; n < 2; ++n) _Pragma("unroll") for (int k = 0; k < 2; ++k) dst[n][k] = *(const PG8_LAS bf16x8*)(lds + PG8_SB(b, h) + boff + n * 2048 + k * 1024); } while (0)
; #define PG8_MMA(ai, bj, At, Bt) do { __builtin_amdgcn_s_setprio(1); _Pragma("unroll") for (int m = 0; m < 4; ++m) _Pragma("unroll") for (int n = 0; n < 2; ++n) _Pragma("unroll") for (int k = 0; k < 2; ++k) \
;         acc[ai][bj][m][n] = __builtin_amdgcn_mfma_f32_16x16x32_bf16(Bt[n][k], At[m][k], acc[ai][bj][m][n], 0, 0, 0); __builtin_amdgcn_s_setprio(0); } while (0)
; #define PG8_WAIT_V(n) asm volatile("s_waitcnt vmcnt(" #n ")" ::: "memory")
; #define PG8_WAIT_L(n) asm volatile("s_waitcnt lgkmcnt(" #n ")" ::: "memory")
; template <class Epi, class Sched, bool ALIGN_EPI = false, bool SP2 = false>
; __device__ __forceinline__ void gemm_phase(PG8_LAS unsigned char* lds, const Gemm g, const Sched& S, const Epi& E) {
;     ...
;             const bool last = (t == nt - 2);
;             const char* a1 = cA + (size_t)(t + 1) * kstep;
;             const char* a2 = last ? nA : cA + (size_t)(t + 2) * kstep; const char* b2 = last ? nB : cB + (size_t)(t + 2) * kstep;
;             const char* a3 = a2 + kstep; const char* b3 = b2 + kstep;
;             if (last && has_next) S.a_ready(nxt);
;             if constexpr (SP2) {
;             PG8_LDB(B0, 0, 0); PG8_LDB(B1, 0, 1); PG8_SCHED; PG8_LDA(At, 0, 0); PG8_STAGE(PG8_SA(1, 1), a1 + hstep, voffA);
;             PG8_WAIT_V(8); PG8_WAIT_L(0); PG8_BAR; PG8_MMA(0, 0, At, B0); PG8_MMA(0, 1, At, B1); PG8_BAR; PG8_SCHED;
;             PG8_LDA(At, 0, 1); PG8_STAGE(PG8_SB(0, 0), b2, voffB); PG8_STAGE(PG8_SB(0, 1), b2 + hstep, voffB); PG8_STAGE(PG8_SA(0, 0), a2, voffA);
;             PG8_WAIT_V(8); PG8_WAIT_L(0); PG8_BAR; PG8_MMA(1, 0, At, B0); PG8_MMA(1, 1, At, B1); PG8_BAR; PG8_SCHED;
.LBB0_362:
	ds_read_b128 v[80:83], v171
	ds_read_b128 v[84:87], v171 offset:1024
	ds_read_b128 v[92:95], v171 offset:2048
	ds_read_b128 v[100:103], v171 offset:3072
	ds_read_b128 v[144:147], v186
	ds_read_b128 v[148:151], v186 offset:1024
	ds_read_b128 v[152:155], v186 offset:2048
	ds_read_b128 v[156:159], v186 offset:3072
	s_add_u32 s28, s74, 0xfff80080
	s_addc_u32 s29, s75, -1
	s_cmp_eq_u32 s77, 28
	s_cselect_b32 s49, s23, s29
	s_cselect_b32 s48, s34, s28
	s_cselect_b32 s29, s21, s76
	s_cselect_b32 s28, s35, s73
	v_lshl_add_u64 v[200:201], s[74:75], 0, v[172:173]
	s_add_i32 m0, s38, 0xc000
	ds_read_b128 v[178:181], v187
	ds_read_b128 v[182:185], v187 offset:1024
	ds_read_b128 v[206:209], v187 offset:2048
	ds_read_b128 v[210:213], v187 offset:3072
	ds_read_b128 v[214:217], v187 offset:4096
	ds_read_b128 v[218:221], v187 offset:5120
	ds_read_b128 v[222:225], v187 offset:6144
	ds_read_b128 v[226:229], v187 offset:7168
	global_load_lds_dwordx4 v[200:201], off
	v_lshl_add_u64 v[200:201], s[74:75], 0, v[174:175]
	s_add_i32 m0, s38, 0xe000
	s_nop 0
	global_load_lds_dwordx4 v[200:201], off
	s_waitcnt vmcnt(8)
	s_waitcnt lgkmcnt(0)
	s_barrier
	s_setprio 1
	s_waitcnt lgkmcnt(0)
	v_mfma_f32_16x16x32_bf16 v[140:143], v[80:83], v[178:181], v[140:143]
	v_mfma_f32_16x16x32_bf16 v[140:143], v[84:87], v[182:185], v[140:143]
	v_mfma_f32_16x16x32_bf16 v[136:139], v[100:103], v[182:185], v[136:139]
	v_mfma_f32_16x16x32_bf16 v[136:139], v[92:95], v[178:181], v[136:139]
	v_mfma_f32_16x16x32_bf16 v[132:135], v[144:147], v[178:181], v[132:135]
	v_mfma_f32_16x16x32_bf16 v[132:135], v[148:151], v[182:185], v[132:135]
	v_mfma_f32_16x16x32_bf16 v[128:131], v[156:159], v[182:185], v[128:131]
	v_mfma_f32_16x16x32_bf16 v[128:131], v[152:155], v[178:181], v[128:131]
	v_mfma_f32_16x16x32_bf16 v[112:115], v[152:155], v[206:209], v[112:115]
	v_mfma_f32_16x16x32_bf16 v[112:115], v[156:159], v[210:213], v[112:115]
	v_mfma_f32_16x16x32_bf16 v[116:119], v[148:151], v[210:213], v[116:119]
	v_mfma_f32_16x16x32_bf16 v[116:119], v[144:147], v[206:209], v[116:119]
	v_mfma_f32_16x16x32_bf16 v[120:123], v[92:95], v[206:209], v[120:123]
	v_mfma_f32_16x16x32_bf16 v[120:123], v[100:103], v[210:213], v[120:123]
	v_mfma_f32_16x16x32_bf16 v[124:127], v[84:87], v[210:213], v[124:127]
	v_mfma_f32_16x16x32_bf16 v[124:127], v[80:83], v[206:209], v[124:127]
	s_setprio 0
	s_setprio 1
	v_mfma_f32_16x16x32_bf16 v[108:111], v[80:83], v[214:217], v[108:111]
	v_mfma_f32_16x16x32_bf16 v[108:111], v[84:87], v[218:221], v[108:111]
	v_mfma_f32_16x16x32_bf16 v[104:107], v[100:103], v[218:221], v[104:107]
	v_mfma_f32_16x16x32_bf16 v[104:107], v[92:95], v[214:217], v[104:107]
	v_mfma_f32_16x16x32_bf16 v[96:99], v[144:147], v[214:217], v[96:99]
	v_mfma_f32_16x16x32_bf16 v[96:99], v[148:151], v[218:221], v[96:99]
	v_mfma_f32_16x16x32_bf16 v[88:91], v[156:159], v[218:221], v[88:91]
	v_mfma_f32_16x16x32_bf16 v[88:91], v[152:155], v[214:217], v[88:91]
	v_mfma_f32_16x16x32_bf16 v[64:67], v[152:155], v[222:225], v[64:67]
	v_mfma_f32_16x16x32_bf16 v[64:67], v[156:159], v[226:229], v[64:67]
	v_mfma_f32_16x16x32_bf16 v[68:71], v[148:151], v[226:229], v[68:71]
	v_mfma_f32_16x16x32_bf16 v[68:71], v[144:147], v[222:225], v[68:71]
	v_mfma_f32_16x16x32_bf16 v[72:75], v[92:95], v[222:225], v[72:75]
	v_mfma_f32_16x16x32_bf16 v[72:75], v[100:103], v[226:229], v[72:75]
	s_setprio 3
	s_barrier
	v_mfma_f32_16x16x32_bf16 v[76:79], v[84:87], v[226:229], v[76:79]
	v_mfma_f32_16x16x32_bf16 v[76:79], v[80:83], v[222:225], v[76:79]
	s_setprio 0
	s_add_i32 s44, s62, s13
	v_lshl_add_u64 v[200:201], s[28:29], 0, v[164:165]
	s_mov_b32 m0, s44
	ds_read_b128 v[178:181], v187 offset:16384
	ds_read_b128 v[182:185], v187 offset:17408
	ds_read_b128 v[206:209], v187 offset:18432
	ds_read_b128 v[210:213], v187 offset:19456
	ds_read_b128 v[214:217], v187 offset:20480
	ds_read_b128 v[218:221], v187 offset:21504
	ds_read_b128 v[222:225], v187 offset:22528
	ds_read_b128 v[226:229], v187 offset:23552
	global_load_lds_dwordx4 v[200:201], off
	s_add_i32 m0, s44, 0x2000
	s_add_u32 s78, s28, 0x80000
	v_lshl_add_u64 v[230:231], s[28:29], 0, v[168:169]
	s_addc_u32 s79, s29, 0
	s_add_i32 s44, s63, s13
	global_load_lds_dwordx4 v[230:231], off
	v_lshl_add_u64 v[232:233], s[78:79], 0, v[164:165]
	s_mov_b32 m0, s44
	v_lshl_add_u64 v[234:235], s[48:49], 0, v[168:169]
	global_load_lds_dwordx4 v[232:233], off
	v_lshl_add_u64 v[232:233], s[78:79], 0, v[168:169]
	s_add_i32 m0, s44, 0x2000
	s_nop 0
	global_load_lds_dwordx4 v[232:233], off
	v_lshl_add_u64 v[232:233], s[48:49], 0, v[164:165]
	s_mov_b32 m0, s38
	s_nop 0
	global_load_lds_dwordx4 v[232:233], off
	s_mov_b32 m0, s39
	s_nop 0
	global_load_lds_dwordx4 v[234:235], off
	s_waitcnt vmcnt(8)
	s_waitcnt lgkmcnt(0)
	s_barrier
; #define PG8_STAGE(bufoff, gbase, voff) do { _Pragma("unroll") for (int _i = 0; _i < 2; ++_i) \
;         __builtin_amdgcn_global_load_lds((const unsigned*)((const char*)(gbase) + (voff)[_i]), (PG8_LAS unsigned*)(lds + (bufoff) + ldsw + _i * 8192), 16, 0, 0); } while (0)
; #define PG8_LDA(dst, b, h) do { _Pragma("unroll") for (int m = 0; m < 4; ++m) _Pragma("unroll") for (int k = 0; k < 2; ++k) dst[m][k] = *(const PG8_LAS bf16x8*)(lds + PG8_SA(b, h) + aoff + m * 2048 + k * 1024); } while (0)
; #define PG8_LDB(dst, b, h) do { _Pragma("unroll") for (int n = 0; n < 2; ++n) _Pragma("unroll") for (int k = 0; k < 2; ++k) dst[n][k] = *(const PG8_LAS bf16x8*)(lds + PG8_SB(b, h) + boff + n * 2048 + k * 1024); } while (0)
; #define PG8_MMA(ai, bj, At, Bt) do { __builtin_amdgcn_s_setprio(1); _Pragma("unroll") for (int m = 0; m < 4; ++m) _Pragma("unroll") for (int n = 0; n < 2; ++n) _Pragma("unroll") for (int k = 0; k < 2; ++k) \
;         acc[ai][bj][m][n] = __builtin_amdgcn_mfma_f32_16x16x32_bf16(Bt[n][k], At[m][k], acc[ai][bj][m][n], 0, 0, 0); __builtin_amdgcn_s_setprio(0); } while (0)
; #define PG8_WAIT_V(n) asm volatile("s_waitcnt vmcnt(" #n ")" ::: "memory")
; #define PG8_WAIT_L(n) asm volatile("s_waitcnt lgkmcnt(" #n ")" ::: "memory")
; #define PG8_BAR __builtin_amdgcn_s_barrier()
; #define PG8_SCHED __builtin_amdgcn_sched_barrier(0)
; template <class Epi, class Sched, bool ALIGN_EPI = false, bool SP2 = false>
; __device__ __forceinline__ void gemm_phase(PG8_LAS unsigned char* lds, const Gemm g, const Sched& S, const Epi& E) {
;     ...
;             PG8_WAIT_V(8); PG8_WAIT_L(0); PG8_BAR; PG8_MMA(1, 0, At, B0); PG8_MMA(1, 1, At, B1); PG8_BAR; PG8_SCHED;
;             PG8_LDB(B0, 1, 0); PG8_LDB(B1, 1, 1); PG8_SCHED; PG8_LDA(At, 1, 0); PG8_STAGE(PG8_SA(0, 1), a2 + hstep, voffA);
;             PG8_WAIT_V(8); PG8_WAIT_L(0); PG8_BAR; PG8_MMA(0, 0, At, B0); PG8_MMA(0, 1, At, B1); PG8_BAR; PG8_SCHED;
	s_setprio 1
	s_waitcnt lgkmcnt(0)
	v_mfma_f32_16x16x32_bf16 v[60:63], v[80:83], v[178:181], v[60:63]
	v_mfma_f32_16x16x32_bf16 v[60:63], v[84:87], v[182:185], v[60:63]
	v_mfma_f32_16x16x32_bf16 v[56:59], v[100:103], v[182:185], v[56:59]
	v_mfma_f32_16x16x32_bf16 v[56:59], v[92:95], v[178:181], v[56:59]
	v_mfma_f32_16x16x32_bf16 v[52:55], v[144:147], v[178:181], v[52:55]
	v_mfma_f32_16x16x32_bf16 v[52:55], v[148:151], v[182:185], v[52:55]
	v_mfma_f32_16x16x32_bf16 v[48:51], v[156:159], v[182:185], v[48:51]
	v_mfma_f32_16x16x32_bf16 v[48:51], v[152:155], v[178:181], v[48:51]
	v_mfma_f32_16x16x32_bf16 v[32:35], v[152:155], v[206:209], v[32:35]
	v_mfma_f32_16x16x32_bf16 v[32:35], v[156:159], v[210:213], v[32:35]
	v_mfma_f32_16x16x32_bf16 v[36:39], v[148:151], v[210:213], v[36:39]
	v_mfma_f32_16x16x32_bf16 v[36:39], v[144:147], v[206:209], v[36:39]
	v_mfma_f32_16x16x32_bf16 v[40:43], v[92:95], v[206:209], v[40:43]
	v_mfma_f32_16x16x32_bf16 v[40:43], v[100:103], v[210:213], v[40:43]
	v_mfma_f32_16x16x32_bf16 v[44:47], v[84:87], v[210:213], v[44:47]
	v_mfma_f32_16x16x32_bf16 v[44:47], v[80:83], v[206:209], v[44:47]
	s_setprio 0
	s_setprio 1
	v_mfma_f32_16x16x32_bf16 v[28:31], v[80:83], v[214:217], v[28:31]
	v_mfma_f32_16x16x32_bf16 v[28:31], v[84:87], v[218:221], v[28:31]
	v_mfma_f32_16x16x32_bf16 v[24:27], v[100:103], v[218:221], v[24:27]
	v_mfma_f32_16x16x32_bf16 v[24:27], v[92:95], v[214:217], v[24:27]
	v_mfma_f32_16x16x32_bf16 v[20:23], v[144:147], v[214:217], v[20:23]
	v_mfma_f32_16x16x32_bf16 v[20:23], v[148:151], v[218:221], v[20:23]
	v_mfma_f32_16x16x32_bf16 v[16:19], v[156:159], v[218:221], v[16:19]
	v_mfma_f32_16x16x32_bf16 v[16:19], v[152:155], v[214:217], v[16:19]
	v_mfma_f32_16x16x32_bf16 v[0:3], v[152:155], v[222:225], v[0:3]
	v_mfma_f32_16x16x32_bf16 v[0:3], v[156:159], v[226:229], v[0:3]
	v_mfma_f32_16x16x32_bf16 v[4:7], v[148:151], v[226:229], v[4:7]
	v_mfma_f32_16x16x32_bf16 v[4:7], v[144:147], v[222:225], v[4:7]
	v_mfma_f32_16x16x32_bf16 v[8:11], v[92:95], v[222:225], v[8:11]
	v_mfma_f32_16x16x32_bf16 v[8:11], v[100:103], v[226:229], v[8:11]
	s_setprio 3
	s_barrier
	v_mfma_f32_16x16x32_bf16 v[12:15], v[84:87], v[226:229], v[12:15]
	v_mfma_f32_16x16x32_bf16 v[12:15], v[80:83], v[222:225], v[12:15]
	s_setprio 0
	s_add_i32 s44, 0, 0x18000
	s_add_i32 s45, 0, 0x1c000
	v_add_u32_e32 v100, s44, v163
	v_add_u32_e32 v156, s45, v163
	ds_read_b128 v[80:83], v100
	ds_read_b128 v[84:87], v100 offset:1024
	ds_read_b128 v[92:95], v100 offset:2048
	ds_read_b128 v[100:103], v100 offset:3072
	ds_read_b128 v[144:147], v156
	ds_read_b128 v[148:151], v156 offset:1024
	ds_read_b128 v[152:155], v156 offset:2048
	ds_read_b128 v[156:159], v156 offset:3072
	s_add_u32 s48, s48, 0x80000
	s_addc_u32 s49, s49, 0
	s_mov_b32 m0, s40
	v_lshl_add_u64 v[236:237], s[48:49], 0, v[164:165]
	ds_read_b128 v[178:181], v187 offset:32768
	ds_read_b128 v[182:185], v187 offset:33792
	ds_read_b128 v[206:209], v187 offset:34816
	ds_read_b128 v[210:213], v187 offset:35840
	ds_read_b128 v[214:217], v187 offset:36864
	ds_read_b128 v[218:221], v187 offset:37888
	ds_read_b128 v[222:225], v187 offset:38912
	ds_read_b128 v[226:229], v187 offset:39936
	global_load_lds_dwordx4 v[236:237], off
	v_lshl_add_u64 v[236:237], s[48:49], 0, v[168:169]
	s_mov_b32 m0, s41
	s_nop 0
	global_load_lds_dwordx4 v[236:237], off
	s_waitcnt vmcnt(8)
	s_waitcnt lgkmcnt(0)
	s_barrier
	s_setprio 1
	s_waitcnt lgkmcnt(0)
	v_mfma_f32_16x16x32_bf16 v[140:143], v[80:83], v[178:181], v[140:143]
	v_mfma_f32_16x16x32_bf16 v[140:143], v[84:87], v[182:185], v[140:143]
	v_mfma_f32_16x16x32_bf16 v[136:139], v[100:103], v[182:185], v[136:139]
	v_mfma_f32_16x16x32_bf16 v[136:139], v[92:95], v[178:181], v[136:139]
	v_mfma_f32_16x16x32_bf16 v[132:135], v[144:147], v[178:181], v[132:135]
	v_mfma_f32_16x16x32_bf16 v[132:135], v[148:151], v[182:185], v[132:135]
	v_mfma_f32_16x16x32_bf16 v[128:131], v[156:159], v[182:185], v[128:131]
	v_mfma_f32_16x16x32_bf16 v[128:131], v[152:155], v[178:181], v[128:131]
	v_mfma_f32_16x16x32_bf16 v[112:115], v[152:155], v[206:209], v[112:115]
	v_mfma_f32_16x16x32_bf16 v[112:115], v[156:159], v[210:213], v[112:115]
	v_mfma_f32_16x16x32_bf16 v[116:119], v[148:151], v[210:213], v[116:119]
	v_mfma_f32_16x16x32_bf16 v[116:119], v[144:147], v[206:209], v[116:119]
	v_mfma_f32_16x16x32_bf16 v[120:123], v[92:95], v[206:209], v[120:123]
	v_mfma_f32_16x16x32_bf16 v[120:123], v[100:103], v[210:213], v[120:123]
	v_mfma_f32_16x16x32_bf16 v[124:127], v[84:87], v[210:213], v[124:127]
	v_mfma_f32_16x16x32_bf16 v[124:127], v[80:83], v[206:209], v[124:127]
	s_setprio 0
	s_setprio 1
	v_mfma_f32_16x16x32_bf16 v[108:111], v[80:83], v[214:217], v[108:111]
	v_mfma_f32_16x16x32_bf16 v[108:111], v[84:87], v[218:221], v[108:111]
	v_mfma_f32_16x16x32_bf16 v[104:107], v[100:103], v[218:221], v[104:107]
	v_mfma_f32_16x16x32_bf16 v[104:107], v[92:95], v[214:217], v[104:107]
	v_mfma_f32_16x16x32_bf16 v[96:99], v[144:147], v[214:217], v[96:99]
	v_mfma_f32_16x16x32_bf16 v[96:99], v[148:151], v[218:221], v[96:99]
	v_mfma_f32_16x16x32_bf16 v[88:91], v[156:159], v[218:221], v[88:91]
	v_mfma_f32_16x16x32_bf16 v[88:91], v[152:155], v[214:217], v[88:91]
	v_mfma_f32_16x16x32_bf16 v[64:67], v[152:155], v[222:225], v[64:67]
	v_mfma_f32_16x16x32_bf16 v[64:67], v[156:159], v[226:229], v[64:67]
	v_mfma_f32_16x16x32_bf16 v[68:71], v[148:151], v[226:229], v[68:71]
	v_mfma_f32_16x16x32_bf16 v[68:71], v[144:147], v[222:225], v[68:71]
	v_mfma_f32_16x16x32_bf16 v[72:75], v[92:95], v[222:225], v[72:75]
	v_mfma_f32_16x16x32_bf16 v[72:75], v[100:103], v[226:229], v[72:75]
	s_setprio 3
	s_barrier
; #define PG8_STAGE(bufoff, gbase, voff) do { _Pragma("unroll") for (int _i = 0; _i < 2; ++_i) \
;         __builtin_amdgcn_global_load_lds((const unsigned*)((const char*)(gbase) + (voff)[_i]), (PG8_LAS unsigned*)(lds + (bufoff) + ldsw + _i * 8192), 16, 0, 0); } while (0)
; #define PG8_LDA(dst, b, h) do { _Pragma("unroll") for (int m = 0; m < 4; ++m) _Pragma("unroll") for (int k = 0; k < 2; ++k) dst[m][k] = *(const PG8_LAS bf16x8*)(lds + PG8_SA(b, h) + aoff + m * 2048 + k * 1024); } while (0)
; #define PG8_MMA(ai, bj, At, Bt) do { __builtin_amdgcn_s_setprio(1); _Pragma("unroll") for (int m = 0; m < 4; ++m) _Pragma("unroll") for (int n = 0; n < 2; ++n) _Pragma("unroll") for (int k = 0; k < 2; ++k) \
;         acc[ai][bj][m][n] = __builtin_amdgcn_mfma_f32_16x16x32_bf16(Bt[n][k], At[m][k], acc[ai][bj][m][n], 0, 0, 0); __builtin_amdgcn_s_setprio(0); } while (0)
; #define PG8_WAIT_V(n) asm volatile("s_waitcnt vmcnt(" #n ")" ::: "memory")
; #define PG8_WAIT_L(n) asm volatile("s_waitcnt lgkmcnt(" #n ")" ::: "memory")
; #define PG8_BAR __builtin_amdgcn_s_barrier()
; #define PG8_SCHED __builtin_amdgcn_sched_barrier(0)
; template <class Epi, class Sched, bool ALIGN_EPI = false, bool SP2 = false>
; __device__ __forceinline__ void gemm_phase(PG8_LAS unsigned char* lds, const Gemm g, const Sched& S, const Epi& E) {
;     ...
;             PG8_WAIT_V(8); PG8_WAIT_L(0); PG8_BAR; PG8_MMA(0, 0, At, B0); PG8_MMA(0, 1, At, B1); PG8_BAR; PG8_SCHED;
;             PG8_LDA(At, 1, 1); PG8_STAGE(PG8_SB(1, 0), b3, voffB); PG8_STAGE(PG8_SB(1, 1), b3 + hstep, voffB); PG8_STAGE(PG8_SA(1, 0), a3, voffA);
;             PG8_WAIT_V(8); PG8_WAIT_L(0); PG8_BAR; PG8_MMA(1, 0, At, B0); PG8_MMA(1, 1, At, B1); PG8_BAR; PG8_SCHED;
;     ...
;         if constexpr (ALIGN_EPI) { if (wr == 0) PG8_BAR; }
	v_mfma_f32_16x16x32_bf16 v[76:79], v[84:87], v[226:229], v[76:79]
	v_mfma_f32_16x16x32_bf16 v[76:79], v[80:83], v[222:225], v[76:79]
	s_setprio 0
	s_add_i32 s44, s44, s13
	v_lshl_add_u64 v[200:201], v[200:201], 0, s[16:17]
	s_mov_b32 m0, s44
	ds_read_b128 v[178:181], v187 offset:49152
	ds_read_b128 v[182:185], v187 offset:50176
	ds_read_b128 v[206:209], v187 offset:51200
	ds_read_b128 v[210:213], v187 offset:52224
	ds_read_b128 v[214:217], v187 offset:53248
	ds_read_b128 v[218:221], v187 offset:54272
	ds_read_b128 v[222:225], v187 offset:55296
	ds_read_b128 v[226:229], v187 offset:56320
	global_load_lds_dwordx4 v[200:201], off
	s_add_i32 m0, s44, 0x2000
	s_add_u32 s28, s28, 0x80080
	v_lshl_add_u64 v[200:201], v[230:231], 0, s[16:17]
	s_addc_u32 s29, s29, 0
	s_add_i32 s44, s45, s13
	global_load_lds_dwordx4 v[200:201], off
	v_lshl_add_u64 v[200:201], s[28:29], 0, v[164:165]
	s_mov_b32 m0, s44
	s_nop 0
	global_load_lds_dwordx4 v[200:201], off
	v_lshl_add_u64 v[200:201], s[28:29], 0, v[168:169]
	s_add_i32 m0, s44, 0x2000
	s_nop 0
	global_load_lds_dwordx4 v[200:201], off
	v_lshl_add_u64 v[200:201], v[232:233], 0, s[16:17]
	s_mov_b32 m0, s56
	s_nop 0
	global_load_lds_dwordx4 v[200:201], off
	v_lshl_add_u64 v[200:201], v[234:235], 0, s[16:17]
	s_mov_b32 m0, s57
	s_nop 0
	global_load_lds_dwordx4 v[200:201], off
	s_waitcnt vmcnt(8)
	s_waitcnt lgkmcnt(0)
	s_barrier
	s_setprio 1
	s_waitcnt lgkmcnt(0)
	v_mfma_f32_16x16x32_bf16 v[60:63], v[80:83], v[178:181], v[60:63]
	v_mfma_f32_16x16x32_bf16 v[60:63], v[84:87], v[182:185], v[60:63]
	v_mfma_f32_16x16x32_bf16 v[56:59], v[100:103], v[182:185], v[56:59]
	v_mfma_f32_16x16x32_bf16 v[56:59], v[92:95], v[178:181], v[56:59]
	v_mfma_f32_16x16x32_bf16 v[52:55], v[144:147], v[178:181], v[52:55]
	v_mfma_f32_16x16x32_bf16 v[52:55], v[148:151], v[182:185], v[52:55]
	v_mfma_f32_16x16x32_bf16 v[48:51], v[156:159], v[182:185], v[48:51]
	v_mfma_f32_16x16x32_bf16 v[48:51], v[152:155], v[178:181], v[48:51]
	v_mfma_f32_16x16x32_bf16 v[32:35], v[152:155], v[206:209], v[32:35]
	v_mfma_f32_16x16x32_bf16 v[32:35], v[156:159], v[210:213], v[32:35]
	v_mfma_f32_16x16x32_bf16 v[36:39], v[148:151], v[210:213], v[36:39]
	v_mfma_f32_16x16x32_bf16 v[36:39], v[144:147], v[206:209], v[36:39]
	v_mfma_f32_16x16x32_bf16 v[40:43], v[92:95], v[206:209], v[40:43]
	v_mfma_f32_16x16x32_bf16 v[40:43], v[100:103], v[210:213], v[40:43]
	v_mfma_f32_16x16x32_bf16 v[44:47], v[84:87], v[210:213], v[44:47]
	v_mfma_f32_16x16x32_bf16 v[44:47], v[80:83], v[206:209], v[44:47]
	s_setprio 0
	s_setprio 1
	v_mfma_f32_16x16x32_bf16 v[28:31], v[80:83], v[214:217], v[28:31]
	v_mfma_f32_16x16x32_bf16 v[28:31], v[84:87], v[218:221], v[28:31]
	v_mfma_f32_16x16x32_bf16 v[24:27], v[100:103], v[218:221], v[24:27]
	v_mfma_f32_16x16x32_bf16 v[24:27], v[92:95], v[214:217], v[24:27]
	v_mfma_f32_16x16x32_bf16 v[20:23], v[144:147], v[214:217], v[20:23]
	v_mfma_f32_16x16x32_bf16 v[20:23], v[148:151], v[218:221], v[20:23]
	v_mfma_f32_16x16x32_bf16 v[16:19], v[156:159], v[218:221], v[16:19]
	v_mfma_f32_16x16x32_bf16 v[16:19], v[152:155], v[214:217], v[16:19]
	v_mfma_f32_16x16x32_bf16 v[0:3], v[152:155], v[222:225], v[0:3]
	v_mfma_f32_16x16x32_bf16 v[0:3], v[156:159], v[226:229], v[0:3]
	v_mfma_f32_16x16x32_bf16 v[4:7], v[148:151], v[226:229], v[4:7]
	v_mfma_f32_16x16x32_bf16 v[4:7], v[144:147], v[222:225], v[4:7]
	v_mfma_f32_16x16x32_bf16 v[8:11], v[92:95], v[222:225], v[8:11]
	v_mfma_f32_16x16x32_bf16 v[8:11], v[100:103], v[226:229], v[8:11]
	s_setprio 3
	s_barrier
	v_mfma_f32_16x16x32_bf16 v[12:15], v[84:87], v[226:229], v[12:15]
	v_mfma_f32_16x16x32_bf16 v[12:15], v[80:83], v[222:225], v[12:15]
	s_setprio 0
	s_add_i32 s77, s77, 2
	s_add_u32 s74, s74, 0x100
	s_addc_u32 s75, s75, 0
	s_add_u32 s73, s73, 0x100
	s_addc_u32 s76, s76, 0
	s_cmp_gt_u32 s77, 29
	s_cbranch_scc0 .LBB0_362
	s_and_b64 vcc, exec, s[18:19]
	s_cbranch_vccz .LBB0_365
	s_barrier

; #define PG8_STAGE(bufoff, gbase, voff) do { _Pragma("unroll") for (int _i = 0; _i < 2; ++_i) \
;         __builtin_amdgcn_global_load_lds((const unsigned*)((const char*)(gbase) + (voff)[_i]), (PG8_LAS unsigned*)(lds + (bufoff) + ldsw + _i * 8192), 16, 0, 0); } while (0)
; #define PG8_LDA(dst, b, h) do { _Pragma("unroll") for (int m = 0; m < 4; ++m) _Pragma("unroll") for (int k = 0; k < 2; ++k) dst[m][k] = *(const PG8_LAS bf16x8*)(lds + PG8_SA(b, h) + aoff + m * 2048 + k * 1024); } while (0)
; #define PG8_LDB(dst, b, h) do { _Pragma("unroll") for (int n = 0; n < 2; ++n) _Pragma("unroll") for (int k = 0; k < 2; ++k) dst[n][k] = *(const PG8_LAS bf16x8*)(lds + PG8_SB(b, h) + boff + n * 2048 + k * 1024); } while (0)
; #define PG8_MMA(ai, bj, At, Bt) do { __builtin_amdgcn_s_setprio(1); _Pragma("unroll") for (int m = 0; m < 4; ++m) _Pragma("unroll") for (int n = 0; n < 2; ++n) _Pragma("unroll") for (int k = 0; k < 2; ++k) \
;         acc[ai][bj][m][n] = __builtin_amdgcn_mfma_f32_16x16x32_bf16(Bt[n][k], At[m][k], acc[ai][bj][m][n], 0, 0, 0); __builtin_amdgcn_s_setprio(0); } while (0)
; #define PG8_WAIT_V(n) asm volatile("s_waitcnt vmcnt(" #n ")" ::: "memory")
; #define PG8_WAIT_L(n) asm volatile("s_waitcnt lgkmcnt(" #n ")" ::: "memory")
; template <class Epi, class Sched, bool ALIGN_EPI = false, bool SP2 = false>
; __device__ __forceinline__ void gemm_phase(PG8_LAS unsigned char* lds, const Gemm g, const Sched& S, const Epi& E) {
;     ...
;             const bool last = (t == nt - 2);
;             const char* a1 = cA + (size_t)(t + 1) * kstep;
;             const char* a2 = last ? nA : cA + (size_t)(t + 2) * kstep; const char* b2 = last ? nB : cB + (size_t)(t + 2) * kstep;
;             const char* a3 = a2 + kstep; const char* b3 = b2 + kstep;
;             if (last && has_next) S.a_ready(nxt);
;             if constexpr (SP2) {
;             PG8_LDB(B0, 0, 0); PG8_LDB(B1, 0, 1); PG8_SCHED; PG8_LDA(At, 0, 0); PG8_STAGE(PG8_SA(1, 1), a1 + hstep, voffA);
;             PG8_WAIT_V(8); PG8_WAIT_L(0); PG8_BAR; PG8_MMA(0, 0, At, B0); PG8_MMA(0, 1, At, B1); PG8_BAR; PG8_SCHED;
;             PG8_LDA(At, 0, 1); PG8_STAGE(PG8_SB(0, 0), b2, voffB); PG8_STAGE(PG8_SB(0, 1), b2 + hstep, voffB); PG8_STAGE(PG8_SA(0, 0), a2, voffA);
;             PG8_WAIT_V(8); PG8_WAIT_L(0); PG8_BAR; PG8_MMA(1, 0, At, B0); PG8_MMA(1, 1, At, B1); PG8_BAR; PG8_SCHED;
.LBB0_416:
	ds_read_b128 v[136:139], v156
	ds_read_b128 v[140:143], v156 offset:1024
	ds_read_b128 v[172:175], v156 offset:2048
	ds_read_b128 v[176:179], v156 offset:3072
	ds_read_b128 v[180:183], v157
	ds_read_b128 v[184:187], v157 offset:1024
	ds_read_b128 v[206:209], v157 offset:2048
	ds_read_b128 v[210:213], v157 offset:3072
	s_add_u32 s28, s68, 0xfff80080
	s_addc_u32 s29, s69, -1
	s_cmp_eq_u32 s79, 28
	s_cselect_b32 s49, s34, s29
	s_cselect_b32 s48, s35, s28
	s_cselect_b32 s29, s23, s78
	s_cselect_b32 s28, s63, s77
	v_lshl_add_u64 v[200:201], s[68:69], 0, v[128:129]
	s_add_i32 m0, s15, 0xc000
	ds_read_b128 v[214:217], v158
	ds_read_b128 v[218:221], v158 offset:1024
	ds_read_b128 v[222:225], v158 offset:2048
	ds_read_b128 v[226:229], v158 offset:3072
	ds_read_b128 v[230:233], v158 offset:4096
	ds_read_b128 v[234:237], v158 offset:5120
	ds_read_b128 v[238:241], v158 offset:6144
	ds_read_b128 v[242:245], v158 offset:7168
	global_load_lds_dwordx4 v[200:201], off
	v_lshl_add_u64 v[200:201], s[68:69], 0, v[130:131]
	s_add_i32 m0, s15, 0xe000
	s_nop 0
	global_load_lds_dwordx4 v[200:201], off
	s_waitcnt vmcnt(8)
	s_waitcnt lgkmcnt(0)
	s_barrier
	s_setprio 1
	s_waitcnt lgkmcnt(0)
	v_mfma_f32_16x16x32_bf16 v[124:127], v[136:139], v[214:217], v[124:127]
	v_mfma_f32_16x16x32_bf16 v[124:127], v[140:143], v[218:221], v[124:127]
	v_mfma_f32_16x16x32_bf16 v[120:123], v[176:179], v[218:221], v[120:123]
	v_mfma_f32_16x16x32_bf16 v[120:123], v[172:175], v[214:217], v[120:123]
	v_mfma_f32_16x16x32_bf16 v[116:119], v[180:183], v[214:217], v[116:119]
	v_mfma_f32_16x16x32_bf16 v[116:119], v[184:187], v[218:221], v[116:119]
	v_mfma_f32_16x16x32_bf16 v[112:115], v[210:213], v[218:221], v[112:115]
	v_mfma_f32_16x16x32_bf16 v[112:115], v[206:209], v[214:217], v[112:115]
	v_mfma_f32_16x16x32_bf16 v[92:95], v[206:209], v[222:225], v[92:95]
	v_mfma_f32_16x16x32_bf16 v[92:95], v[210:213], v[226:229], v[92:95]
	v_mfma_f32_16x16x32_bf16 v[100:103], v[184:187], v[226:229], v[100:103]
	v_mfma_f32_16x16x32_bf16 v[100:103], v[180:183], v[222:225], v[100:103]
	v_mfma_f32_16x16x32_bf16 v[104:107], v[172:175], v[222:225], v[104:107]
	v_mfma_f32_16x16x32_bf16 v[104:107], v[176:179], v[226:229], v[104:107]
	v_mfma_f32_16x16x32_bf16 v[108:111], v[140:143], v[226:229], v[108:111]
	v_mfma_f32_16x16x32_bf16 v[108:111], v[136:139], v[222:225], v[108:111]
	s_setprio 0
	s_setprio 1
	v_mfma_f32_16x16x32_bf16 v[96:99], v[136:139], v[230:233], v[96:99]
	v_mfma_f32_16x16x32_bf16 v[96:99], v[140:143], v[234:237], v[96:99]
	v_mfma_f32_16x16x32_bf16 v[88:91], v[176:179], v[234:237], v[88:91]
	v_mfma_f32_16x16x32_bf16 v[88:91], v[172:175], v[230:233], v[88:91]
	v_mfma_f32_16x16x32_bf16 v[84:87], v[180:183], v[230:233], v[84:87]
	v_mfma_f32_16x16x32_bf16 v[84:87], v[184:187], v[234:237], v[84:87]
	v_mfma_f32_16x16x32_bf16 v[76:79], v[210:213], v[234:237], v[76:79]
	v_mfma_f32_16x16x32_bf16 v[76:79], v[206:209], v[230:233], v[76:79]
	v_mfma_f32_16x16x32_bf16 v[64:67], v[206:209], v[238:241], v[64:67]
	v_mfma_f32_16x16x32_bf16 v[64:67], v[210:213], v[242:245], v[64:67]
	v_mfma_f32_16x16x32_bf16 v[68:71], v[184:187], v[242:245], v[68:71]
	v_mfma_f32_16x16x32_bf16 v[68:71], v[180:183], v[238:241], v[68:71]
	v_mfma_f32_16x16x32_bf16 v[72:75], v[172:175], v[238:241], v[72:75]
	v_mfma_f32_16x16x32_bf16 v[72:75], v[176:179], v[242:245], v[72:75]
	s_setprio 3
	s_barrier
	v_mfma_f32_16x16x32_bf16 v[80:83], v[140:143], v[242:245], v[80:83]
	v_mfma_f32_16x16x32_bf16 v[80:83], v[136:139], v[238:241], v[80:83]
	s_setprio 0
	s_add_i32 s44, s72, s39
	v_lshl_add_u64 v[200:201], s[28:29], 0, v[166:167]
	s_mov_b32 m0, s44
	ds_read_b128 v[214:217], v158 offset:16384
	ds_read_b128 v[218:221], v158 offset:17408
	ds_read_b128 v[222:225], v158 offset:18432
	ds_read_b128 v[226:229], v158 offset:19456
	ds_read_b128 v[230:233], v158 offset:20480
	ds_read_b128 v[234:237], v158 offset:21504
	ds_read_b128 v[238:241], v158 offset:22528
	ds_read_b128 v[242:245], v158 offset:23552
	global_load_lds_dwordx4 v[200:201], off
	s_add_i32 m0, s44, 0x2000
	s_add_u32 s80, s28, 0x80000
	v_lshl_add_u64 v[246:247], s[28:29], 0, v[170:171]
	s_addc_u32 s81, s29, 0
	s_add_i32 s44, s73, s39
	global_load_lds_dwordx4 v[246:247], off
	v_lshl_add_u64 v[248:249], s[80:81], 0, v[166:167]
	s_mov_b32 m0, s44
	v_lshl_add_u64 v[250:251], s[48:49], 0, v[168:169]
	global_load_lds_dwordx4 v[248:249], off
	v_lshl_add_u64 v[248:249], s[80:81], 0, v[170:171]
	s_add_i32 m0, s44, 0x2000
	s_nop 0
	global_load_lds_dwordx4 v[248:249], off
	v_lshl_add_u64 v[248:249], s[48:49], 0, v[164:165]
	s_mov_b32 m0, s15
	s_nop 0
	global_load_lds_dwordx4 v[248:249], off
	s_mov_b32 m0, s41
	s_nop 0
	global_load_lds_dwordx4 v[250:251], off
	s_waitcnt vmcnt(8)
	s_waitcnt lgkmcnt(0)
	s_barrier
; #define PG8_STAGE(bufoff, gbase, voff) do { _Pragma("unroll") for (int _i = 0; _i < 2; ++_i) \
;         __builtin_amdgcn_global_load_lds((const unsigned*)((const char*)(gbase) + (voff)[_i]), (PG8_LAS unsigned*)(lds + (bufoff) + ldsw + _i * 8192), 16, 0, 0); } while (0)
; #define PG8_LDA(dst, b, h) do { _Pragma("unroll") for (int m = 0; m < 4; ++m) _Pragma("unroll") for (int k = 0; k < 2; ++k) dst[m][k] = *(const PG8_LAS bf16x8*)(lds + PG8_SA(b, h) + aoff + m * 2048 + k * 1024); } while (0)
; #define PG8_LDB(dst, b, h) do { _Pragma("unroll") for (int n = 0; n < 2; ++n) _Pragma("unroll") for (int k = 0; k < 2; ++k) dst[n][k] = *(const PG8_LAS bf16x8*)(lds + PG8_SB(b, h) + boff + n * 2048 + k * 1024); } while (0)
; #define PG8_MMA(ai, bj, At, Bt) do { __builtin_amdgcn_s_setprio(1); _Pragma("unroll") for (int m = 0; m < 4; ++m) _Pragma("unroll") for (int n = 0; n < 2; ++n) _Pragma("unroll") for (int k = 0; k < 2; ++k) \
;         acc[ai][bj][m][n] = __builtin_amdgcn_mfma_f32_16x16x32_bf16(Bt[n][k], At[m][k], acc[ai][bj][m][n], 0, 0, 0); __builtin_amdgcn_s_setprio(0); } while (0)
; #define PG8_WAIT_V(n) asm volatile("s_waitcnt vmcnt(" #n ")" ::: "memory")
; #define PG8_WAIT_L(n) asm volatile("s_waitcnt lgkmcnt(" #n ")" ::: "memory")
; #define PG8_BAR __builtin_amdgcn_s_barrier()
; #define PG8_SCHED __builtin_amdgcn_sched_barrier(0)
; template <class Epi, class Sched, bool ALIGN_EPI = false, bool SP2 = false>
; __device__ __forceinline__ void gemm_phase(PG8_LAS unsigned char* lds, const Gemm g, const Sched& S, const Epi& E) {
;     ...
;             PG8_WAIT_V(8); PG8_WAIT_L(0); PG8_BAR; PG8_MMA(1, 0, At, B0); PG8_MMA(1, 1, At, B1); PG8_BAR; PG8_SCHED;
;             PG8_LDB(B0, 1, 0); PG8_LDB(B1, 1, 1); PG8_SCHED; PG8_LDA(At, 1, 0); PG8_STAGE(PG8_SA(0, 1), a2 + hstep, voffA);
;             PG8_WAIT_V(8); PG8_WAIT_L(0); PG8_BAR; PG8_MMA(0, 0, At, B0); PG8_MMA(0, 1, At, B1); PG8_BAR; PG8_SCHED;
	s_setprio 1
	s_waitcnt lgkmcnt(0)
	v_mfma_f32_16x16x32_bf16 v[60:63], v[136:139], v[214:217], v[60:63]
	v_mfma_f32_16x16x32_bf16 v[60:63], v[140:143], v[218:221], v[60:63]
	v_mfma_f32_16x16x32_bf16 v[56:59], v[176:179], v[218:221], v[56:59]
	v_mfma_f32_16x16x32_bf16 v[56:59], v[172:175], v[214:217], v[56:59]
	v_mfma_f32_16x16x32_bf16 v[52:55], v[180:183], v[214:217], v[52:55]
	v_mfma_f32_16x16x32_bf16 v[52:55], v[184:187], v[218:221], v[52:55]
	v_mfma_f32_16x16x32_bf16 v[44:47], v[210:213], v[218:221], v[44:47]
	v_mfma_f32_16x16x32_bf16 v[44:47], v[206:209], v[214:217], v[44:47]
	v_mfma_f32_16x16x32_bf16 v[28:31], v[206:209], v[222:225], v[28:31]
	v_mfma_f32_16x16x32_bf16 v[28:31], v[210:213], v[226:229], v[28:31]
	v_mfma_f32_16x16x32_bf16 v[36:39], v[184:187], v[226:229], v[36:39]
	v_mfma_f32_16x16x32_bf16 v[36:39], v[180:183], v[222:225], v[36:39]
	v_mfma_f32_16x16x32_bf16 v[40:43], v[172:175], v[222:225], v[40:43]
	v_mfma_f32_16x16x32_bf16 v[40:43], v[176:179], v[226:229], v[40:43]
	v_mfma_f32_16x16x32_bf16 v[48:51], v[140:143], v[226:229], v[48:51]
	v_mfma_f32_16x16x32_bf16 v[48:51], v[136:139], v[222:225], v[48:51]
	s_setprio 0
	s_setprio 1
	v_mfma_f32_16x16x32_bf16 v[32:35], v[136:139], v[230:233], v[32:35]
	v_mfma_f32_16x16x32_bf16 v[32:35], v[140:143], v[234:237], v[32:35]
	v_mfma_f32_16x16x32_bf16 v[24:27], v[176:179], v[234:237], v[24:27]
	v_mfma_f32_16x16x32_bf16 v[24:27], v[172:175], v[230:233], v[24:27]
	v_mfma_f32_16x16x32_bf16 v[20:23], v[180:183], v[230:233], v[20:23]
	v_mfma_f32_16x16x32_bf16 v[20:23], v[184:187], v[234:237], v[20:23]
	v_mfma_f32_16x16x32_bf16 v[16:19], v[210:213], v[234:237], v[16:19]
	v_mfma_f32_16x16x32_bf16 v[16:19], v[206:209], v[230:233], v[16:19]
	v_mfma_f32_16x16x32_bf16 v[0:3], v[206:209], v[238:241], v[0:3]
	v_mfma_f32_16x16x32_bf16 v[0:3], v[210:213], v[242:245], v[0:3]
	v_mfma_f32_16x16x32_bf16 v[4:7], v[184:187], v[242:245], v[4:7]
	v_mfma_f32_16x16x32_bf16 v[4:7], v[180:183], v[238:241], v[4:7]
	v_mfma_f32_16x16x32_bf16 v[8:11], v[172:175], v[238:241], v[8:11]
	v_mfma_f32_16x16x32_bf16 v[8:11], v[176:179], v[242:245], v[8:11]
	s_setprio 3
	s_barrier
	v_mfma_f32_16x16x32_bf16 v[12:15], v[140:143], v[242:245], v[12:15]
	v_mfma_f32_16x16x32_bf16 v[12:15], v[136:139], v[238:241], v[12:15]
	s_setprio 0
	s_add_i32 s44, 0, 0x18000
	v_add_u32_e32 v144, s44, v146
	s_add_i32 s45, 0, 0x1c000
	ds_read_b128 v[136:139], v144
	ds_read_b128 v[140:143], v144 offset:1024
	ds_read_b128 v[172:175], v144 offset:2048
	ds_read_b128 v[176:179], v144 offset:3072
	v_add_u32_e32 v144, s45, v146
	ds_read_b128 v[180:183], v144
	ds_read_b128 v[184:187], v144 offset:1024
	ds_read_b128 v[206:209], v144 offset:2048
	ds_read_b128 v[210:213], v144 offset:3072
	s_add_u32 s48, s48, 0x80000
	s_addc_u32 s49, s49, 0
	s_mov_b32 m0, s56
	v_lshl_add_u64 v[252:253], s[48:49], 0, v[164:165]
	ds_read_b128 v[214:217], v158 offset:32768
	ds_read_b128 v[218:221], v158 offset:33792
	ds_read_b128 v[222:225], v158 offset:34816
	ds_read_b128 v[226:229], v158 offset:35840
	ds_read_b128 v[230:233], v158 offset:36864
	ds_read_b128 v[234:237], v158 offset:37888
	ds_read_b128 v[238:241], v158 offset:38912
	ds_read_b128 v[242:245], v158 offset:39936
	global_load_lds_dwordx4 v[252:253], off
	v_lshl_add_u64 v[252:253], s[48:49], 0, v[168:169]
	s_mov_b32 m0, s57
	s_nop 0
	global_load_lds_dwordx4 v[252:253], off
	s_waitcnt vmcnt(8)
	s_waitcnt lgkmcnt(0)
	s_barrier
	s_setprio 1
	s_waitcnt lgkmcnt(0)
	v_mfma_f32_16x16x32_bf16 v[124:127], v[136:139], v[214:217], v[124:127]
	v_mfma_f32_16x16x32_bf16 v[124:127], v[140:143], v[218:221], v[124:127]
	v_mfma_f32_16x16x32_bf16 v[120:123], v[176:179], v[218:221], v[120:123]
	v_mfma_f32_16x16x32_bf16 v[120:123], v[172:175], v[214:217], v[120:123]
	v_mfma_f32_16x16x32_bf16 v[116:119], v[180:183], v[214:217], v[116:119]
	v_mfma_f32_16x16x32_bf16 v[116:119], v[184:187], v[218:221], v[116:119]
	v_mfma_f32_16x16x32_bf16 v[112:115], v[210:213], v[218:221], v[112:115]
	v_mfma_f32_16x16x32_bf16 v[112:115], v[206:209], v[214:217], v[112:115]
	v_mfma_f32_16x16x32_bf16 v[92:95], v[206:209], v[222:225], v[92:95]
	v_mfma_f32_16x16x32_bf16 v[92:95], v[210:213], v[226:229], v[92:95]
	v_mfma_f32_16x16x32_bf16 v[100:103], v[184:187], v[226:229], v[100:103]
	v_mfma_f32_16x16x32_bf16 v[100:103], v[180:183], v[222:225], v[100:103]
	v_mfma_f32_16x16x32_bf16 v[104:107], v[172:175], v[222:225], v[104:107]
	v_mfma_f32_16x16x32_bf16 v[104:107], v[176:179], v[226:229], v[104:107]
	v_mfma_f32_16x16x32_bf16 v[108:111], v[140:143], v[226:229], v[108:111]
	v_mfma_f32_16x16x32_bf16 v[108:111], v[136:139], v[222:225], v[108:111]
	s_setprio 0
	s_setprio 1
	v_mfma_f32_16x16x32_bf16 v[96:99], v[136:139], v[230:233], v[96:99]
	v_mfma_f32_16x16x32_bf16 v[96:99], v[140:143], v[234:237], v[96:99]
	v_mfma_f32_16x16x32_bf16 v[88:91], v[176:179], v[234:237], v[88:91]
	v_mfma_f32_16x16x32_bf16 v[88:91], v[172:175], v[230:233], v[88:91]
	v_mfma_f32_16x16x32_bf16 v[84:87], v[180:183], v[230:233], v[84:87]
	v_mfma_f32_16x16x32_bf16 v[84:87], v[184:187], v[234:237], v[84:87]
	v_mfma_f32_16x16x32_bf16 v[76:79], v[210:213], v[234:237], v[76:79]
	v_mfma_f32_16x16x32_bf16 v[76:79], v[206:209], v[230:233], v[76:79]
	v_mfma_f32_16x16x32_bf16 v[64:67], v[206:209], v[238:241], v[64:67]
	v_mfma_f32_16x16x32_bf16 v[64:67], v[210:213], v[242:245], v[64:67]
	v_mfma_f32_16x16x32_bf16 v[68:71], v[184:187], v[242:245], v[68:71]
	v_mfma_f32_16x16x32_bf16 v[68:71], v[180:183], v[238:241], v[68:71]
	v_mfma_f32_16x16x32_bf16 v[72:75], v[172:175], v[238:241], v[72:75]
	v_mfma_f32_16x16x32_bf16 v[72:75], v[176:179], v[242:245], v[72:75]
	s_setprio 3
	s_barrier
; #define PG8_STAGE(bufoff, gbase, voff) do { _Pragma("unroll") for (int _i = 0; _i < 2; ++_i) \
;         __builtin_amdgcn_global_load_lds((const unsigned*)((const char*)(gbase) + (voff)[_i]), (PG8_LAS unsigned*)(lds + (bufoff) + ldsw + _i * 8192), 16, 0, 0); } while (0)
; #define PG8_LDA(dst, b, h) do { _Pragma("unroll") for (int m = 0; m < 4; ++m) _Pragma("unroll") for (int k = 0; k < 2; ++k) dst[m][k] = *(const PG8_LAS bf16x8*)(lds + PG8_SA(b, h) + aoff + m * 2048 + k * 1024); } while (0)
; #define PG8_MMA(ai, bj, At, Bt) do { __builtin_amdgcn_s_setprio(1); _Pragma("unroll") for (int m = 0; m < 4; ++m) _Pragma("unroll") for (int n = 0; n < 2; ++n) _Pragma("unroll") for (int k = 0; k < 2; ++k) \
;         acc[ai][bj][m][n] = __builtin_amdgcn_mfma_f32_16x16x32_bf16(Bt[n][k], At[m][k], acc[ai][bj][m][n], 0, 0, 0); __builtin_amdgcn_s_setprio(0); } while (0)
; #define PG8_WAIT_V(n) asm volatile("s_waitcnt vmcnt(" #n ")" ::: "memory")
; #define PG8_WAIT_L(n) asm volatile("s_waitcnt lgkmcnt(" #n ")" ::: "memory")
; #define PG8_BAR __builtin_amdgcn_s_barrier()
; #define PG8_SCHED __builtin_amdgcn_sched_barrier(0)
; template <class Epi, class Sched, bool ALIGN_EPI = false, bool SP2 = false>
; __device__ __forceinline__ void gemm_phase(PG8_LAS unsigned char* lds, const Gemm g, const Sched& S, const Epi& E) {
;     ...
;             PG8_WAIT_V(8); PG8_WAIT_L(0); PG8_BAR; PG8_MMA(0, 0, At, B0); PG8_MMA(0, 1, At, B1); PG8_BAR; PG8_SCHED;
;             PG8_LDA(At, 1, 1); PG8_STAGE(PG8_SB(1, 0), b3, voffB); PG8_STAGE(PG8_SB(1, 1), b3 + hstep, voffB); PG8_STAGE(PG8_SA(1, 0), a3, voffA);
;             PG8_WAIT_V(8); PG8_WAIT_L(0); PG8_BAR; PG8_MMA(1, 0, At, B0); PG8_MMA(1, 1, At, B1); PG8_BAR; PG8_SCHED;
;     ...
;         if constexpr (ALIGN_EPI) { if (wr == 0) PG8_BAR; }
	v_mfma_f32_16x16x32_bf16 v[80:83], v[140:143], v[242:245], v[80:83]
	v_mfma_f32_16x16x32_bf16 v[80:83], v[136:139], v[238:241], v[80:83]
	s_setprio 0
	s_add_i32 s44, s44, s39
	v_lshl_add_u64 v[200:201], v[200:201], 0, s[18:19]
	s_mov_b32 m0, s44
	ds_read_b128 v[214:217], v158 offset:49152
	ds_read_b128 v[218:221], v158 offset:50176
	ds_read_b128 v[222:225], v158 offset:51200
	ds_read_b128 v[226:229], v158 offset:52224
	ds_read_b128 v[230:233], v158 offset:53248
	ds_read_b128 v[234:237], v158 offset:54272
	ds_read_b128 v[238:241], v158 offset:55296
	ds_read_b128 v[242:245], v158 offset:56320
	global_load_lds_dwordx4 v[200:201], off
	s_add_i32 m0, s44, 0x2000
	s_add_u32 s28, s28, 0x80080
	v_lshl_add_u64 v[200:201], v[246:247], 0, s[18:19]
	s_addc_u32 s29, s29, 0
	s_add_i32 s44, s45, s39
	global_load_lds_dwordx4 v[200:201], off
	v_lshl_add_u64 v[200:201], s[28:29], 0, v[166:167]
	s_mov_b32 m0, s44
	s_nop 0
	global_load_lds_dwordx4 v[200:201], off
	v_lshl_add_u64 v[200:201], s[28:29], 0, v[170:171]
	s_add_i32 m0, s44, 0x2000
	s_nop 0
	global_load_lds_dwordx4 v[200:201], off
	v_lshl_add_u64 v[200:201], v[248:249], 0, s[18:19]
	s_mov_b32 m0, s70
	s_nop 0
	global_load_lds_dwordx4 v[200:201], off
	v_lshl_add_u64 v[200:201], v[250:251], 0, s[18:19]
	s_mov_b32 m0, s71
	s_nop 0
	global_load_lds_dwordx4 v[200:201], off
	s_waitcnt vmcnt(8)
	s_waitcnt lgkmcnt(0)
	s_barrier
	s_setprio 1
	s_waitcnt lgkmcnt(0)
	v_mfma_f32_16x16x32_bf16 v[60:63], v[136:139], v[214:217], v[60:63]
	v_mfma_f32_16x16x32_bf16 v[60:63], v[140:143], v[218:221], v[60:63]
	v_mfma_f32_16x16x32_bf16 v[56:59], v[176:179], v[218:221], v[56:59]
	v_mfma_f32_16x16x32_bf16 v[56:59], v[172:175], v[214:217], v[56:59]
	v_mfma_f32_16x16x32_bf16 v[52:55], v[180:183], v[214:217], v[52:55]
	v_mfma_f32_16x16x32_bf16 v[52:55], v[184:187], v[218:221], v[52:55]
	v_mfma_f32_16x16x32_bf16 v[44:47], v[210:213], v[218:221], v[44:47]
	v_mfma_f32_16x16x32_bf16 v[44:47], v[206:209], v[214:217], v[44:47]
	v_mfma_f32_16x16x32_bf16 v[28:31], v[206:209], v[222:225], v[28:31]
	v_mfma_f32_16x16x32_bf16 v[28:31], v[210:213], v[226:229], v[28:31]
	v_mfma_f32_16x16x32_bf16 v[36:39], v[184:187], v[226:229], v[36:39]
	v_mfma_f32_16x16x32_bf16 v[36:39], v[180:183], v[222:225], v[36:39]
	v_mfma_f32_16x16x32_bf16 v[40:43], v[172:175], v[222:225], v[40:43]
	v_mfma_f32_16x16x32_bf16 v[40:43], v[176:179], v[226:229], v[40:43]
	v_mfma_f32_16x16x32_bf16 v[48:51], v[140:143], v[226:229], v[48:51]
	v_mfma_f32_16x16x32_bf16 v[48:51], v[136:139], v[222:225], v[48:51]
	s_setprio 0
	s_setprio 1
	v_mfma_f32_16x16x32_bf16 v[32:35], v[136:139], v[230:233], v[32:35]
	v_mfma_f32_16x16x32_bf16 v[32:35], v[140:143], v[234:237], v[32:35]
	v_mfma_f32_16x16x32_bf16 v[24:27], v[176:179], v[234:237], v[24:27]
	v_mfma_f32_16x16x32_bf16 v[24:27], v[172:175], v[230:233], v[24:27]
	v_mfma_f32_16x16x32_bf16 v[20:23], v[180:183], v[230:233], v[20:23]
	v_mfma_f32_16x16x32_bf16 v[20:23], v[184:187], v[234:237], v[20:23]
	v_mfma_f32_16x16x32_bf16 v[16:19], v[210:213], v[234:237], v[16:19]
	v_mfma_f32_16x16x32_bf16 v[16:19], v[206:209], v[230:233], v[16:19]
	v_mfma_f32_16x16x32_bf16 v[0:3], v[206:209], v[238:241], v[0:3]
	v_mfma_f32_16x16x32_bf16 v[0:3], v[210:213], v[242:245], v[0:3]
	v_mfma_f32_16x16x32_bf16 v[4:7], v[184:187], v[242:245], v[4:7]
	v_mfma_f32_16x16x32_bf16 v[4:7], v[180:183], v[238:241], v[4:7]
	v_mfma_f32_16x16x32_bf16 v[8:11], v[172:175], v[238:241], v[8:11]
	v_mfma_f32_16x16x32_bf16 v[8:11], v[176:179], v[242:245], v[8:11]
	s_setprio 3
	s_barrier
	v_mfma_f32_16x16x32_bf16 v[12:15], v[140:143], v[242:245], v[12:15]
	v_mfma_f32_16x16x32_bf16 v[12:15], v[136:139], v[238:241], v[12:15]
	s_setprio 0
	s_add_i32 s79, s79, 2
	s_add_u32 s68, s68, 0x100
	s_addc_u32 s69, s69, 0
	s_add_u32 s77, s77, 0x100
	s_addc_u32 s78, s78, 0
	s_cmp_gt_u32 s79, 29
	s_cbranch_scc0 .LBB0_416
	s_and_b64 vcc, exec, s[20:21]
	s_cbranch_vccz .LBB0_419
	s_barrier

; #define PG8_STAGE(bufoff, gbase, voff) do { _Pragma("unroll") for (int _i = 0; _i < 2; ++_i) \
;         __builtin_amdgcn_global_load_lds((const unsigned*)((const char*)(gbase) + (voff)[_i]), (PG8_LAS unsigned*)(lds + (bufoff) + ldsw + _i * 8192), 16, 0, 0); } while (0)
; #define PG8_LDA(dst, b, h) do { _Pragma("unroll") for (int m = 0; m < 4; ++m) _Pragma("unroll") for (int k = 0; k < 2; ++k) dst[m][k] = *(const PG8_LAS bf16x8*)(lds + PG8_SA(b, h) + aoff + m * 2048 + k * 1024); } while (0)
; #define PG8_LDB(dst, b, h) do { _Pragma("unroll") for (int n = 0; n < 2; ++n) _Pragma("unroll") for (int k = 0; k < 2; ++k) dst[n][k] = *(const PG8_LAS bf16x8*)(lds + PG8_SB(b, h) + boff + n * 2048 + k * 1024); } while (0)
; #define PG8_MMA(ai, bj, At, Bt) do { __builtin_amdgcn_s_setprio(1); _Pragma("unroll") for (int m = 0; m < 4; ++m) _Pragma("unroll") for (int n = 0; n < 2; ++n) _Pragma("unroll") for (int k = 0; k < 2; ++k) \
;         acc[ai][bj][m][n] = __builtin_amdgcn_mfma_f32_16x16x32_bf16(Bt[n][k], At[m][k], acc[ai][bj][m][n], 0, 0, 0); __builtin_amdgcn_s_setprio(0); } while (0)
; #define PG8_WAIT_V(n) asm volatile("s_waitcnt vmcnt(" #n ")" ::: "memory")
; #define PG8_WAIT_L(n) asm volatile("s_waitcnt lgkmcnt(" #n ")" ::: "memory")
; template <class Epi, class Sched, bool ALIGN_EPI = false, bool SP2 = false>
; __device__ __forceinline__ void gemm_phase(PG8_LAS unsigned char* lds, const Gemm g, const Sched& S, const Epi& E) {
;     ...
;             const bool last = (t == nt - 2);
;             const char* a1 = cA + (size_t)(t + 1) * kstep;
;             const char* a2 = last ? nA : cA + (size_t)(t + 2) * kstep; const char* b2 = last ? nB : cB + (size_t)(t + 2) * kstep;
;             const char* a3 = a2 + kstep; const char* b3 = b2 + kstep;
;             if (last && has_next) S.a_ready(nxt);
;             if constexpr (SP2) {
;             PG8_LDB(B0, 0, 0); PG8_LDB(B1, 0, 1); PG8_SCHED; PG8_LDA(At, 0, 0); PG8_STAGE(PG8_SA(1, 1), a1 + hstep, voffA);
;             PG8_WAIT_V(8); PG8_WAIT_L(0); PG8_BAR; PG8_MMA(0, 0, At, B0); PG8_MMA(0, 1, At, B1); PG8_BAR; PG8_SCHED;
;             PG8_LDA(At, 0, 1); PG8_STAGE(PG8_SB(0, 0), b2, voffB); PG8_STAGE(PG8_SB(0, 1), b2 + hstep, voffB); PG8_STAGE(PG8_SA(0, 0), a2, voffA);
;             PG8_WAIT_V(8); PG8_WAIT_L(0); PG8_BAR; PG8_MMA(1, 0, At, B0); PG8_MMA(1, 1, At, B1); PG8_BAR; PG8_SCHED;
.LBB0_482:
	ds_read_b128 v[76:79], v171
	ds_read_b128 v[84:87], v171 offset:1024
	ds_read_b128 v[92:95], v171 offset:2048
	ds_read_b128 v[96:99], v171 offset:3072
	ds_read_b128 v[144:147], v186
	ds_read_b128 v[148:151], v186 offset:1024
	ds_read_b128 v[152:155], v186 offset:2048
	ds_read_b128 v[156:159], v186 offset:3072
	s_add_u32 s28, s64, 0xffea0080
	s_addc_u32 s29, s65, -1
	s_cmpk_eq_i32 s77, 0x54
	s_cselect_b32 s49, s39, s29
	s_cselect_b32 s48, s38, s28
	s_cselect_b32 s29, s63, s35
	s_cselect_b32 s28, s62, s34
	v_lshl_add_u64 v[200:201], s[64:65], 0, v[172:173]
	s_add_i32 m0, s56, 0xc000
	ds_read_b128 v[178:181], v187
	ds_read_b128 v[182:185], v187 offset:1024
	ds_read_b128 v[206:209], v187 offset:2048
	ds_read_b128 v[210:213], v187 offset:3072
	ds_read_b128 v[214:217], v187 offset:4096
	ds_read_b128 v[218:221], v187 offset:5120
	ds_read_b128 v[222:225], v187 offset:6144
	ds_read_b128 v[226:229], v187 offset:7168
	global_load_lds_dwordx4 v[200:201], off
	v_lshl_add_u64 v[200:201], s[64:65], 0, v[174:175]
	s_add_i32 m0, s56, 0xe000
	s_nop 0
	global_load_lds_dwordx4 v[200:201], off
	s_waitcnt vmcnt(8)
	s_waitcnt lgkmcnt(0)
	s_barrier
	s_setprio 1
	s_waitcnt lgkmcnt(0)
	v_mfma_f32_16x16x32_bf16 v[140:143], v[76:79], v[178:181], v[140:143]
	v_mfma_f32_16x16x32_bf16 v[140:143], v[84:87], v[182:185], v[140:143]
	v_mfma_f32_16x16x32_bf16 v[136:139], v[96:99], v[182:185], v[136:139]
	v_mfma_f32_16x16x32_bf16 v[136:139], v[92:95], v[178:181], v[136:139]
	v_mfma_f32_16x16x32_bf16 v[132:135], v[144:147], v[178:181], v[132:135]
	v_mfma_f32_16x16x32_bf16 v[132:135], v[148:151], v[182:185], v[132:135]
	v_mfma_f32_16x16x32_bf16 v[128:131], v[156:159], v[182:185], v[128:131]
	v_mfma_f32_16x16x32_bf16 v[128:131], v[152:155], v[178:181], v[128:131]
	v_mfma_f32_16x16x32_bf16 v[112:115], v[152:155], v[206:209], v[112:115]
	v_mfma_f32_16x16x32_bf16 v[112:115], v[156:159], v[210:213], v[112:115]
	v_mfma_f32_16x16x32_bf16 v[116:119], v[148:151], v[210:213], v[116:119]
	v_mfma_f32_16x16x32_bf16 v[116:119], v[144:147], v[206:209], v[116:119]
	v_mfma_f32_16x16x32_bf16 v[120:123], v[92:95], v[206:209], v[120:123]
	v_mfma_f32_16x16x32_bf16 v[120:123], v[96:99], v[210:213], v[120:123]
	v_mfma_f32_16x16x32_bf16 v[124:127], v[84:87], v[210:213], v[124:127]
	v_mfma_f32_16x16x32_bf16 v[124:127], v[76:79], v[206:209], v[124:127]
	s_setprio 0
	s_setprio 1
	v_mfma_f32_16x16x32_bf16 v[108:111], v[76:79], v[214:217], v[108:111]
	v_mfma_f32_16x16x32_bf16 v[108:111], v[84:87], v[218:221], v[108:111]
	v_mfma_f32_16x16x32_bf16 v[104:107], v[96:99], v[218:221], v[104:107]
	v_mfma_f32_16x16x32_bf16 v[104:107], v[92:95], v[214:217], v[104:107]
	v_mfma_f32_16x16x32_bf16 v[100:103], v[144:147], v[214:217], v[100:103]
	v_mfma_f32_16x16x32_bf16 v[100:103], v[148:151], v[218:221], v[100:103]
	v_mfma_f32_16x16x32_bf16 v[88:91], v[156:159], v[218:221], v[88:91]
	v_mfma_f32_16x16x32_bf16 v[88:91], v[152:155], v[214:217], v[88:91]
	v_mfma_f32_16x16x32_bf16 v[64:67], v[152:155], v[222:225], v[64:67]
	v_mfma_f32_16x16x32_bf16 v[64:67], v[156:159], v[226:229], v[64:67]
	v_mfma_f32_16x16x32_bf16 v[68:71], v[148:151], v[226:229], v[68:71]
	v_mfma_f32_16x16x32_bf16 v[68:71], v[144:147], v[222:225], v[68:71]
	v_mfma_f32_16x16x32_bf16 v[72:75], v[92:95], v[222:225], v[72:75]
	v_mfma_f32_16x16x32_bf16 v[72:75], v[96:99], v[226:229], v[72:75]
	s_setprio 3
	s_barrier
	v_mfma_f32_16x16x32_bf16 v[80:83], v[84:87], v[226:229], v[80:83]
	v_mfma_f32_16x16x32_bf16 v[80:83], v[76:79], v[222:225], v[80:83]
	s_setprio 0
	s_add_i32 s44, s70, s41
	v_lshl_add_u64 v[200:201], s[28:29], 0, v[160:161]
	s_mov_b32 m0, s44
	ds_read_b128 v[178:181], v187 offset:16384
	ds_read_b128 v[182:185], v187 offset:17408
	ds_read_b128 v[206:209], v187 offset:18432
	ds_read_b128 v[210:213], v187 offset:19456
	ds_read_b128 v[214:217], v187 offset:20480
	ds_read_b128 v[218:221], v187 offset:21504
	ds_read_b128 v[222:225], v187 offset:22528
	ds_read_b128 v[226:229], v187 offset:23552
	global_load_lds_dwordx4 v[200:201], off
	s_add_i32 m0, s44, 0x2000
	s_add_u32 s78, s28, 0x160000
	v_lshl_add_u64 v[230:231], s[28:29], 0, v[162:163]
	s_addc_u32 s79, s29, 0
	s_add_i32 s44, s71, s41
	global_load_lds_dwordx4 v[230:231], off
	v_lshl_add_u64 v[232:233], s[78:79], 0, v[160:161]
	s_mov_b32 m0, s44
	v_lshl_add_u64 v[234:235], s[48:49], 0, v[162:163]
	global_load_lds_dwordx4 v[232:233], off
	v_lshl_add_u64 v[232:233], s[78:79], 0, v[162:163]
	s_add_i32 m0, s44, 0x2000
	s_nop 0
	global_load_lds_dwordx4 v[232:233], off
	v_lshl_add_u64 v[232:233], s[48:49], 0, v[160:161]
	s_mov_b32 m0, s56
	s_nop 0
	global_load_lds_dwordx4 v[232:233], off
	s_mov_b32 m0, s57
	s_nop 0
	global_load_lds_dwordx4 v[234:235], off
	s_waitcnt vmcnt(8)
	s_waitcnt lgkmcnt(0)
	s_barrier
; #define PG8_STAGE(bufoff, gbase, voff) do { _Pragma("unroll") for (int _i = 0; _i < 2; ++_i) \
;         __builtin_amdgcn_global_load_lds((const unsigned*)((const char*)(gbase) + (voff)[_i]), (PG8_LAS unsigned*)(lds + (bufoff) + ldsw + _i * 8192), 16, 0, 0); } while (0)
; #define PG8_LDA(dst, b, h) do { _Pragma("unroll") for (int m = 0; m < 4; ++m) _Pragma("unroll") for (int k = 0; k < 2; ++k) dst[m][k] = *(const PG8_LAS bf16x8*)(lds + PG8_SA(b, h) + aoff + m * 2048 + k * 1024); } while (0)
; #define PG8_LDB(dst, b, h) do { _Pragma("unroll") for (int n = 0; n < 2; ++n) _Pragma("unroll") for (int k = 0; k < 2; ++k) dst[n][k] = *(const PG8_LAS bf16x8*)(lds + PG8_SB(b, h) + boff + n * 2048 + k * 1024); } while (0)
; #define PG8_MMA(ai, bj, At, Bt) do { __builtin_amdgcn_s_setprio(1); _Pragma("unroll") for (int m = 0; m < 4; ++m) _Pragma("unroll") for (int n = 0; n < 2; ++n) _Pragma("unroll") for (int k = 0; k < 2; ++k) \
;         acc[ai][bj][m][n] = __builtin_amdgcn_mfma_f32_16x16x32_bf16(Bt[n][k], At[m][k], acc[ai][bj][m][n], 0, 0, 0); __builtin_amdgcn_s_setprio(0); } while (0)
; #define PG8_WAIT_V(n) asm volatile("s_waitcnt vmcnt(" #n ")" ::: "memory")
; #define PG8_WAIT_L(n) asm volatile("s_waitcnt lgkmcnt(" #n ")" ::: "memory")
; #define PG8_BAR __builtin_amdgcn_s_barrier()
; #define PG8_SCHED __builtin_amdgcn_sched_barrier(0)
; template <class Epi, class Sched, bool ALIGN_EPI = false, bool SP2 = false>
; __device__ __forceinline__ void gemm_phase(PG8_LAS unsigned char* lds, const Gemm g, const Sched& S, const Epi& E) {
;     ...
;             PG8_WAIT_V(8); PG8_WAIT_L(0); PG8_BAR; PG8_MMA(1, 0, At, B0); PG8_MMA(1, 1, At, B1); PG8_BAR; PG8_SCHED;
;             PG8_LDB(B0, 1, 0); PG8_LDB(B1, 1, 1); PG8_SCHED; PG8_LDA(At, 1, 0); PG8_STAGE(PG8_SA(0, 1), a2 + hstep, voffA);
;             PG8_WAIT_V(8); PG8_WAIT_L(0); PG8_BAR; PG8_MMA(0, 0, At, B0); PG8_MMA(0, 1, At, B1); PG8_BAR; PG8_SCHED;
	s_setprio 1
	s_waitcnt lgkmcnt(0)
	v_mfma_f32_16x16x32_bf16 v[60:63], v[76:79], v[178:181], v[60:63]
	v_mfma_f32_16x16x32_bf16 v[60:63], v[84:87], v[182:185], v[60:63]
	v_mfma_f32_16x16x32_bf16 v[56:59], v[96:99], v[182:185], v[56:59]
	v_mfma_f32_16x16x32_bf16 v[56:59], v[92:95], v[178:181], v[56:59]
	v_mfma_f32_16x16x32_bf16 v[52:55], v[144:147], v[178:181], v[52:55]
	v_mfma_f32_16x16x32_bf16 v[52:55], v[148:151], v[182:185], v[52:55]
	v_mfma_f32_16x16x32_bf16 v[48:51], v[156:159], v[182:185], v[48:51]
	v_mfma_f32_16x16x32_bf16 v[48:51], v[152:155], v[178:181], v[48:51]
	v_mfma_f32_16x16x32_bf16 v[32:35], v[152:155], v[206:209], v[32:35]
	v_mfma_f32_16x16x32_bf16 v[32:35], v[156:159], v[210:213], v[32:35]
	v_mfma_f32_16x16x32_bf16 v[36:39], v[148:151], v[210:213], v[36:39]
	v_mfma_f32_16x16x32_bf16 v[36:39], v[144:147], v[206:209], v[36:39]
	v_mfma_f32_16x16x32_bf16 v[40:43], v[92:95], v[206:209], v[40:43]
	v_mfma_f32_16x16x32_bf16 v[40:43], v[96:99], v[210:213], v[40:43]
	v_mfma_f32_16x16x32_bf16 v[44:47], v[84:87], v[210:213], v[44:47]
	v_mfma_f32_16x16x32_bf16 v[44:47], v[76:79], v[206:209], v[44:47]
	s_setprio 0
	s_setprio 1
	v_mfma_f32_16x16x32_bf16 v[28:31], v[76:79], v[214:217], v[28:31]
	v_mfma_f32_16x16x32_bf16 v[28:31], v[84:87], v[218:221], v[28:31]
	v_mfma_f32_16x16x32_bf16 v[24:27], v[96:99], v[218:221], v[24:27]
	v_mfma_f32_16x16x32_bf16 v[24:27], v[92:95], v[214:217], v[24:27]
	v_mfma_f32_16x16x32_bf16 v[20:23], v[144:147], v[214:217], v[20:23]
	v_mfma_f32_16x16x32_bf16 v[20:23], v[148:151], v[218:221], v[20:23]
	v_mfma_f32_16x16x32_bf16 v[16:19], v[156:159], v[218:221], v[16:19]
	v_mfma_f32_16x16x32_bf16 v[16:19], v[152:155], v[214:217], v[16:19]
	v_mfma_f32_16x16x32_bf16 v[0:3], v[152:155], v[222:225], v[0:3]
	v_mfma_f32_16x16x32_bf16 v[0:3], v[156:159], v[226:229], v[0:3]
	v_mfma_f32_16x16x32_bf16 v[4:7], v[148:151], v[226:229], v[4:7]
	v_mfma_f32_16x16x32_bf16 v[4:7], v[144:147], v[222:225], v[4:7]
	v_mfma_f32_16x16x32_bf16 v[8:11], v[92:95], v[222:225], v[8:11]
	v_mfma_f32_16x16x32_bf16 v[8:11], v[96:99], v[226:229], v[8:11]
	s_setprio 3
	s_barrier
	v_mfma_f32_16x16x32_bf16 v[12:15], v[84:87], v[226:229], v[12:15]
	v_mfma_f32_16x16x32_bf16 v[12:15], v[76:79], v[222:225], v[12:15]
	s_setprio 0
	s_add_i32 s44, 0, 0x18000
	s_add_i32 s45, 0, 0x1c000
	v_add_u32_e32 v96, s44, v167
	v_add_u32_e32 v156, s45, v167
	ds_read_b128 v[76:79], v96
	ds_read_b128 v[84:87], v96 offset:1024
	ds_read_b128 v[92:95], v96 offset:2048
	ds_read_b128 v[96:99], v96 offset:3072
	ds_read_b128 v[144:147], v156
	ds_read_b128 v[148:151], v156 offset:1024
	ds_read_b128 v[152:155], v156 offset:2048
	ds_read_b128 v[156:159], v156 offset:3072
	s_add_u32 s48, s48, 0x160000
	s_addc_u32 s49, s49, 0
	s_mov_b32 m0, s61
	v_lshl_add_u64 v[236:237], s[48:49], 0, v[160:161]
	ds_read_b128 v[178:181], v187 offset:32768
	ds_read_b128 v[182:185], v187 offset:33792
	ds_read_b128 v[206:209], v187 offset:34816
	ds_read_b128 v[210:213], v187 offset:35840
	ds_read_b128 v[214:217], v187 offset:36864
	ds_read_b128 v[218:221], v187 offset:37888
	ds_read_b128 v[222:225], v187 offset:38912
	ds_read_b128 v[226:229], v187 offset:39936
	global_load_lds_dwordx4 v[236:237], off
	v_lshl_add_u64 v[236:237], s[48:49], 0, v[162:163]
	s_mov_b32 m0, s66
	s_nop 0
	global_load_lds_dwordx4 v[236:237], off
	s_waitcnt vmcnt(8)
	s_waitcnt lgkmcnt(0)
	s_barrier
	s_setprio 1
	s_waitcnt lgkmcnt(0)
	v_mfma_f32_16x16x32_bf16 v[140:143], v[76:79], v[178:181], v[140:143]
	v_mfma_f32_16x16x32_bf16 v[140:143], v[84:87], v[182:185], v[140:143]
	v_mfma_f32_16x16x32_bf16 v[136:139], v[96:99], v[182:185], v[136:139]
	v_mfma_f32_16x16x32_bf16 v[136:139], v[92:95], v[178:181], v[136:139]
	v_mfma_f32_16x16x32_bf16 v[132:135], v[144:147], v[178:181], v[132:135]
	v_mfma_f32_16x16x32_bf16 v[132:135], v[148:151], v[182:185], v[132:135]
	v_mfma_f32_16x16x32_bf16 v[128:131], v[156:159], v[182:185], v[128:131]
	v_mfma_f32_16x16x32_bf16 v[128:131], v[152:155], v[178:181], v[128:131]
	v_mfma_f32_16x16x32_bf16 v[112:115], v[152:155], v[206:209], v[112:115]
	v_mfma_f32_16x16x32_bf16 v[112:115], v[156:159], v[210:213], v[112:115]
	v_mfma_f32_16x16x32_bf16 v[116:119], v[148:151], v[210:213], v[116:119]
	v_mfma_f32_16x16x32_bf16 v[116:119], v[144:147], v[206:209], v[116:119]
	v_mfma_f32_16x16x32_bf16 v[120:123], v[92:95], v[206:209], v[120:123]
	v_mfma_f32_16x16x32_bf16 v[120:123], v[96:99], v[210:213], v[120:123]
	v_mfma_f32_16x16x32_bf16 v[124:127], v[84:87], v[210:213], v[124:127]
	v_mfma_f32_16x16x32_bf16 v[124:127], v[76:79], v[206:209], v[124:127]
	s_setprio 0
	s_setprio 1
	v_mfma_f32_16x16x32_bf16 v[108:111], v[76:79], v[214:217], v[108:111]
	v_mfma_f32_16x16x32_bf16 v[108:111], v[84:87], v[218:221], v[108:111]
	v_mfma_f32_16x16x32_bf16 v[104:107], v[96:99], v[218:221], v[104:107]
	v_mfma_f32_16x16x32_bf16 v[104:107], v[92:95], v[214:217], v[104:107]
	v_mfma_f32_16x16x32_bf16 v[100:103], v[144:147], v[214:217], v[100:103]
	v_mfma_f32_16x16x32_bf16 v[100:103], v[148:151], v[218:221], v[100:103]
	v_mfma_f32_16x16x32_bf16 v[88:91], v[156:159], v[218:221], v[88:91]
	v_mfma_f32_16x16x32_bf16 v[88:91], v[152:155], v[214:217], v[88:91]
	v_mfma_f32_16x16x32_bf16 v[64:67], v[152:155], v[222:225], v[64:67]
	v_mfma_f32_16x16x32_bf16 v[64:67], v[156:159], v[226:229], v[64:67]
	v_mfma_f32_16x16x32_bf16 v[68:71], v[148:151], v[226:229], v[68:71]
	v_mfma_f32_16x16x32_bf16 v[68:71], v[144:147], v[222:225], v[68:71]
	v_mfma_f32_16x16x32_bf16 v[72:75], v[92:95], v[222:225], v[72:75]
	v_mfma_f32_16x16x32_bf16 v[72:75], v[96:99], v[226:229], v[72:75]
	s_setprio 3
	s_barrier
; #define PG8_STAGE(bufoff, gbase, voff) do { _Pragma("unroll") for (int _i = 0; _i < 2; ++_i) \
;         __builtin_amdgcn_global_load_lds((const unsigned*)((const char*)(gbase) + (voff)[_i]), (PG8_LAS unsigned*)(lds + (bufoff) + ldsw + _i * 8192), 16, 0, 0); } while (0)
; #define PG8_LDA(dst, b, h) do { _Pragma("unroll") for (int m = 0; m < 4; ++m) _Pragma("unroll") for (int k = 0; k < 2; ++k) dst[m][k] = *(const PG8_LAS bf16x8*)(lds + PG8_SA(b, h) + aoff + m * 2048 + k * 1024); } while (0)
; #define PG8_MMA(ai, bj, At, Bt) do { __builtin_amdgcn_s_setprio(1); _Pragma("unroll") for (int m = 0; m < 4; ++m) _Pragma("unroll") for (int n = 0; n < 2; ++n) _Pragma("unroll") for (int k = 0; k < 2; ++k) \
;         acc[ai][bj][m][n] = __builtin_amdgcn_mfma_f32_16x16x32_bf16(Bt[n][k], At[m][k], acc[ai][bj][m][n], 0, 0, 0); __builtin_amdgcn_s_setprio(0); } while (0)
; #define PG8_WAIT_V(n) asm volatile("s_waitcnt vmcnt(" #n ")" ::: "memory")
; #define PG8_WAIT_L(n) asm volatile("s_waitcnt lgkmcnt(" #n ")" ::: "memory")
; #define PG8_BAR __builtin_amdgcn_s_barrier()
; #define PG8_SCHED __builtin_amdgcn_sched_barrier(0)
; template <class Epi, class Sched, bool ALIGN_EPI = false, bool SP2 = false>
; __device__ __forceinline__ void gemm_phase(PG8_LAS unsigned char* lds, const Gemm g, const Sched& S, const Epi& E) {
;     ...
;             PG8_WAIT_V(8); PG8_WAIT_L(0); PG8_BAR; PG8_MMA(0, 0, At, B0); PG8_MMA(0, 1, At, B1); PG8_BAR; PG8_SCHED;
;             PG8_LDA(At, 1, 1); PG8_STAGE(PG8_SB(1, 0), b3, voffB); PG8_STAGE(PG8_SB(1, 1), b3 + hstep, voffB); PG8_STAGE(PG8_SA(1, 0), a3, voffA);
;             PG8_WAIT_V(8); PG8_WAIT_L(0); PG8_BAR; PG8_MMA(1, 0, At, B0); PG8_MMA(1, 1, At, B1); PG8_BAR; PG8_SCHED;
;     ...
;         if constexpr (ALIGN_EPI) { if (wr == 0) PG8_BAR; }
	v_mfma_f32_16x16x32_bf16 v[80:83], v[84:87], v[226:229], v[80:83]
	v_mfma_f32_16x16x32_bf16 v[80:83], v[76:79], v[222:225], v[80:83]
	s_setprio 0
	s_add_i32 s44, s44, s41
	v_lshl_add_u64 v[200:201], v[200:201], 0, s[20:21]
	s_mov_b32 m0, s44
	ds_read_b128 v[178:181], v187 offset:49152
	ds_read_b128 v[182:185], v187 offset:50176
	ds_read_b128 v[206:209], v187 offset:51200
	ds_read_b128 v[210:213], v187 offset:52224
	ds_read_b128 v[214:217], v187 offset:53248
	ds_read_b128 v[218:221], v187 offset:54272
	ds_read_b128 v[222:225], v187 offset:55296
	ds_read_b128 v[226:229], v187 offset:56320
	global_load_lds_dwordx4 v[200:201], off
	s_add_i32 m0, s44, 0x2000
	s_add_u32 s28, s28, 0x160080
	v_lshl_add_u64 v[200:201], v[230:231], 0, s[20:21]
	s_addc_u32 s29, s29, 0
	s_add_i32 s44, s45, s41
	global_load_lds_dwordx4 v[200:201], off
	v_lshl_add_u64 v[200:201], s[28:29], 0, v[160:161]
	s_mov_b32 m0, s44
	s_nop 0
	global_load_lds_dwordx4 v[200:201], off
	v_lshl_add_u64 v[200:201], s[28:29], 0, v[162:163]
	s_add_i32 m0, s44, 0x2000
	s_nop 0
	global_load_lds_dwordx4 v[200:201], off
	v_lshl_add_u64 v[200:201], v[232:233], 0, s[20:21]
	s_mov_b32 m0, s67
	s_nop 0
	global_load_lds_dwordx4 v[200:201], off
	v_lshl_add_u64 v[200:201], v[234:235], 0, s[20:21]
	s_mov_b32 m0, s68
	s_nop 0
	global_load_lds_dwordx4 v[200:201], off
	s_waitcnt vmcnt(8)
	s_waitcnt lgkmcnt(0)
	s_barrier
	s_setprio 1
	s_waitcnt lgkmcnt(0)
	v_mfma_f32_16x16x32_bf16 v[60:63], v[76:79], v[178:181], v[60:63]
	v_mfma_f32_16x16x32_bf16 v[60:63], v[84:87], v[182:185], v[60:63]
	v_mfma_f32_16x16x32_bf16 v[56:59], v[96:99], v[182:185], v[56:59]
	v_mfma_f32_16x16x32_bf16 v[56:59], v[92:95], v[178:181], v[56:59]
	v_mfma_f32_16x16x32_bf16 v[52:55], v[144:147], v[178:181], v[52:55]
	v_mfma_f32_16x16x32_bf16 v[52:55], v[148:151], v[182:185], v[52:55]
	v_mfma_f32_16x16x32_bf16 v[48:51], v[156:159], v[182:185], v[48:51]
	v_mfma_f32_16x16x32_bf16 v[48:51], v[152:155], v[178:181], v[48:51]
	v_mfma_f32_16x16x32_bf16 v[32:35], v[152:155], v[206:209], v[32:35]
	v_mfma_f32_16x16x32_bf16 v[32:35], v[156:159], v[210:213], v[32:35]
	v_mfma_f32_16x16x32_bf16 v[36:39], v[148:151], v[210:213], v[36:39]
	v_mfma_f32_16x16x32_bf16 v[36:39], v[144:147], v[206:209], v[36:39]
	v_mfma_f32_16x16x32_bf16 v[40:43], v[92:95], v[206:209], v[40:43]
	v_mfma_f32_16x16x32_bf16 v[40:43], v[96:99], v[210:213], v[40:43]
	v_mfma_f32_16x16x32_bf16 v[44:47], v[84:87], v[210:213], v[44:47]
	v_mfma_f32_16x16x32_bf16 v[44:47], v[76:79], v[206:209], v[44:47]
	s_setprio 0
	s_setprio 1
	v_mfma_f32_16x16x32_bf16 v[28:31], v[76:79], v[214:217], v[28:31]
	v_mfma_f32_16x16x32_bf16 v[28:31], v[84:87], v[218:221], v[28:31]
	v_mfma_f32_16x16x32_bf16 v[24:27], v[96:99], v[218:221], v[24:27]
	v_mfma_f32_16x16x32_bf16 v[24:27], v[92:95], v[214:217], v[24:27]
	v_mfma_f32_16x16x32_bf16 v[20:23], v[144:147], v[214:217], v[20:23]
	v_mfma_f32_16x16x32_bf16 v[20:23], v[148:151], v[218:221], v[20:23]
	v_mfma_f32_16x16x32_bf16 v[16:19], v[156:159], v[218:221], v[16:19]
	v_mfma_f32_16x16x32_bf16 v[16:19], v[152:155], v[214:217], v[16:19]
	v_mfma_f32_16x16x32_bf16 v[0:3], v[152:155], v[222:225], v[0:3]
	v_mfma_f32_16x16x32_bf16 v[0:3], v[156:159], v[226:229], v[0:3]
	v_mfma_f32_16x16x32_bf16 v[4:7], v[148:151], v[226:229], v[4:7]
	v_mfma_f32_16x16x32_bf16 v[4:7], v[144:147], v[222:225], v[4:7]
	v_mfma_f32_16x16x32_bf16 v[8:11], v[92:95], v[222:225], v[8:11]
	v_mfma_f32_16x16x32_bf16 v[8:11], v[96:99], v[226:229], v[8:11]
	s_setprio 3
	s_barrier
	v_mfma_f32_16x16x32_bf16 v[12:15], v[84:87], v[226:229], v[12:15]
	v_mfma_f32_16x16x32_bf16 v[12:15], v[76:79], v[222:225], v[12:15]
	s_setprio 0
	s_add_i32 s77, s77, 2
	s_add_u32 s64, s64, 0x100
	s_addc_u32 s65, s65, 0
	s_add_u32 s34, s34, 0x100
	s_addc_u32 s35, s35, 0
	s_cmpk_gt_u32 s77, 0x55
	s_cbranch_scc0 .LBB0_482
	s_and_b64 vcc, exec, s[22:23]
	s_cbranch_vccz .LBB0_485
	s_barrier

; #define PG8_STAGE(bufoff, gbase, voff) do { _Pragma("unroll") for (int _i = 0; _i < 2; ++_i) \
;         __builtin_amdgcn_global_load_lds((const unsigned*)((const char*)(gbase) + (voff)[_i]), (PG8_LAS unsigned*)(lds + (bufoff) + ldsw + _i * 8192), 16, 0, 0); } while (0)
; #define PG8_LDA(dst, b, h) do { _Pragma("unroll") for (int m = 0; m < 4; ++m) _Pragma("unroll") for (int k = 0; k < 2; ++k) dst[m][k] = *(const PG8_LAS bf16x8*)(lds + PG8_SA(b, h) + aoff + m * 2048 + k * 1024); } while (0)
; #define PG8_LDB(dst, b, h) do { _Pragma("unroll") for (int n = 0; n < 2; ++n) _Pragma("unroll") for (int k = 0; k < 2; ++k) dst[n][k] = *(const PG8_LAS bf16x8*)(lds + PG8_SB(b, h) + boff + n * 2048 + k * 1024); } while (0)
; #define PG8_MMA(ai, bj, At, Bt) do { __builtin_amdgcn_s_setprio(1); _Pragma("unroll") for (int m = 0; m < 4; ++m) _Pragma("unroll") for (int n = 0; n < 2; ++n) _Pragma("unroll") for (int k = 0; k < 2; ++k) \
;         acc[ai][bj][m][n] = __builtin_amdgcn_mfma_f32_16x16x32_bf16(Bt[n][k], At[m][k], acc[ai][bj][m][n], 0, 0, 0); __builtin_amdgcn_s_setprio(0); } while (0)
; #define PG8_WAIT_V(n) asm volatile("s_waitcnt vmcnt(" #n ")" ::: "memory")
; #define PG8_WAIT_L(n) asm volatile("s_waitcnt lgkmcnt(" #n ")" ::: "memory")
; template <class Epi, class Sched, bool ALIGN_EPI = false, bool SP2 = false>
; __device__ __forceinline__ void gemm_phase(PG8_LAS unsigned char* lds, const Gemm g, const Sched& S, const Epi& E) {
;     ...
;             const bool last = (t == nt - 2);
;             const char* a1 = cA + (size_t)(t + 1) * kstep;
;             const char* a2 = last ? nA : cA + (size_t)(t + 2) * kstep; const char* b2 = last ? nB : cB + (size_t)(t + 2) * kstep;
;             const char* a3 = a2 + kstep; const char* b3 = b2 + kstep;
;             if (last && has_next) S.a_ready(nxt);
;             if constexpr (SP2) {
;             PG8_LDB(B0, 0, 0); PG8_LDB(B1, 0, 1); PG8_SCHED; PG8_LDA(At, 0, 0); PG8_STAGE(PG8_SA(1, 1), a1 + hstep, voffA);
;             PG8_WAIT_V(8); PG8_WAIT_L(0); PG8_BAR; PG8_MMA(0, 0, At, B0); PG8_MMA(0, 1, At, B1); PG8_BAR; PG8_SCHED;
;             PG8_LDA(At, 0, 1); PG8_STAGE(PG8_SB(0, 0), b2, voffB); PG8_STAGE(PG8_SB(0, 1), b2 + hstep, voffB); PG8_STAGE(PG8_SA(0, 0), a2, voffA);
;             PG8_WAIT_V(8); PG8_WAIT_L(0); PG8_BAR; PG8_MMA(1, 0, At, B0); PG8_MMA(1, 1, At, B1); PG8_BAR; PG8_SCHED;
.LBB0_536:
	ds_read_b128 v[136:139], v156
	ds_read_b128 v[140:143], v156 offset:1024
	ds_read_b128 v[172:175], v156 offset:2048
	ds_read_b128 v[176:179], v156 offset:3072
	ds_read_b128 v[180:183], v157
	ds_read_b128 v[184:187], v157 offset:1024
	ds_read_b128 v[206:209], v157 offset:2048
	ds_read_b128 v[210:213], v157 offset:3072
	s_add_u32 s28, s66, 0xfff80080
	s_addc_u32 s29, s67, -1
	s_cmp_eq_u32 s79, 28
	s_cselect_b32 s49, s34, s29
	s_cselect_b32 s48, s35, s28
	s_cselect_b32 s29, s23, s78
	s_cselect_b32 s28, s39, s77
	v_lshl_add_u64 v[200:201], s[66:67], 0, v[128:129]
	s_add_i32 m0, s11, 0xc000
	ds_read_b128 v[214:217], v158
	ds_read_b128 v[218:221], v158 offset:1024
	ds_read_b128 v[222:225], v158 offset:2048
	ds_read_b128 v[226:229], v158 offset:3072
	ds_read_b128 v[230:233], v158 offset:4096
	ds_read_b128 v[234:237], v158 offset:5120
	ds_read_b128 v[238:241], v158 offset:6144
	ds_read_b128 v[242:245], v158 offset:7168
	global_load_lds_dwordx4 v[200:201], off
	v_lshl_add_u64 v[200:201], s[66:67], 0, v[130:131]
	s_add_i32 m0, s11, 0xe000
	s_nop 0
	global_load_lds_dwordx4 v[200:201], off
	s_waitcnt vmcnt(8)
	s_waitcnt lgkmcnt(0)
	s_barrier
	s_setprio 1
	s_waitcnt lgkmcnt(0)
	v_mfma_f32_16x16x32_bf16 v[124:127], v[136:139], v[214:217], v[124:127]
	v_mfma_f32_16x16x32_bf16 v[124:127], v[140:143], v[218:221], v[124:127]
	v_mfma_f32_16x16x32_bf16 v[120:123], v[176:179], v[218:221], v[120:123]
	v_mfma_f32_16x16x32_bf16 v[120:123], v[172:175], v[214:217], v[120:123]
	v_mfma_f32_16x16x32_bf16 v[116:119], v[180:183], v[214:217], v[116:119]
	v_mfma_f32_16x16x32_bf16 v[116:119], v[184:187], v[218:221], v[116:119]
	v_mfma_f32_16x16x32_bf16 v[112:115], v[210:213], v[218:221], v[112:115]
	v_mfma_f32_16x16x32_bf16 v[112:115], v[206:209], v[214:217], v[112:115]
	v_mfma_f32_16x16x32_bf16 v[92:95], v[206:209], v[222:225], v[92:95]
	v_mfma_f32_16x16x32_bf16 v[92:95], v[210:213], v[226:229], v[92:95]
	v_mfma_f32_16x16x32_bf16 v[100:103], v[184:187], v[226:229], v[100:103]
	v_mfma_f32_16x16x32_bf16 v[100:103], v[180:183], v[222:225], v[100:103]
	v_mfma_f32_16x16x32_bf16 v[104:107], v[172:175], v[222:225], v[104:107]
	v_mfma_f32_16x16x32_bf16 v[104:107], v[176:179], v[226:229], v[104:107]
	v_mfma_f32_16x16x32_bf16 v[108:111], v[140:143], v[226:229], v[108:111]
	v_mfma_f32_16x16x32_bf16 v[108:111], v[136:139], v[222:225], v[108:111]
	s_setprio 0
	s_setprio 1
	v_mfma_f32_16x16x32_bf16 v[96:99], v[136:139], v[230:233], v[96:99]
	v_mfma_f32_16x16x32_bf16 v[96:99], v[140:143], v[234:237], v[96:99]
	v_mfma_f32_16x16x32_bf16 v[88:91], v[176:179], v[234:237], v[88:91]
	v_mfma_f32_16x16x32_bf16 v[88:91], v[172:175], v[230:233], v[88:91]
	v_mfma_f32_16x16x32_bf16 v[84:87], v[180:183], v[230:233], v[84:87]
	v_mfma_f32_16x16x32_bf16 v[84:87], v[184:187], v[234:237], v[84:87]
	v_mfma_f32_16x16x32_bf16 v[76:79], v[210:213], v[234:237], v[76:79]
	v_mfma_f32_16x16x32_bf16 v[76:79], v[206:209], v[230:233], v[76:79]
	v_mfma_f32_16x16x32_bf16 v[64:67], v[206:209], v[238:241], v[64:67]
	v_mfma_f32_16x16x32_bf16 v[64:67], v[210:213], v[242:245], v[64:67]
	v_mfma_f32_16x16x32_bf16 v[68:71], v[184:187], v[242:245], v[68:71]
	v_mfma_f32_16x16x32_bf16 v[68:71], v[180:183], v[238:241], v[68:71]
	v_mfma_f32_16x16x32_bf16 v[72:75], v[172:175], v[238:241], v[72:75]
	v_mfma_f32_16x16x32_bf16 v[72:75], v[176:179], v[242:245], v[72:75]
	s_setprio 3
	s_barrier
	v_mfma_f32_16x16x32_bf16 v[80:83], v[140:143], v[242:245], v[80:83]
	v_mfma_f32_16x16x32_bf16 v[80:83], v[136:139], v[238:241], v[80:83]
	s_setprio 0
	s_add_i32 s44, s72, s41
	v_lshl_add_u64 v[200:201], s[28:29], 0, v[166:167]
	s_mov_b32 m0, s44
	ds_read_b128 v[214:217], v158 offset:16384
	ds_read_b128 v[218:221], v158 offset:17408
	ds_read_b128 v[222:225], v158 offset:18432
	ds_read_b128 v[226:229], v158 offset:19456
	ds_read_b128 v[230:233], v158 offset:20480
	ds_read_b128 v[234:237], v158 offset:21504
	ds_read_b128 v[238:241], v158 offset:22528
	ds_read_b128 v[242:245], v158 offset:23552
	global_load_lds_dwordx4 v[200:201], off
	s_add_i32 m0, s44, 0x2000
	s_add_u32 s80, s28, 0x80000
	v_lshl_add_u64 v[246:247], s[28:29], 0, v[170:171]
	s_addc_u32 s81, s29, 0
	s_add_i32 s44, s73, s41
	global_load_lds_dwordx4 v[246:247], off
	v_lshl_add_u64 v[248:249], s[80:81], 0, v[166:167]
	s_mov_b32 m0, s44
	v_lshl_add_u64 v[250:251], s[48:49], 0, v[168:169]
	global_load_lds_dwordx4 v[248:249], off
	v_lshl_add_u64 v[248:249], s[80:81], 0, v[170:171]
	s_add_i32 m0, s44, 0x2000
	s_nop 0
	global_load_lds_dwordx4 v[248:249], off
	v_lshl_add_u64 v[248:249], s[48:49], 0, v[164:165]
	s_mov_b32 m0, s11
	s_nop 0
	global_load_lds_dwordx4 v[248:249], off
	s_mov_b32 m0, s57
	s_nop 0
	global_load_lds_dwordx4 v[250:251], off
	s_waitcnt vmcnt(8)
	s_waitcnt lgkmcnt(0)
	s_barrier
; #define PG8_STAGE(bufoff, gbase, voff) do { _Pragma("unroll") for (int _i = 0; _i < 2; ++_i) \
;         __builtin_amdgcn_global_load_lds((const unsigned*)((const char*)(gbase) + (voff)[_i]), (PG8_LAS unsigned*)(lds + (bufoff) + ldsw + _i * 8192), 16, 0, 0); } while (0)
; #define PG8_LDA(dst, b, h) do { _Pragma("unroll") for (int m = 0; m < 4; ++m) _Pragma("unroll") for (int k = 0; k < 2; ++k) dst[m][k] = *(const PG8_LAS bf16x8*)(lds + PG8_SA(b, h) + aoff + m * 2048 + k * 1024); } while (0)
; #define PG8_LDB(dst, b, h) do { _Pragma("unroll") for (int n = 0; n < 2; ++n) _Pragma("unroll") for (int k = 0; k < 2; ++k) dst[n][k] = *(const PG8_LAS bf16x8*)(lds + PG8_SB(b, h) + boff + n * 2048 + k * 1024); } while (0)
; #define PG8_MMA(ai, bj, At, Bt) do { __builtin_amdgcn_s_setprio(1); _Pragma("unroll") for (int m = 0; m < 4; ++m) _Pragma("unroll") for (int n = 0; n < 2; ++n) _Pragma("unroll") for (int k = 0; k < 2; ++k) \
;         acc[ai][bj][m][n] = __builtin_amdgcn_mfma_f32_16x16x32_bf16(Bt[n][k], At[m][k], acc[ai][bj][m][n], 0, 0, 0); __builtin_amdgcn_s_setprio(0); } while (0)
; #define PG8_WAIT_V(n) asm volatile("s_waitcnt vmcnt(" #n ")" ::: "memory")
; #define PG8_WAIT_L(n) asm volatile("s_waitcnt lgkmcnt(" #n ")" ::: "memory")
; #define PG8_BAR __builtin_amdgcn_s_barrier()
; #define PG8_SCHED __builtin_amdgcn_sched_barrier(0)
; template <class Epi, class Sched, bool ALIGN_EPI = false, bool SP2 = false>
; __device__ __forceinline__ void gemm_phase(PG8_LAS unsigned char* lds, const Gemm g, const Sched& S, const Epi& E) {
;     ...
;             PG8_WAIT_V(8); PG8_WAIT_L(0); PG8_BAR; PG8_MMA(1, 0, At, B0); PG8_MMA(1, 1, At, B1); PG8_BAR; PG8_SCHED;
;             PG8_LDB(B0, 1, 0); PG8_LDB(B1, 1, 1); PG8_SCHED; PG8_LDA(At, 1, 0); PG8_STAGE(PG8_SA(0, 1), a2 + hstep, voffA);
;             PG8_WAIT_V(8); PG8_WAIT_L(0); PG8_BAR; PG8_MMA(0, 0, At, B0); PG8_MMA(0, 1, At, B1); PG8_BAR; PG8_SCHED;
	s_setprio 1
	s_waitcnt lgkmcnt(0)
	v_mfma_f32_16x16x32_bf16 v[60:63], v[136:139], v[214:217], v[60:63]
	v_mfma_f32_16x16x32_bf16 v[60:63], v[140:143], v[218:221], v[60:63]
	v_mfma_f32_16x16x32_bf16 v[56:59], v[176:179], v[218:221], v[56:59]
	v_mfma_f32_16x16x32_bf16 v[56:59], v[172:175], v[214:217], v[56:59]
	v_mfma_f32_16x16x32_bf16 v[52:55], v[180:183], v[214:217], v[52:55]
	v_mfma_f32_16x16x32_bf16 v[52:55], v[184:187], v[218:221], v[52:55]
	v_mfma_f32_16x16x32_bf16 v[44:47], v[210:213], v[218:221], v[44:47]
	v_mfma_f32_16x16x32_bf16 v[44:47], v[206:209], v[214:217], v[44:47]
	v_mfma_f32_16x16x32_bf16 v[28:31], v[206:209], v[222:225], v[28:31]
	v_mfma_f32_16x16x32_bf16 v[28:31], v[210:213], v[226:229], v[28:31]
	v_mfma_f32_16x16x32_bf16 v[36:39], v[184:187], v[226:229], v[36:39]
	v_mfma_f32_16x16x32_bf16 v[36:39], v[180:183], v[222:225], v[36:39]
	v_mfma_f32_16x16x32_bf16 v[40:43], v[172:175], v[222:225], v[40:43]
	v_mfma_f32_16x16x32_bf16 v[40:43], v[176:179], v[226:229], v[40:43]
	v_mfma_f32_16x16x32_bf16 v[48:51], v[140:143], v[226:229], v[48:51]
	v_mfma_f32_16x16x32_bf16 v[48:51], v[136:139], v[222:225], v[48:51]
	s_setprio 0
	s_setprio 1
	v_mfma_f32_16x16x32_bf16 v[32:35], v[136:139], v[230:233], v[32:35]
	v_mfma_f32_16x16x32_bf16 v[32:35], v[140:143], v[234:237], v[32:35]
	v_mfma_f32_16x16x32_bf16 v[24:27], v[176:179], v[234:237], v[24:27]
	v_mfma_f32_16x16x32_bf16 v[24:27], v[172:175], v[230:233], v[24:27]
	v_mfma_f32_16x16x32_bf16 v[20:23], v[180:183], v[230:233], v[20:23]
	v_mfma_f32_16x16x32_bf16 v[20:23], v[184:187], v[234:237], v[20:23]
	v_mfma_f32_16x16x32_bf16 v[16:19], v[210:213], v[234:237], v[16:19]
	v_mfma_f32_16x16x32_bf16 v[16:19], v[206:209], v[230:233], v[16:19]
	v_mfma_f32_16x16x32_bf16 v[0:3], v[206:209], v[238:241], v[0:3]
	v_mfma_f32_16x16x32_bf16 v[0:3], v[210:213], v[242:245], v[0:3]
	v_mfma_f32_16x16x32_bf16 v[4:7], v[184:187], v[242:245], v[4:7]
	v_mfma_f32_16x16x32_bf16 v[4:7], v[180:183], v[238:241], v[4:7]
	v_mfma_f32_16x16x32_bf16 v[8:11], v[172:175], v[238:241], v[8:11]
	v_mfma_f32_16x16x32_bf16 v[8:11], v[176:179], v[242:245], v[8:11]
	s_setprio 3
	s_barrier
	v_mfma_f32_16x16x32_bf16 v[12:15], v[140:143], v[242:245], v[12:15]
	v_mfma_f32_16x16x32_bf16 v[12:15], v[136:139], v[238:241], v[12:15]
	s_setprio 0
	s_add_i32 s44, 0, 0x18000
	v_add_u32_e32 v144, s44, v146
	s_add_i32 s45, 0, 0x1c000
	ds_read_b128 v[136:139], v144
	ds_read_b128 v[140:143], v144 offset:1024
	ds_read_b128 v[172:175], v144 offset:2048
	ds_read_b128 v[176:179], v144 offset:3072
	v_add_u32_e32 v144, s45, v146
	ds_read_b128 v[180:183], v144
	ds_read_b128 v[184:187], v144 offset:1024
	ds_read_b128 v[206:209], v144 offset:2048
	ds_read_b128 v[210:213], v144 offset:3072
	s_add_u32 s48, s48, 0x80000
	s_addc_u32 s49, s49, 0
	s_mov_b32 m0, s61
	v_lshl_add_u64 v[252:253], s[48:49], 0, v[164:165]
	ds_read_b128 v[214:217], v158 offset:32768
	ds_read_b128 v[218:221], v158 offset:33792
	ds_read_b128 v[222:225], v158 offset:34816
	ds_read_b128 v[226:229], v158 offset:35840
	ds_read_b128 v[230:233], v158 offset:36864
	ds_read_b128 v[234:237], v158 offset:37888
	ds_read_b128 v[238:241], v158 offset:38912
	ds_read_b128 v[242:245], v158 offset:39936
	global_load_lds_dwordx4 v[252:253], off
	v_lshl_add_u64 v[252:253], s[48:49], 0, v[168:169]
	s_mov_b32 m0, s68
	s_nop 0
	global_load_lds_dwordx4 v[252:253], off
	s_waitcnt vmcnt(8)
	s_waitcnt lgkmcnt(0)
	s_barrier
	s_setprio 1
	s_waitcnt lgkmcnt(0)
	v_mfma_f32_16x16x32_bf16 v[124:127], v[136:139], v[214:217], v[124:127]
	v_mfma_f32_16x16x32_bf16 v[124:127], v[140:143], v[218:221], v[124:127]
	v_mfma_f32_16x16x32_bf16 v[120:123], v[176:179], v[218:221], v[120:123]
	v_mfma_f32_16x16x32_bf16 v[120:123], v[172:175], v[214:217], v[120:123]
	v_mfma_f32_16x16x32_bf16 v[116:119], v[180:183], v[214:217], v[116:119]
	v_mfma_f32_16x16x32_bf16 v[116:119], v[184:187], v[218:221], v[116:119]
	v_mfma_f32_16x16x32_bf16 v[112:115], v[210:213], v[218:221], v[112:115]
	v_mfma_f32_16x16x32_bf16 v[112:115], v[206:209], v[214:217], v[112:115]
	v_mfma_f32_16x16x32_bf16 v[92:95], v[206:209], v[222:225], v[92:95]
	v_mfma_f32_16x16x32_bf16 v[92:95], v[210:213], v[226:229], v[92:95]
	v_mfma_f32_16x16x32_bf16 v[100:103], v[184:187], v[226:229], v[100:103]
	v_mfma_f32_16x16x32_bf16 v[100:103], v[180:183], v[222:225], v[100:103]
	v_mfma_f32_16x16x32_bf16 v[104:107], v[172:175], v[222:225], v[104:107]
	v_mfma_f32_16x16x32_bf16 v[104:107], v[176:179], v[226:229], v[104:107]
	v_mfma_f32_16x16x32_bf16 v[108:111], v[140:143], v[226:229], v[108:111]
	v_mfma_f32_16x16x32_bf16 v[108:111], v[136:139], v[222:225], v[108:111]
	s_setprio 0
	s_setprio 1
	v_mfma_f32_16x16x32_bf16 v[96:99], v[136:139], v[230:233], v[96:99]
	v_mfma_f32_16x16x32_bf16 v[96:99], v[140:143], v[234:237], v[96:99]
	v_mfma_f32_16x16x32_bf16 v[88:91], v[176:179], v[234:237], v[88:91]
	v_mfma_f32_16x16x32_bf16 v[88:91], v[172:175], v[230:233], v[88:91]
	v_mfma_f32_16x16x32_bf16 v[84:87], v[180:183], v[230:233], v[84:87]
	v_mfma_f32_16x16x32_bf16 v[84:87], v[184:187], v[234:237], v[84:87]
	v_mfma_f32_16x16x32_bf16 v[76:79], v[210:213], v[234:237], v[76:79]
	v_mfma_f32_16x16x32_bf16 v[76:79], v[206:209], v[230:233], v[76:79]
	v_mfma_f32_16x16x32_bf16 v[64:67], v[206:209], v[238:241], v[64:67]
	v_mfma_f32_16x16x32_bf16 v[64:67], v[210:213], v[242:245], v[64:67]
	v_mfma_f32_16x16x32_bf16 v[68:71], v[184:187], v[242:245], v[68:71]
	v_mfma_f32_16x16x32_bf16 v[68:71], v[180:183], v[238:241], v[68:71]
	v_mfma_f32_16x16x32_bf16 v[72:75], v[172:175], v[238:241], v[72:75]
	v_mfma_f32_16x16x32_bf16 v[72:75], v[176:179], v[242:245], v[72:75]
	s_setprio 3
	s_barrier
; #define PG8_STAGE(bufoff, gbase, voff) do { _Pragma("unroll") for (int _i = 0; _i < 2; ++_i) \
;         __builtin_amdgcn_global_load_lds((const unsigned*)((const char*)(gbase) + (voff)[_i]), (PG8_LAS unsigned*)(lds + (bufoff) + ldsw + _i * 8192), 16, 0, 0); } while (0)
; #define PG8_LDA(dst, b, h) do { _Pragma("unroll") for (int m = 0; m < 4; ++m) _Pragma("unroll") for (int k = 0; k < 2; ++k) dst[m][k] = *(const PG8_LAS bf16x8*)(lds + PG8_SA(b, h) + aoff + m * 2048 + k * 1024); } while (0)
; #define PG8_MMA(ai, bj, At, Bt) do { __builtin_amdgcn_s_setprio(1); _Pragma("unroll") for (int m = 0; m < 4; ++m) _Pragma("unroll") for (int n = 0; n < 2; ++n) _Pragma("unroll") for (int k = 0; k < 2; ++k) \
;         acc[ai][bj][m][n] = __builtin_amdgcn_mfma_f32_16x16x32_bf16(Bt[n][k], At[m][k], acc[ai][bj][m][n], 0, 0, 0); __builtin_amdgcn_s_setprio(0); } while (0)
; #define PG8_WAIT_V(n) asm volatile("s_waitcnt vmcnt(" #n ")" ::: "memory")
; #define PG8_WAIT_L(n) asm volatile("s_waitcnt lgkmcnt(" #n ")" ::: "memory")
; #define PG8_BAR __builtin_amdgcn_s_barrier()
; #define PG8_SCHED __builtin_amdgcn_sched_barrier(0)
; template <class Epi, class Sched, bool ALIGN_EPI = false, bool SP2 = false>
; __device__ __forceinline__ void gemm_phase(PG8_LAS unsigned char* lds, const Gemm g, const Sched& S, const Epi& E) {
;     ...
;             PG8_WAIT_V(8); PG8_WAIT_L(0); PG8_BAR; PG8_MMA(0, 0, At, B0); PG8_MMA(0, 1, At, B1); PG8_BAR; PG8_SCHED;
;             PG8_LDA(At, 1, 1); PG8_STAGE(PG8_SB(1, 0), b3, voffB); PG8_STAGE(PG8_SB(1, 1), b3 + hstep, voffB); PG8_STAGE(PG8_SA(1, 0), a3, voffA);
;             PG8_WAIT_V(8); PG8_WAIT_L(0); PG8_BAR; PG8_MMA(1, 0, At, B0); PG8_MMA(1, 1, At, B1); PG8_BAR; PG8_SCHED;
;     ...
;         if constexpr (ALIGN_EPI) { if (wr == 0) PG8_BAR; }
	v_mfma_f32_16x16x32_bf16 v[80:83], v[140:143], v[242:245], v[80:83]
	v_mfma_f32_16x16x32_bf16 v[80:83], v[136:139], v[238:241], v[80:83]
	s_setprio 0
	s_add_i32 s44, s44, s41
	v_lshl_add_u64 v[200:201], v[200:201], 0, s[18:19]
	s_mov_b32 m0, s44
	ds_read_b128 v[214:217], v158 offset:49152
	ds_read_b128 v[218:221], v158 offset:50176
	ds_read_b128 v[222:225], v158 offset:51200
	ds_read_b128 v[226:229], v158 offset:52224
	ds_read_b128 v[230:233], v158 offset:53248
	ds_read_b128 v[234:237], v158 offset:54272
	ds_read_b128 v[238:241], v158 offset:55296
	ds_read_b128 v[242:245], v158 offset:56320
	global_load_lds_dwordx4 v[200:201], off
	s_add_i32 m0, s44, 0x2000
	s_add_u32 s28, s28, 0x80080
	v_lshl_add_u64 v[200:201], v[246:247], 0, s[18:19]
	s_addc_u32 s29, s29, 0
	s_add_i32 s44, s45, s41
	global_load_lds_dwordx4 v[200:201], off
	v_lshl_add_u64 v[200:201], s[28:29], 0, v[166:167]
	s_mov_b32 m0, s44
	s_nop 0
	global_load_lds_dwordx4 v[200:201], off
	v_lshl_add_u64 v[200:201], s[28:29], 0, v[170:171]
	s_add_i32 m0, s44, 0x2000
	s_nop 0
	global_load_lds_dwordx4 v[200:201], off
	v_lshl_add_u64 v[200:201], v[248:249], 0, s[18:19]
	s_mov_b32 m0, s70
	s_nop 0
	global_load_lds_dwordx4 v[200:201], off
	v_lshl_add_u64 v[200:201], v[250:251], 0, s[18:19]
	s_mov_b32 m0, s71
	s_nop 0
	global_load_lds_dwordx4 v[200:201], off
	s_waitcnt vmcnt(8)
	s_waitcnt lgkmcnt(0)
	s_barrier
	s_setprio 1
	s_waitcnt lgkmcnt(0)
	v_mfma_f32_16x16x32_bf16 v[60:63], v[136:139], v[214:217], v[60:63]
	v_mfma_f32_16x16x32_bf16 v[60:63], v[140:143], v[218:221], v[60:63]
	v_mfma_f32_16x16x32_bf16 v[56:59], v[176:179], v[218:221], v[56:59]
	v_mfma_f32_16x16x32_bf16 v[56:59], v[172:175], v[214:217], v[56:59]
	v_mfma_f32_16x16x32_bf16 v[52:55], v[180:183], v[214:217], v[52:55]
	v_mfma_f32_16x16x32_bf16 v[52:55], v[184:187], v[218:221], v[52:55]
	v_mfma_f32_16x16x32_bf16 v[44:47], v[210:213], v[218:221], v[44:47]
	v_mfma_f32_16x16x32_bf16 v[44:47], v[206:209], v[214:217], v[44:47]
	v_mfma_f32_16x16x32_bf16 v[28:31], v[206:209], v[222:225], v[28:31]
	v_mfma_f32_16x16x32_bf16 v[28:31], v[210:213], v[226:229], v[28:31]
	v_mfma_f32_16x16x32_bf16 v[36:39], v[184:187], v[226:229], v[36:39]
	v_mfma_f32_16x16x32_bf16 v[36:39], v[180:183], v[222:225], v[36:39]
	v_mfma_f32_16x16x32_bf16 v[40:43], v[172:175], v[222:225], v[40:43]
	v_mfma_f32_16x16x32_bf16 v[40:43], v[176:179], v[226:229], v[40:43]
	v_mfma_f32_16x16x32_bf16 v[48:51], v[140:143], v[226:229], v[48:51]
	v_mfma_f32_16x16x32_bf16 v[48:51], v[136:139], v[222:225], v[48:51]
	s_setprio 0
	s_setprio 1
	v_mfma_f32_16x16x32_bf16 v[32:35], v[136:139], v[230:233], v[32:35]
	v_mfma_f32_16x16x32_bf16 v[32:35], v[140:143], v[234:237], v[32:35]
	v_mfma_f32_16x16x32_bf16 v[24:27], v[176:179], v[234:237], v[24:27]
	v_mfma_f32_16x16x32_bf16 v[24:27], v[172:175], v[230:233], v[24:27]
	v_mfma_f32_16x16x32_bf16 v[20:23], v[180:183], v[230:233], v[20:23]
	v_mfma_f32_16x16x32_bf16 v[20:23], v[184:187], v[234:237], v[20:23]
	v_mfma_f32_16x16x32_bf16 v[16:19], v[210:213], v[234:237], v[16:19]
	v_mfma_f32_16x16x32_bf16 v[16:19], v[206:209], v[230:233], v[16:19]
	v_mfma_f32_16x16x32_bf16 v[0:3], v[206:209], v[238:241], v[0:3]
	v_mfma_f32_16x16x32_bf16 v[0:3], v[210:213], v[242:245], v[0:3]
	v_mfma_f32_16x16x32_bf16 v[4:7], v[184:187], v[242:245], v[4:7]
	v_mfma_f32_16x16x32_bf16 v[4:7], v[180:183], v[238:241], v[4:7]
	v_mfma_f32_16x16x32_bf16 v[8:11], v[172:175], v[238:241], v[8:11]
	v_mfma_f32_16x16x32_bf16 v[8:11], v[176:179], v[242:245], v[8:11]
	s_setprio 3
	s_barrier
	v_mfma_f32_16x16x32_bf16 v[12:15], v[140:143], v[242:245], v[12:15]
	v_mfma_f32_16x16x32_bf16 v[12:15], v[136:139], v[238:241], v[12:15]
	s_setprio 0
	s_add_i32 s79, s79, 2
	s_add_u32 s66, s66, 0x100
	s_addc_u32 s67, s67, 0
	s_add_u32 s77, s77, 0x100
	s_addc_u32 s78, s78, 0
	s_cmp_gt_u32 s79, 29
	s_cbranch_scc0 .LBB0_536
	s_and_b64 vcc, exec, s[20:21]
	s_cbranch_vccz .LBB0_539
	s_barrier

; #define PG8_STAGE(bufoff, gbase, voff) do { _Pragma("unroll") for (int _i = 0; _i < 2; ++_i) \
;         __builtin_amdgcn_global_load_lds((const unsigned*)((const char*)(gbase) + (voff)[_i]), (PG8_LAS unsigned*)(lds + (bufoff) + ldsw + _i * 8192), 16, 0, 0); } while (0)
; #define PG8_LDA(dst, b, h) do { _Pragma("unroll") for (int m = 0; m < 4; ++m) _Pragma("unroll") for (int k = 0; k < 2; ++k) dst[m][k] = *(const PG8_LAS bf16x8*)(lds + PG8_SA(b, h) + aoff + m * 2048 + k * 1024); } while (0)
; #define PG8_LDB(dst, b, h) do { _Pragma("unroll") for (int n = 0; n < 2; ++n) _Pragma("unroll") for (int k = 0; k < 2; ++k) dst[n][k] = *(const PG8_LAS bf16x8*)(lds + PG8_SB(b, h) + boff + n * 2048 + k * 1024); } while (0)
; #define PG8_MMA(ai, bj, At, Bt) do { __builtin_amdgcn_s_setprio(1); _Pragma("unroll") for (int m = 0; m < 4; ++m) _Pragma("unroll") for (int n = 0; n < 2; ++n) _Pragma("unroll") for (int k = 0; k < 2; ++k) \
;         acc[ai][bj][m][n] = __builtin_amdgcn_mfma_f32_16x16x32_bf16(Bt[n][k], At[m][k], acc[ai][bj][m][n], 0, 0, 0); __builtin_amdgcn_s_setprio(0); } while (0)
; #define PG8_WAIT_V(n) asm volatile("s_waitcnt vmcnt(" #n ")" ::: "memory")
; #define PG8_WAIT_L(n) asm volatile("s_waitcnt lgkmcnt(" #n ")" ::: "memory")
; template <class Epi, class Sched, bool ALIGN_EPI = false, bool SP2 = false>
; __device__ __forceinline__ void gemm_phase(PG8_LAS unsigned char* lds, const Gemm g, const Sched& S, const Epi& E) {
;     ...
;             const bool last = (t == nt - 2);
;             const char* a1 = cA + (size_t)(t + 1) * kstep;
;             const char* a2 = last ? nA : cA + (size_t)(t + 2) * kstep; const char* b2 = last ? nB : cB + (size_t)(t + 2) * kstep;
;             const char* a3 = a2 + kstep; const char* b3 = b2 + kstep;
;             if (last && has_next) S.a_ready(nxt);
;             if constexpr (SP2) {
;             PG8_LDB(B0, 0, 0); PG8_LDB(B1, 0, 1); PG8_SCHED; PG8_LDA(At, 0, 0); PG8_STAGE(PG8_SA(1, 1), a1 + hstep, voffA);
;             PG8_WAIT_V(8); PG8_WAIT_L(0); PG8_BAR; PG8_MMA(0, 0, At, B0); PG8_MMA(0, 1, At, B1); PG8_BAR; PG8_SCHED;
;             PG8_LDA(At, 0, 1); PG8_STAGE(PG8_SB(0, 0), b2, voffB); PG8_STAGE(PG8_SB(0, 1), b2 + hstep, voffB); PG8_STAGE(PG8_SA(0, 0), a2, voffA);
;             PG8_WAIT_V(8); PG8_WAIT_L(0); PG8_BAR; PG8_MMA(1, 0, At, B0); PG8_MMA(1, 1, At, B1); PG8_BAR; PG8_SCHED;
.LBB0_602:
	ds_read_b128 v[76:79], v171
	ds_read_b128 v[84:87], v171 offset:1024
	ds_read_b128 v[92:95], v171 offset:2048
	ds_read_b128 v[96:99], v171 offset:3072
	ds_read_b128 v[144:147], v186
	ds_read_b128 v[148:151], v186 offset:1024
	ds_read_b128 v[152:155], v186 offset:2048
	ds_read_b128 v[156:159], v186 offset:3072
	s_add_u32 s28, s62, 0xffea0080
	s_addc_u32 s29, s63, -1
	s_cmpk_eq_i32 s77, 0x54
	s_cselect_b32 s49, s39, s29
	s_cselect_b32 s48, s38, s28
	s_cselect_b32 s29, s41, s35
	s_cselect_b32 s28, s40, s34
	v_lshl_add_u64 v[200:201], s[62:63], 0, v[172:173]
	s_add_i32 m0, s61, 0xc000
	ds_read_b128 v[178:181], v187
	ds_read_b128 v[182:185], v187 offset:1024
	ds_read_b128 v[206:209], v187 offset:2048
	ds_read_b128 v[210:213], v187 offset:3072
	ds_read_b128 v[214:217], v187 offset:4096
	ds_read_b128 v[218:221], v187 offset:5120
	ds_read_b128 v[222:225], v187 offset:6144
	ds_read_b128 v[226:229], v187 offset:7168
	global_load_lds_dwordx4 v[200:201], off
	v_lshl_add_u64 v[200:201], s[62:63], 0, v[174:175]
	s_add_i32 m0, s61, 0xe000
	s_nop 0
	global_load_lds_dwordx4 v[200:201], off
	s_waitcnt vmcnt(8)
	s_waitcnt lgkmcnt(0)
	s_barrier
	s_setprio 1
	s_waitcnt lgkmcnt(0)
	v_mfma_f32_16x16x32_bf16 v[140:143], v[76:79], v[178:181], v[140:143]
	v_mfma_f32_16x16x32_bf16 v[140:143], v[84:87], v[182:185], v[140:143]
	v_mfma_f32_16x16x32_bf16 v[136:139], v[96:99], v[182:185], v[136:139]
	v_mfma_f32_16x16x32_bf16 v[136:139], v[92:95], v[178:181], v[136:139]
	v_mfma_f32_16x16x32_bf16 v[132:135], v[144:147], v[178:181], v[132:135]
	v_mfma_f32_16x16x32_bf16 v[132:135], v[148:151], v[182:185], v[132:135]
	v_mfma_f32_16x16x32_bf16 v[128:131], v[156:159], v[182:185], v[128:131]
	v_mfma_f32_16x16x32_bf16 v[128:131], v[152:155], v[178:181], v[128:131]
	v_mfma_f32_16x16x32_bf16 v[112:115], v[152:155], v[206:209], v[112:115]
	v_mfma_f32_16x16x32_bf16 v[112:115], v[156:159], v[210:213], v[112:115]
	v_mfma_f32_16x16x32_bf16 v[116:119], v[148:151], v[210:213], v[116:119]
	v_mfma_f32_16x16x32_bf16 v[116:119], v[144:147], v[206:209], v[116:119]
	v_mfma_f32_16x16x32_bf16 v[120:123], v[92:95], v[206:209], v[120:123]
	v_mfma_f32_16x16x32_bf16 v[120:123], v[96:99], v[210:213], v[120:123]
	v_mfma_f32_16x16x32_bf16 v[124:127], v[84:87], v[210:213], v[124:127]
	v_mfma_f32_16x16x32_bf16 v[124:127], v[76:79], v[206:209], v[124:127]
	s_setprio 0
	s_setprio 1
	v_mfma_f32_16x16x32_bf16 v[108:111], v[76:79], v[214:217], v[108:111]
	v_mfma_f32_16x16x32_bf16 v[108:111], v[84:87], v[218:221], v[108:111]
	v_mfma_f32_16x16x32_bf16 v[104:107], v[96:99], v[218:221], v[104:107]
	v_mfma_f32_16x16x32_bf16 v[104:107], v[92:95], v[214:217], v[104:107]
	v_mfma_f32_16x16x32_bf16 v[100:103], v[144:147], v[214:217], v[100:103]
	v_mfma_f32_16x16x32_bf16 v[100:103], v[148:151], v[218:221], v[100:103]
	v_mfma_f32_16x16x32_bf16 v[88:91], v[156:159], v[218:221], v[88:91]
	v_mfma_f32_16x16x32_bf16 v[88:91], v[152:155], v[214:217], v[88:91]
	v_mfma_f32_16x16x32_bf16 v[64:67], v[152:155], v[222:225], v[64:67]
	v_mfma_f32_16x16x32_bf16 v[64:67], v[156:159], v[226:229], v[64:67]
	v_mfma_f32_16x16x32_bf16 v[68:71], v[148:151], v[226:229], v[68:71]
	v_mfma_f32_16x16x32_bf16 v[68:71], v[144:147], v[222:225], v[68:71]
	v_mfma_f32_16x16x32_bf16 v[72:75], v[92:95], v[222:225], v[72:75]
	v_mfma_f32_16x16x32_bf16 v[72:75], v[96:99], v[226:229], v[72:75]
	s_setprio 3
	s_barrier
	v_mfma_f32_16x16x32_bf16 v[80:83], v[84:87], v[226:229], v[80:83]
	v_mfma_f32_16x16x32_bf16 v[80:83], v[76:79], v[222:225], v[80:83]
	s_setprio 0
	s_add_i32 s44, s70, s57
	v_lshl_add_u64 v[200:201], s[28:29], 0, v[160:161]
	s_mov_b32 m0, s44
	ds_read_b128 v[178:181], v187 offset:16384
	ds_read_b128 v[182:185], v187 offset:17408
	ds_read_b128 v[206:209], v187 offset:18432
	ds_read_b128 v[210:213], v187 offset:19456
	ds_read_b128 v[214:217], v187 offset:20480
	ds_read_b128 v[218:221], v187 offset:21504
	ds_read_b128 v[222:225], v187 offset:22528
	ds_read_b128 v[226:229], v187 offset:23552
	global_load_lds_dwordx4 v[200:201], off
	s_add_i32 m0, s44, 0x2000
	s_add_u32 s78, s28, 0x160000
	v_lshl_add_u64 v[230:231], s[28:29], 0, v[162:163]
	s_addc_u32 s79, s29, 0
	s_add_i32 s44, s71, s57
	global_load_lds_dwordx4 v[230:231], off
	v_lshl_add_u64 v[232:233], s[78:79], 0, v[160:161]
	s_mov_b32 m0, s44
	v_lshl_add_u64 v[234:235], s[48:49], 0, v[162:163]
	global_load_lds_dwordx4 v[232:233], off
	v_lshl_add_u64 v[232:233], s[78:79], 0, v[162:163]
	s_add_i32 m0, s44, 0x2000
	s_nop 0
	global_load_lds_dwordx4 v[232:233], off
	v_lshl_add_u64 v[232:233], s[48:49], 0, v[160:161]
	s_mov_b32 m0, s61
	s_nop 0
	global_load_lds_dwordx4 v[232:233], off
	s_mov_b32 m0, s64
	s_nop 0
	global_load_lds_dwordx4 v[234:235], off
	s_waitcnt vmcnt(8)
	s_waitcnt lgkmcnt(0)
	s_barrier
; #define PG8_STAGE(bufoff, gbase, voff) do { _Pragma("unroll") for (int _i = 0; _i < 2; ++_i) \
;         __builtin_amdgcn_global_load_lds((const unsigned*)((const char*)(gbase) + (voff)[_i]), (PG8_LAS unsigned*)(lds + (bufoff) + ldsw + _i * 8192), 16, 0, 0); } while (0)
; #define PG8_LDA(dst, b, h) do { _Pragma("unroll") for (int m = 0; m < 4; ++m) _Pragma("unroll") for (int k = 0; k < 2; ++k) dst[m][k] = *(const PG8_LAS bf16x8*)(lds + PG8_SA(b, h) + aoff + m * 2048 + k * 1024); } while (0)
; #define PG8_LDB(dst, b, h) do { _Pragma("unroll") for (int n = 0; n < 2; ++n) _Pragma("unroll") for (int k = 0; k < 2; ++k) dst[n][k] = *(const PG8_LAS bf16x8*)(lds + PG8_SB(b, h) + boff + n * 2048 + k * 1024); } while (0)
; #define PG8_MMA(ai, bj, At, Bt) do { __builtin_amdgcn_s_setprio(1); _Pragma("unroll") for (int m = 0; m < 4; ++m) _Pragma("unroll") for (int n = 0; n < 2; ++n) _Pragma("unroll") for (int k = 0; k < 2; ++k) \
;         acc[ai][bj][m][n] = __builtin_amdgcn_mfma_f32_16x16x32_bf16(Bt[n][k], At[m][k], acc[ai][bj][m][n], 0, 0, 0); __builtin_amdgcn_s_setprio(0); } while (0)
; #define PG8_WAIT_V(n) asm volatile("s_waitcnt vmcnt(" #n ")" ::: "memory")
; #define PG8_WAIT_L(n) asm volatile("s_waitcnt lgkmcnt(" #n ")" ::: "memory")
; #define PG8_BAR __builtin_amdgcn_s_barrier()
; #define PG8_SCHED __builtin_amdgcn_sched_barrier(0)
; template <class Epi, class Sched, bool ALIGN_EPI = false, bool SP2 = false>
; __device__ __forceinline__ void gemm_phase(PG8_LAS unsigned char* lds, const Gemm g, const Sched& S, const Epi& E) {
;     ...
;             PG8_WAIT_V(8); PG8_WAIT_L(0); PG8_BAR; PG8_MMA(1, 0, At, B0); PG8_MMA(1, 1, At, B1); PG8_BAR; PG8_SCHED;
;             PG8_LDB(B0, 1, 0); PG8_LDB(B1, 1, 1); PG8_SCHED; PG8_LDA(At, 1, 0); PG8_STAGE(PG8_SA(0, 1), a2 + hstep, voffA);
;             PG8_WAIT_V(8); PG8_WAIT_L(0); PG8_BAR; PG8_MMA(0, 0, At, B0); PG8_MMA(0, 1, At, B1); PG8_BAR; PG8_SCHED;
	s_setprio 1
	s_waitcnt lgkmcnt(0)
	v_mfma_f32_16x16x32_bf16 v[60:63], v[76:79], v[178:181], v[60:63]
	v_mfma_f32_16x16x32_bf16 v[60:63], v[84:87], v[182:185], v[60:63]
	v_mfma_f32_16x16x32_bf16 v[56:59], v[96:99], v[182:185], v[56:59]
	v_mfma_f32_16x16x32_bf16 v[56:59], v[92:95], v[178:181], v[56:59]
	v_mfma_f32_16x16x32_bf16 v[52:55], v[144:147], v[178:181], v[52:55]
	v_mfma_f32_16x16x32_bf16 v[52:55], v[148:151], v[182:185], v[52:55]
	v_mfma_f32_16x16x32_bf16 v[48:51], v[156:159], v[182:185], v[48:51]
	v_mfma_f32_16x16x32_bf16 v[48:51], v[152:155], v[178:181], v[48:51]
	v_mfma_f32_16x16x32_bf16 v[32:35], v[152:155], v[206:209], v[32:35]
	v_mfma_f32_16x16x32_bf16 v[32:35], v[156:159], v[210:213], v[32:35]
	v_mfma_f32_16x16x32_bf16 v[36:39], v[148:151], v[210:213], v[36:39]
	v_mfma_f32_16x16x32_bf16 v[36:39], v[144:147], v[206:209], v[36:39]
	v_mfma_f32_16x16x32_bf16 v[40:43], v[92:95], v[206:209], v[40:43]
	v_mfma_f32_16x16x32_bf16 v[40:43], v[96:99], v[210:213], v[40:43]
	v_mfma_f32_16x16x32_bf16 v[44:47], v[84:87], v[210:213], v[44:47]
	v_mfma_f32_16x16x32_bf16 v[44:47], v[76:79], v[206:209], v[44:47]
	s_setprio 0
	s_setprio 1
	v_mfma_f32_16x16x32_bf16 v[28:31], v[76:79], v[214:217], v[28:31]
	v_mfma_f32_16x16x32_bf16 v[28:31], v[84:87], v[218:221], v[28:31]
	v_mfma_f32_16x16x32_bf16 v[24:27], v[96:99], v[218:221], v[24:27]
	v_mfma_f32_16x16x32_bf16 v[24:27], v[92:95], v[214:217], v[24:27]
	v_mfma_f32_16x16x32_bf16 v[20:23], v[144:147], v[214:217], v[20:23]
	v_mfma_f32_16x16x32_bf16 v[20:23], v[148:151], v[218:221], v[20:23]
	v_mfma_f32_16x16x32_bf16 v[16:19], v[156:159], v[218:221], v[16:19]
	v_mfma_f32_16x16x32_bf16 v[16:19], v[152:155], v[214:217], v[16:19]
	v_mfma_f32_16x16x32_bf16 v[0:3], v[152:155], v[222:225], v[0:3]
	v_mfma_f32_16x16x32_bf16 v[0:3], v[156:159], v[226:229], v[0:3]
	v_mfma_f32_16x16x32_bf16 v[4:7], v[148:151], v[226:229], v[4:7]
	v_mfma_f32_16x16x32_bf16 v[4:7], v[144:147], v[222:225], v[4:7]
	v_mfma_f32_16x16x32_bf16 v[8:11], v[92:95], v[222:225], v[8:11]
	v_mfma_f32_16x16x32_bf16 v[8:11], v[96:99], v[226:229], v[8:11]
	s_setprio 3
	s_barrier
	v_mfma_f32_16x16x32_bf16 v[12:15], v[84:87], v[226:229], v[12:15]
	v_mfma_f32_16x16x32_bf16 v[12:15], v[76:79], v[222:225], v[12:15]
	s_setprio 0
	s_add_i32 s44, 0, 0x18000
	s_add_i32 s45, 0, 0x1c000
	v_add_u32_e32 v96, s44, v167
	v_add_u32_e32 v156, s45, v167
	ds_read_b128 v[76:79], v96
	ds_read_b128 v[84:87], v96 offset:1024
	ds_read_b128 v[92:95], v96 offset:2048
	ds_read_b128 v[96:99], v96 offset:3072
	ds_read_b128 v[144:147], v156
	ds_read_b128 v[148:151], v156 offset:1024
	ds_read_b128 v[152:155], v156 offset:2048
	ds_read_b128 v[156:159], v156 offset:3072
	s_add_u32 s48, s48, 0x160000
	s_addc_u32 s49, s49, 0
	s_mov_b32 m0, s65
	v_lshl_add_u64 v[236:237], s[48:49], 0, v[160:161]
	ds_read_b128 v[178:181], v187 offset:32768
	ds_read_b128 v[182:185], v187 offset:33792
	ds_read_b128 v[206:209], v187 offset:34816
	ds_read_b128 v[210:213], v187 offset:35840
	ds_read_b128 v[214:217], v187 offset:36864
	ds_read_b128 v[218:221], v187 offset:37888
	ds_read_b128 v[222:225], v187 offset:38912
	ds_read_b128 v[226:229], v187 offset:39936
	global_load_lds_dwordx4 v[236:237], off
	v_lshl_add_u64 v[236:237], s[48:49], 0, v[162:163]
	s_mov_b32 m0, s66
	s_nop 0
	global_load_lds_dwordx4 v[236:237], off
	s_waitcnt vmcnt(8)
	s_waitcnt lgkmcnt(0)
	s_barrier
	s_setprio 1
	s_waitcnt lgkmcnt(0)
	v_mfma_f32_16x16x32_bf16 v[140:143], v[76:79], v[178:181], v[140:143]
	v_mfma_f32_16x16x32_bf16 v[140:143], v[84:87], v[182:185], v[140:143]
	v_mfma_f32_16x16x32_bf16 v[136:139], v[96:99], v[182:185], v[136:139]
	v_mfma_f32_16x16x32_bf16 v[136:139], v[92:95], v[178:181], v[136:139]
	v_mfma_f32_16x16x32_bf16 v[132:135], v[144:147], v[178:181], v[132:135]
	v_mfma_f32_16x16x32_bf16 v[132:135], v[148:151], v[182:185], v[132:135]
	v_mfma_f32_16x16x32_bf16 v[128:131], v[156:159], v[182:185], v[128:131]
	v_mfma_f32_16x16x32_bf16 v[128:131], v[152:155], v[178:181], v[128:131]
	v_mfma_f32_16x16x32_bf16 v[112:115], v[152:155], v[206:209], v[112:115]
	v_mfma_f32_16x16x32_bf16 v[112:115], v[156:159], v[210:213], v[112:115]
	v_mfma_f32_16x16x32_bf16 v[116:119], v[148:151], v[210:213], v[116:119]
	v_mfma_f32_16x16x32_bf16 v[116:119], v[144:147], v[206:209], v[116:119]
	v_mfma_f32_16x16x32_bf16 v[120:123], v[92:95], v[206:209], v[120:123]
	v_mfma_f32_16x16x32_bf16 v[120:123], v[96:99], v[210:213], v[120:123]
	v_mfma_f32_16x16x32_bf16 v[124:127], v[84:87], v[210:213], v[124:127]
	v_mfma_f32_16x16x32_bf16 v[124:127], v[76:79], v[206:209], v[124:127]
	s_setprio 0
	s_setprio 1
	v_mfma_f32_16x16x32_bf16 v[108:111], v[76:79], v[214:217], v[108:111]
	v_mfma_f32_16x16x32_bf16 v[108:111], v[84:87], v[218:221], v[108:111]
	v_mfma_f32_16x16x32_bf16 v[104:107], v[96:99], v[218:221], v[104:107]
	v_mfma_f32_16x16x32_bf16 v[104:107], v[92:95], v[214:217], v[104:107]
	v_mfma_f32_16x16x32_bf16 v[100:103], v[144:147], v[214:217], v[100:103]
	v_mfma_f32_16x16x32_bf16 v[100:103], v[148:151], v[218:221], v[100:103]
	v_mfma_f32_16x16x32_bf16 v[88:91], v[156:159], v[218:221], v[88:91]
	v_mfma_f32_16x16x32_bf16 v[88:91], v[152:155], v[214:217], v[88:91]
	v_mfma_f32_16x16x32_bf16 v[64:67], v[152:155], v[222:225], v[64:67]
	v_mfma_f32_16x16x32_bf16 v[64:67], v[156:159], v[226:229], v[64:67]
	v_mfma_f32_16x16x32_bf16 v[68:71], v[148:151], v[226:229], v[68:71]
	v_mfma_f32_16x16x32_bf16 v[68:71], v[144:147], v[222:225], v[68:71]
	v_mfma_f32_16x16x32_bf16 v[72:75], v[92:95], v[222:225], v[72:75]
	v_mfma_f32_16x16x32_bf16 v[72:75], v[96:99], v[226:229], v[72:75]
	s_setprio 3
	s_barrier
; #define PG8_STAGE(bufoff, gbase, voff) do { _Pragma("unroll") for (int _i = 0; _i < 2; ++_i) \
;         __builtin_amdgcn_global_load_lds((const unsigned*)((const char*)(gbase) + (voff)[_i]), (PG8_LAS unsigned*)(lds + (bufoff) + ldsw + _i * 8192), 16, 0, 0); } while (0)
; #define PG8_LDA(dst, b, h) do { _Pragma("unroll") for (int m = 0; m < 4; ++m) _Pragma("unroll") for (int k = 0; k < 2; ++k) dst[m][k] = *(const PG8_LAS bf16x8*)(lds + PG8_SA(b, h) + aoff + m * 2048 + k * 1024); } while (0)
; #define PG8_MMA(ai, bj, At, Bt) do { __builtin_amdgcn_s_setprio(1); _Pragma("unroll") for (int m = 0; m < 4; ++m) _Pragma("unroll") for (int n = 0; n < 2; ++n) _Pragma("unroll") for (int k = 0; k < 2; ++k) \
;         acc[ai][bj][m][n] = __builtin_amdgcn_mfma_f32_16x16x32_bf16(Bt[n][k], At[m][k], acc[ai][bj][m][n], 0, 0, 0); __builtin_amdgcn_s_setprio(0); } while (0)
; #define PG8_WAIT_V(n) asm volatile("s_waitcnt vmcnt(" #n ")" ::: "memory")
; #define PG8_WAIT_L(n) asm volatile("s_waitcnt lgkmcnt(" #n ")" ::: "memory")
; #define PG8_BAR __builtin_amdgcn_s_barrier()
; #define PG8_SCHED __builtin_amdgcn_sched_barrier(0)
; template <class Epi, class Sched, bool ALIGN_EPI = false, bool SP2 = false>
; __device__ __forceinline__ void gemm_phase(PG8_LAS unsigned char* lds, const Gemm g, const Sched& S, const Epi& E) {
;     ...
;             PG8_WAIT_V(8); PG8_WAIT_L(0); PG8_BAR; PG8_MMA(0, 0, At, B0); PG8_MMA(0, 1, At, B1); PG8_BAR; PG8_SCHED;
;             PG8_LDA(At, 1, 1); PG8_STAGE(PG8_SB(1, 0), b3, voffB); PG8_STAGE(PG8_SB(1, 1), b3 + hstep, voffB); PG8_STAGE(PG8_SA(1, 0), a3, voffA);
;             PG8_WAIT_V(8); PG8_WAIT_L(0); PG8_BAR; PG8_MMA(1, 0, At, B0); PG8_MMA(1, 1, At, B1); PG8_BAR; PG8_SCHED;
;     ...
;         if constexpr (ALIGN_EPI) { if (wr == 0) PG8_BAR; }
	v_mfma_f32_16x16x32_bf16 v[80:83], v[84:87], v[226:229], v[80:83]
	v_mfma_f32_16x16x32_bf16 v[80:83], v[76:79], v[222:225], v[80:83]
	s_setprio 0
	s_add_i32 s44, s44, s57
	v_lshl_add_u64 v[200:201], v[200:201], 0, s[20:21]
	s_mov_b32 m0, s44
	ds_read_b128 v[178:181], v187 offset:49152
	ds_read_b128 v[182:185], v187 offset:50176
	ds_read_b128 v[206:209], v187 offset:51200
	ds_read_b128 v[210:213], v187 offset:52224
	ds_read_b128 v[214:217], v187 offset:53248
	ds_read_b128 v[218:221], v187 offset:54272
	ds_read_b128 v[222:225], v187 offset:55296
	ds_read_b128 v[226:229], v187 offset:56320
	global_load_lds_dwordx4 v[200:201], off
	s_add_i32 m0, s44, 0x2000
	s_add_u32 s28, s28, 0x160080
	v_lshl_add_u64 v[200:201], v[230:231], 0, s[20:21]
	s_addc_u32 s29, s29, 0
	s_add_i32 s44, s45, s57
	global_load_lds_dwordx4 v[200:201], off
	v_lshl_add_u64 v[200:201], s[28:29], 0, v[160:161]
	s_mov_b32 m0, s44
	s_nop 0
	global_load_lds_dwordx4 v[200:201], off
	v_lshl_add_u64 v[200:201], s[28:29], 0, v[162:163]
	s_add_i32 m0, s44, 0x2000
	s_nop 0
	global_load_lds_dwordx4 v[200:201], off
	v_lshl_add_u64 v[200:201], v[232:233], 0, s[20:21]
	s_mov_b32 m0, s67
	s_nop 0
	global_load_lds_dwordx4 v[200:201], off
	v_lshl_add_u64 v[200:201], v[234:235], 0, s[20:21]
	s_mov_b32 m0, s68
	s_nop 0
	global_load_lds_dwordx4 v[200:201], off
	s_waitcnt vmcnt(8)
	s_waitcnt lgkmcnt(0)
	s_barrier
	s_setprio 1
	s_waitcnt lgkmcnt(0)
	v_mfma_f32_16x16x32_bf16 v[60:63], v[76:79], v[178:181], v[60:63]
	v_mfma_f32_16x16x32_bf16 v[60:63], v[84:87], v[182:185], v[60:63]
	v_mfma_f32_16x16x32_bf16 v[56:59], v[96:99], v[182:185], v[56:59]
	v_mfma_f32_16x16x32_bf16 v[56:59], v[92:95], v[178:181], v[56:59]
	v_mfma_f32_16x16x32_bf16 v[52:55], v[144:147], v[178:181], v[52:55]
	v_mfma_f32_16x16x32_bf16 v[52:55], v[148:151], v[182:185], v[52:55]
	v_mfma_f32_16x16x32_bf16 v[48:51], v[156:159], v[182:185], v[48:51]
	v_mfma_f32_16x16x32_bf16 v[48:51], v[152:155], v[178:181], v[48:51]
	v_mfma_f32_16x16x32_bf16 v[32:35], v[152:155], v[206:209], v[32:35]
	v_mfma_f32_16x16x32_bf16 v[32:35], v[156:159], v[210:213], v[32:35]
	v_mfma_f32_16x16x32_bf16 v[36:39], v[148:151], v[210:213], v[36:39]
	v_mfma_f32_16x16x32_bf16 v[36:39], v[144:147], v[206:209], v[36:39]
	v_mfma_f32_16x16x32_bf16 v[40:43], v[92:95], v[206:209], v[40:43]
	v_mfma_f32_16x16x32_bf16 v[40:43], v[96:99], v[210:213], v[40:43]
	v_mfma_f32_16x16x32_bf16 v[44:47], v[84:87], v[210:213], v[44:47]
	v_mfma_f32_16x16x32_bf16 v[44:47], v[76:79], v[206:209], v[44:47]
	s_setprio 0
	s_setprio 1
	v_mfma_f32_16x16x32_bf16 v[28:31], v[76:79], v[214:217], v[28:31]
	v_mfma_f32_16x16x32_bf16 v[28:31], v[84:87], v[218:221], v[28:31]
	v_mfma_f32_16x16x32_bf16 v[24:27], v[96:99], v[218:221], v[24:27]
	v_mfma_f32_16x16x32_bf16 v[24:27], v[92:95], v[214:217], v[24:27]
	v_mfma_f32_16x16x32_bf16 v[20:23], v[144:147], v[214:217], v[20:23]
	v_mfma_f32_16x16x32_bf16 v[20:23], v[148:151], v[218:221], v[20:23]
	v_mfma_f32_16x16x32_bf16 v[16:19], v[156:159], v[218:221], v[16:19]
	v_mfma_f32_16x16x32_bf16 v[16:19], v[152:155], v[214:217], v[16:19]
	v_mfma_f32_16x16x32_bf16 v[0:3], v[152:155], v[222:225], v[0:3]
	v_mfma_f32_16x16x32_bf16 v[0:3], v[156:159], v[226:229], v[0:3]
	v_mfma_f32_16x16x32_bf16 v[4:7], v[148:151], v[226:229], v[4:7]
	v_mfma_f32_16x16x32_bf16 v[4:7], v[144:147], v[222:225], v[4:7]
	v_mfma_f32_16x16x32_bf16 v[8:11], v[92:95], v[222:225], v[8:11]
	v_mfma_f32_16x16x32_bf16 v[8:11], v[96:99], v[226:229], v[8:11]
	s_setprio 3
	s_barrier
	v_mfma_f32_16x16x32_bf16 v[12:15], v[84:87], v[226:229], v[12:15]
	v_mfma_f32_16x16x32_bf16 v[12:15], v[76:79], v[222:225], v[12:15]
	s_setprio 0
	s_add_i32 s77, s77, 2
	s_add_u32 s62, s62, 0x100
	s_addc_u32 s63, s63, 0
	s_add_u32 s34, s34, 0x100
	s_addc_u32 s35, s35, 0
	s_cmpk_gt_u32 s77, 0x55
	s_cbranch_scc0 .LBB0_602
	s_and_b64 vcc, exec, s[22:23]
	s_cbranch_vccz .LBB0_605
	s_barrier

; #define PG8_STAGE(bufoff, gbase, voff) do { _Pragma("unroll") for (int _i = 0; _i < 2; ++_i) \
;         __builtin_amdgcn_global_load_lds((const unsigned*)((const char*)(gbase) + (voff)[_i]), (PG8_LAS unsigned*)(lds + (bufoff) + ldsw + _i * 8192), 16, 0, 0); } while (0)
; #define PG8_LDA(dst, b, h) do { _Pragma("unroll") for (int m = 0; m < 4; ++m) _Pragma("unroll") for (int k = 0; k < 2; ++k) dst[m][k] = *(const PG8_LAS bf16x8*)(lds + PG8_SA(b, h) + aoff + m * 2048 + k * 1024); } while (0)
; #define PG8_LDB(dst, b, h) do { _Pragma("unroll") for (int n = 0; n < 2; ++n) _Pragma("unroll") for (int k = 0; k < 2; ++k) dst[n][k] = *(const PG8_LAS bf16x8*)(lds + PG8_SB(b, h) + boff + n * 2048 + k * 1024); } while (0)
; #define PG8_MMA(ai, bj, At, Bt) do { __builtin_amdgcn_s_setprio(1); _Pragma("unroll") for (int m = 0; m < 4; ++m) _Pragma("unroll") for (int n = 0; n < 2; ++n) _Pragma("unroll") for (int k = 0; k < 2; ++k) \
;         acc[ai][bj][m][n] = __builtin_amdgcn_mfma_f32_16x16x32_bf16(Bt[n][k], At[m][k], acc[ai][bj][m][n], 0, 0, 0); __builtin_amdgcn_s_setprio(0); } while (0)
; #define PG8_WAIT_V(n) asm volatile("s_waitcnt vmcnt(" #n ")" ::: "memory")
; #define PG8_WAIT_L(n) asm volatile("s_waitcnt lgkmcnt(" #n ")" ::: "memory")
; template <class Epi, class Sched, bool ALIGN_EPI = false, bool SP2 = false>
; __device__ __forceinline__ void gemm_phase(PG8_LAS unsigned char* lds, const Gemm g, const Sched& S, const Epi& E) {
;     ...
;             const bool last = (t == nt - 2);
;             const char* a1 = cA + (size_t)(t + 1) * kstep;
;             const char* a2 = last ? nA : cA + (size_t)(t + 2) * kstep; const char* b2 = last ? nB : cB + (size_t)(t + 2) * kstep;
;             const char* a3 = a2 + kstep; const char* b3 = b2 + kstep;
;             if (last && has_next) S.a_ready(nxt);
;             if constexpr (SP2) {
;             PG8_LDB(B0, 0, 0); PG8_LDB(B1, 0, 1); PG8_SCHED; PG8_LDA(At, 0, 0); PG8_STAGE(PG8_SA(1, 1), a1 + hstep, voffA);
;             PG8_WAIT_V(8); PG8_WAIT_L(0); PG8_BAR; PG8_MMA(0, 0, At, B0); PG8_MMA(0, 1, At, B1); PG8_BAR; PG8_SCHED;
;             PG8_LDA(At, 0, 1); PG8_STAGE(PG8_SB(0, 0), b2, voffB); PG8_STAGE(PG8_SB(0, 1), b2 + hstep, voffB); PG8_STAGE(PG8_SA(0, 0), a2, voffA);
;             PG8_WAIT_V(8); PG8_WAIT_L(0); PG8_BAR; PG8_MMA(1, 0, At, B0); PG8_MMA(1, 1, At, B1); PG8_BAR; PG8_SCHED;
.LBB0_719:
	ds_read_b128 v[88:91], v208
	ds_read_b128 v[96:99], v208 offset:1024
	ds_read_b128 v[136:139], v208 offset:2048
	ds_read_b128 v[140:143], v208 offset:3072
	ds_read_b128 v[144:147], v209
	ds_read_b128 v[148:151], v209 offset:1024
	ds_read_b128 v[152:155], v209 offset:2048
	ds_read_b128 v[156:159], v209 offset:3072
	s_add_u32 s44, s62, 0xfff80080
	s_addc_u32 s45, s63, -1
	s_cmp_eq_u32 s76, 28
	s_cselect_b32 s59, s29, s45
	s_cselect_b32 s58, s34, s44
	s_cselect_b32 s57, s23, s75
	s_cselect_b32 s56, s35, s74
	v_lshl_add_u64 v[200:201], s[62:63], 0, v[172:173]
	s_add_i32 m0, s49, 0xc000
	ds_read_b128 v[178:181], v210
	ds_read_b128 v[182:185], v210 offset:1024
	ds_read_b128 v[186:189], v210 offset:2048
	ds_read_b128 v[212:215], v210 offset:3072
	ds_read_b128 v[216:219], v210 offset:4096
	ds_read_b128 v[220:223], v210 offset:5120
	ds_read_b128 v[224:227], v210 offset:6144
	ds_read_b128 v[228:231], v210 offset:7168
	global_load_lds_dwordx4 v[200:201], off
	v_lshl_add_u64 v[200:201], s[62:63], 0, v[174:175]
	s_add_i32 m0, s49, 0xe000
	s_nop 0
	global_load_lds_dwordx4 v[200:201], off
	s_waitcnt vmcnt(8)
	s_waitcnt lgkmcnt(0)
	s_barrier
	s_setprio 1
	s_waitcnt lgkmcnt(0)
	v_mfma_f32_16x16x32_bf16 v[128:131], v[88:91], v[178:181], v[128:131]
	v_mfma_f32_16x16x32_bf16 v[128:131], v[96:99], v[182:185], v[128:131]
	v_mfma_f32_16x16x32_bf16 v[120:123], v[140:143], v[182:185], v[120:123]
	v_mfma_f32_16x16x32_bf16 v[120:123], v[136:139], v[178:181], v[120:123]
	v_mfma_f32_16x16x32_bf16 v[132:135], v[144:147], v[178:181], v[132:135]
	v_mfma_f32_16x16x32_bf16 v[132:135], v[148:151], v[182:185], v[132:135]
	v_mfma_f32_16x16x32_bf16 v[124:127], v[156:159], v[182:185], v[124:127]
	v_mfma_f32_16x16x32_bf16 v[124:127], v[152:155], v[178:181], v[124:127]
	v_mfma_f32_16x16x32_bf16 v[104:107], v[152:155], v[186:189], v[104:107]
	v_mfma_f32_16x16x32_bf16 v[104:107], v[156:159], v[212:215], v[104:107]
	v_mfma_f32_16x16x32_bf16 v[112:115], v[148:151], v[212:215], v[112:115]
	v_mfma_f32_16x16x32_bf16 v[112:115], v[144:147], v[186:189], v[112:115]
	v_mfma_f32_16x16x32_bf16 v[108:111], v[136:139], v[186:189], v[108:111]
	v_mfma_f32_16x16x32_bf16 v[108:111], v[140:143], v[212:215], v[108:111]
	v_mfma_f32_16x16x32_bf16 v[116:119], v[96:99], v[212:215], v[116:119]
	v_mfma_f32_16x16x32_bf16 v[116:119], v[88:91], v[186:189], v[116:119]
	s_setprio 0
	s_setprio 1
	v_mfma_f32_16x16x32_bf16 v[100:103], v[88:91], v[216:219], v[100:103]
	v_mfma_f32_16x16x32_bf16 v[100:103], v[96:99], v[220:223], v[100:103]
	v_mfma_f32_16x16x32_bf16 v[84:87], v[140:143], v[220:223], v[84:87]
	v_mfma_f32_16x16x32_bf16 v[84:87], v[136:139], v[216:219], v[84:87]
	v_mfma_f32_16x16x32_bf16 v[92:95], v[144:147], v[216:219], v[92:95]
	v_mfma_f32_16x16x32_bf16 v[92:95], v[148:151], v[220:223], v[92:95]
	v_mfma_f32_16x16x32_bf16 v[80:83], v[156:159], v[220:223], v[80:83]
	v_mfma_f32_16x16x32_bf16 v[80:83], v[152:155], v[216:219], v[80:83]
	v_mfma_f32_16x16x32_bf16 v[64:67], v[152:155], v[224:227], v[64:67]
	v_mfma_f32_16x16x32_bf16 v[64:67], v[156:159], v[228:231], v[64:67]
	v_mfma_f32_16x16x32_bf16 v[72:75], v[148:151], v[228:231], v[72:75]
	v_mfma_f32_16x16x32_bf16 v[72:75], v[144:147], v[224:227], v[72:75]
	v_mfma_f32_16x16x32_bf16 v[68:71], v[136:139], v[224:227], v[68:71]
	v_mfma_f32_16x16x32_bf16 v[68:71], v[140:143], v[228:231], v[68:71]
	s_setprio 3
	s_barrier
	v_mfma_f32_16x16x32_bf16 v[76:79], v[96:99], v[228:231], v[76:79]
	v_mfma_f32_16x16x32_bf16 v[76:79], v[88:91], v[224:227], v[76:79]
	s_setprio 0
	s_add_i32 s44, s71, s65
	v_lshl_add_u64 v[200:201], s[56:57], 0, v[164:165]
	s_mov_b32 m0, s44
	ds_read_b128 v[178:181], v210 offset:16384
	ds_read_b128 v[182:185], v210 offset:17408
	ds_read_b128 v[186:189], v210 offset:18432
	ds_read_b128 v[212:215], v210 offset:19456
	ds_read_b128 v[216:219], v210 offset:20480
	ds_read_b128 v[220:223], v210 offset:21504
	ds_read_b128 v[224:227], v210 offset:22528
	ds_read_b128 v[228:231], v210 offset:23552
	global_load_lds_dwordx4 v[200:201], off
	s_add_i32 m0, s44, 0x2000
	s_add_u32 s78, s56, 0x80000
	v_lshl_add_u64 v[232:233], s[56:57], 0, v[168:169]
	s_addc_u32 s79, s57, 0
	s_add_i32 s44, s72, s65
	global_load_lds_dwordx4 v[232:233], off
	v_lshl_add_u64 v[234:235], s[78:79], 0, v[164:165]
	s_mov_b32 m0, s44
	v_lshl_add_u64 v[236:237], s[58:59], 0, v[168:169]
	global_load_lds_dwordx4 v[234:235], off
	v_lshl_add_u64 v[234:235], s[78:79], 0, v[168:169]
	s_add_i32 m0, s44, 0x2000
	s_nop 0
	global_load_lds_dwordx4 v[234:235], off
	v_lshl_add_u64 v[234:235], s[58:59], 0, v[164:165]
	s_mov_b32 m0, s49
	s_nop 0
	global_load_lds_dwordx4 v[234:235], off
	s_mov_b32 m0, s61
	s_nop 0
	global_load_lds_dwordx4 v[236:237], off
	s_waitcnt vmcnt(8)
	s_waitcnt lgkmcnt(0)
	s_barrier
; #define PG8_STAGE(bufoff, gbase, voff) do { _Pragma("unroll") for (int _i = 0; _i < 2; ++_i) \
;         __builtin_amdgcn_global_load_lds((const unsigned*)((const char*)(gbase) + (voff)[_i]), (PG8_LAS unsigned*)(lds + (bufoff) + ldsw + _i * 8192), 16, 0, 0); } while (0)
; #define PG8_LDA(dst, b, h) do { _Pragma("unroll") for (int m = 0; m < 4; ++m) _Pragma("unroll") for (int k = 0; k < 2; ++k) dst[m][k] = *(const PG8_LAS bf16x8*)(lds + PG8_SA(b, h) + aoff + m * 2048 + k * 1024); } while (0)
; #define PG8_LDB(dst, b, h) do { _Pragma("unroll") for (int n = 0; n < 2; ++n) _Pragma("unroll") for (int k = 0; k < 2; ++k) dst[n][k] = *(const PG8_LAS bf16x8*)(lds + PG8_SB(b, h) + boff + n * 2048 + k * 1024); } while (0)
; #define PG8_MMA(ai, bj, At, Bt) do { __builtin_amdgcn_s_setprio(1); _Pragma("unroll") for (int m = 0; m < 4; ++m) _Pragma("unroll") for (int n = 0; n < 2; ++n) _Pragma("unroll") for (int k = 0; k < 2; ++k) \
;         acc[ai][bj][m][n] = __builtin_amdgcn_mfma_f32_16x16x32_bf16(Bt[n][k], At[m][k], acc[ai][bj][m][n], 0, 0, 0); __builtin_amdgcn_s_setprio(0); } while (0)
; #define PG8_WAIT_V(n) asm volatile("s_waitcnt vmcnt(" #n ")" ::: "memory")
; #define PG8_WAIT_L(n) asm volatile("s_waitcnt lgkmcnt(" #n ")" ::: "memory")
; #define PG8_BAR __builtin_amdgcn_s_barrier()
; #define PG8_SCHED __builtin_amdgcn_sched_barrier(0)
; template <class Epi, class Sched, bool ALIGN_EPI = false, bool SP2 = false>
; __device__ __forceinline__ void gemm_phase(PG8_LAS unsigned char* lds, const Gemm g, const Sched& S, const Epi& E) {
;     ...
;             PG8_WAIT_V(8); PG8_WAIT_L(0); PG8_BAR; PG8_MMA(1, 0, At, B0); PG8_MMA(1, 1, At, B1); PG8_BAR; PG8_SCHED;
;             PG8_LDB(B0, 1, 0); PG8_LDB(B1, 1, 1); PG8_SCHED; PG8_LDA(At, 1, 0); PG8_STAGE(PG8_SA(0, 1), a2 + hstep, voffA);
;             PG8_WAIT_V(8); PG8_WAIT_L(0); PG8_BAR; PG8_MMA(0, 0, At, B0); PG8_MMA(0, 1, At, B1); PG8_BAR; PG8_SCHED;
	s_setprio 1
	s_waitcnt lgkmcnt(0)
	v_mfma_f32_16x16x32_bf16 v[56:59], v[88:91], v[178:181], v[56:59]
	v_mfma_f32_16x16x32_bf16 v[56:59], v[96:99], v[182:185], v[56:59]
	v_mfma_f32_16x16x32_bf16 v[48:51], v[140:143], v[182:185], v[48:51]
	v_mfma_f32_16x16x32_bf16 v[48:51], v[136:139], v[178:181], v[48:51]
	v_mfma_f32_16x16x32_bf16 v[60:63], v[144:147], v[178:181], v[60:63]
	v_mfma_f32_16x16x32_bf16 v[60:63], v[148:151], v[182:185], v[60:63]
	v_mfma_f32_16x16x32_bf16 v[52:55], v[156:159], v[182:185], v[52:55]
	v_mfma_f32_16x16x32_bf16 v[52:55], v[152:155], v[178:181], v[52:55]
	v_mfma_f32_16x16x32_bf16 v[32:35], v[152:155], v[186:189], v[32:35]
	v_mfma_f32_16x16x32_bf16 v[32:35], v[156:159], v[212:215], v[32:35]
	v_mfma_f32_16x16x32_bf16 v[40:43], v[148:151], v[212:215], v[40:43]
	v_mfma_f32_16x16x32_bf16 v[40:43], v[144:147], v[186:189], v[40:43]
	v_mfma_f32_16x16x32_bf16 v[36:39], v[136:139], v[186:189], v[36:39]
	v_mfma_f32_16x16x32_bf16 v[36:39], v[140:143], v[212:215], v[36:39]
	v_mfma_f32_16x16x32_bf16 v[44:47], v[96:99], v[212:215], v[44:47]
	v_mfma_f32_16x16x32_bf16 v[44:47], v[88:91], v[186:189], v[44:47]
	s_setprio 0
	s_setprio 1
	v_mfma_f32_16x16x32_bf16 v[28:31], v[88:91], v[216:219], v[28:31]
	v_mfma_f32_16x16x32_bf16 v[28:31], v[96:99], v[220:223], v[28:31]
	v_mfma_f32_16x16x32_bf16 v[20:23], v[140:143], v[220:223], v[20:23]
	v_mfma_f32_16x16x32_bf16 v[20:23], v[136:139], v[216:219], v[20:23]
	v_mfma_f32_16x16x32_bf16 v[24:27], v[144:147], v[216:219], v[24:27]
	v_mfma_f32_16x16x32_bf16 v[24:27], v[148:151], v[220:223], v[24:27]
	v_mfma_f32_16x16x32_bf16 v[16:19], v[156:159], v[220:223], v[16:19]
	v_mfma_f32_16x16x32_bf16 v[16:19], v[152:155], v[216:219], v[16:19]
	v_mfma_f32_16x16x32_bf16 v[0:3], v[152:155], v[224:227], v[0:3]
	v_mfma_f32_16x16x32_bf16 v[0:3], v[156:159], v[228:231], v[0:3]
	v_mfma_f32_16x16x32_bf16 v[8:11], v[148:151], v[228:231], v[8:11]
	v_mfma_f32_16x16x32_bf16 v[8:11], v[144:147], v[224:227], v[8:11]
	v_mfma_f32_16x16x32_bf16 v[4:7], v[136:139], v[224:227], v[4:7]
	v_mfma_f32_16x16x32_bf16 v[4:7], v[140:143], v[228:231], v[4:7]
	s_setprio 3
	s_barrier
	v_mfma_f32_16x16x32_bf16 v[12:15], v[96:99], v[228:231], v[12:15]
	v_mfma_f32_16x16x32_bf16 v[12:15], v[88:91], v[224:227], v[12:15]
	s_setprio 0
	s_add_i32 s44, 0, 0x18000
	s_add_i32 s45, 0, 0x1c000
	v_add_u32_e32 v140, s44, v163
	v_add_u32_e32 v156, s45, v163
	ds_read_b128 v[88:91], v140
	ds_read_b128 v[96:99], v140 offset:1024
	ds_read_b128 v[136:139], v140 offset:2048
	ds_read_b128 v[140:143], v140 offset:3072
	ds_read_b128 v[144:147], v156
	ds_read_b128 v[148:151], v156 offset:1024
	ds_read_b128 v[152:155], v156 offset:2048
	ds_read_b128 v[156:159], v156 offset:3072
	s_add_u32 s58, s58, 0x80000
	s_addc_u32 s59, s59, 0
	s_mov_b32 m0, s66
	v_lshl_add_u64 v[238:239], s[58:59], 0, v[164:165]
	ds_read_b128 v[178:181], v210 offset:32768
	ds_read_b128 v[182:185], v210 offset:33792
	ds_read_b128 v[186:189], v210 offset:34816
	ds_read_b128 v[212:215], v210 offset:35840
	ds_read_b128 v[216:219], v210 offset:36864
	ds_read_b128 v[220:223], v210 offset:37888
	ds_read_b128 v[224:227], v210 offset:38912
	ds_read_b128 v[228:231], v210 offset:39936
	global_load_lds_dwordx4 v[238:239], off
	v_lshl_add_u64 v[238:239], s[58:59], 0, v[168:169]
	s_mov_b32 m0, s67
	s_nop 0
	global_load_lds_dwordx4 v[238:239], off
	s_waitcnt vmcnt(8)
	s_waitcnt lgkmcnt(0)
	s_barrier
	s_setprio 1
	s_waitcnt lgkmcnt(0)
	v_mfma_f32_16x16x32_bf16 v[128:131], v[88:91], v[178:181], v[128:131]
	v_mfma_f32_16x16x32_bf16 v[128:131], v[96:99], v[182:185], v[128:131]
	v_mfma_f32_16x16x32_bf16 v[120:123], v[140:143], v[182:185], v[120:123]
	v_mfma_f32_16x16x32_bf16 v[120:123], v[136:139], v[178:181], v[120:123]
	v_mfma_f32_16x16x32_bf16 v[132:135], v[144:147], v[178:181], v[132:135]
	v_mfma_f32_16x16x32_bf16 v[132:135], v[148:151], v[182:185], v[132:135]
	v_mfma_f32_16x16x32_bf16 v[124:127], v[156:159], v[182:185], v[124:127]
	v_mfma_f32_16x16x32_bf16 v[124:127], v[152:155], v[178:181], v[124:127]
	v_mfma_f32_16x16x32_bf16 v[104:107], v[152:155], v[186:189], v[104:107]
	v_mfma_f32_16x16x32_bf16 v[104:107], v[156:159], v[212:215], v[104:107]
	v_mfma_f32_16x16x32_bf16 v[112:115], v[148:151], v[212:215], v[112:115]
	v_mfma_f32_16x16x32_bf16 v[112:115], v[144:147], v[186:189], v[112:115]
	v_mfma_f32_16x16x32_bf16 v[108:111], v[136:139], v[186:189], v[108:111]
	v_mfma_f32_16x16x32_bf16 v[108:111], v[140:143], v[212:215], v[108:111]
	v_mfma_f32_16x16x32_bf16 v[116:119], v[96:99], v[212:215], v[116:119]
	v_mfma_f32_16x16x32_bf16 v[116:119], v[88:91], v[186:189], v[116:119]
	s_setprio 0
	s_setprio 1
	v_mfma_f32_16x16x32_bf16 v[100:103], v[88:91], v[216:219], v[100:103]
	v_mfma_f32_16x16x32_bf16 v[100:103], v[96:99], v[220:223], v[100:103]
	v_mfma_f32_16x16x32_bf16 v[84:87], v[140:143], v[220:223], v[84:87]
	v_mfma_f32_16x16x32_bf16 v[84:87], v[136:139], v[216:219], v[84:87]
	v_mfma_f32_16x16x32_bf16 v[92:95], v[144:147], v[216:219], v[92:95]
	v_mfma_f32_16x16x32_bf16 v[92:95], v[148:151], v[220:223], v[92:95]
	v_mfma_f32_16x16x32_bf16 v[80:83], v[156:159], v[220:223], v[80:83]
	v_mfma_f32_16x16x32_bf16 v[80:83], v[152:155], v[216:219], v[80:83]
	v_mfma_f32_16x16x32_bf16 v[64:67], v[152:155], v[224:227], v[64:67]
	v_mfma_f32_16x16x32_bf16 v[64:67], v[156:159], v[228:231], v[64:67]
	v_mfma_f32_16x16x32_bf16 v[72:75], v[148:151], v[228:231], v[72:75]
	v_mfma_f32_16x16x32_bf16 v[72:75], v[144:147], v[224:227], v[72:75]
	v_mfma_f32_16x16x32_bf16 v[68:71], v[136:139], v[224:227], v[68:71]
	v_mfma_f32_16x16x32_bf16 v[68:71], v[140:143], v[228:231], v[68:71]
	s_setprio 3
	s_barrier
; #define PG8_STAGE(bufoff, gbase, voff) do { _Pragma("unroll") for (int _i = 0; _i < 2; ++_i) \
;         __builtin_amdgcn_global_load_lds((const unsigned*)((const char*)(gbase) + (voff)[_i]), (PG8_LAS unsigned*)(lds + (bufoff) + ldsw + _i * 8192), 16, 0, 0); } while (0)
; #define PG8_LDA(dst, b, h) do { _Pragma("unroll") for (int m = 0; m < 4; ++m) _Pragma("unroll") for (int k = 0; k < 2; ++k) dst[m][k] = *(const PG8_LAS bf16x8*)(lds + PG8_SA(b, h) + aoff + m * 2048 + k * 1024); } while (0)
; #define PG8_MMA(ai, bj, At, Bt) do { __builtin_amdgcn_s_setprio(1); _Pragma("unroll") for (int m = 0; m < 4; ++m) _Pragma("unroll") for (int n = 0; n < 2; ++n) _Pragma("unroll") for (int k = 0; k < 2; ++k) \
;         acc[ai][bj][m][n] = __builtin_amdgcn_mfma_f32_16x16x32_bf16(Bt[n][k], At[m][k], acc[ai][bj][m][n], 0, 0, 0); __builtin_amdgcn_s_setprio(0); } while (0)
; #define PG8_WAIT_V(n) asm volatile("s_waitcnt vmcnt(" #n ")" ::: "memory")
; #define PG8_WAIT_L(n) asm volatile("s_waitcnt lgkmcnt(" #n ")" ::: "memory")
; #define PG8_BAR __builtin_amdgcn_s_barrier()
; #define PG8_SCHED __builtin_amdgcn_sched_barrier(0)
; template <class Epi, class Sched, bool ALIGN_EPI = false, bool SP2 = false>
; __device__ __forceinline__ void gemm_phase(PG8_LAS unsigned char* lds, const Gemm g, const Sched& S, const Epi& E) {
;     ...
;             PG8_WAIT_V(8); PG8_WAIT_L(0); PG8_BAR; PG8_MMA(0, 0, At, B0); PG8_MMA(0, 1, At, B1); PG8_BAR; PG8_SCHED;
;             PG8_LDA(At, 1, 1); PG8_STAGE(PG8_SB(1, 0), b3, voffB); PG8_STAGE(PG8_SB(1, 1), b3 + hstep, voffB); PG8_STAGE(PG8_SA(1, 0), a3, voffA);
;             PG8_WAIT_V(8); PG8_WAIT_L(0); PG8_BAR; PG8_MMA(1, 0, At, B0); PG8_MMA(1, 1, At, B1); PG8_BAR; PG8_SCHED;
;     ...
;         if constexpr (ALIGN_EPI) { if (wr == 0) PG8_BAR; }
	v_mfma_f32_16x16x32_bf16 v[76:79], v[96:99], v[228:231], v[76:79]
	v_mfma_f32_16x16x32_bf16 v[76:79], v[88:91], v[224:227], v[76:79]
	s_setprio 0
	s_add_i32 s44, s44, s65
	v_lshl_add_u64 v[200:201], v[200:201], 0, s[18:19]
	s_mov_b32 m0, s44
	ds_read_b128 v[178:181], v210 offset:49152
	ds_read_b128 v[182:185], v210 offset:50176
	ds_read_b128 v[186:189], v210 offset:51200
	ds_read_b128 v[212:215], v210 offset:52224
	ds_read_b128 v[216:219], v210 offset:53248
	ds_read_b128 v[220:223], v210 offset:54272
	ds_read_b128 v[224:227], v210 offset:55296
	ds_read_b128 v[228:231], v210 offset:56320
	global_load_lds_dwordx4 v[200:201], off
	s_add_i32 m0, s44, 0x2000
	s_add_u32 s56, s56, 0x80080
	v_lshl_add_u64 v[200:201], v[232:233], 0, s[18:19]
	s_addc_u32 s57, s57, 0
	s_add_i32 s44, s45, s65
	global_load_lds_dwordx4 v[200:201], off
	v_lshl_add_u64 v[200:201], s[56:57], 0, v[164:165]
	s_mov_b32 m0, s44
	s_nop 0
	global_load_lds_dwordx4 v[200:201], off
	v_lshl_add_u64 v[200:201], s[56:57], 0, v[168:169]
	s_add_i32 m0, s44, 0x2000
	s_nop 0
	global_load_lds_dwordx4 v[200:201], off
	v_lshl_add_u64 v[200:201], v[234:235], 0, s[18:19]
	s_mov_b32 m0, s68
	s_nop 0
	global_load_lds_dwordx4 v[200:201], off
	v_lshl_add_u64 v[200:201], v[236:237], 0, s[18:19]
	s_mov_b32 m0, s69
	s_nop 0
	global_load_lds_dwordx4 v[200:201], off
	s_waitcnt vmcnt(8)
	s_waitcnt lgkmcnt(0)
	s_barrier
	s_setprio 1
	s_waitcnt lgkmcnt(0)
	v_mfma_f32_16x16x32_bf16 v[56:59], v[88:91], v[178:181], v[56:59]
	v_mfma_f32_16x16x32_bf16 v[56:59], v[96:99], v[182:185], v[56:59]
	v_mfma_f32_16x16x32_bf16 v[48:51], v[140:143], v[182:185], v[48:51]
	v_mfma_f32_16x16x32_bf16 v[48:51], v[136:139], v[178:181], v[48:51]
	v_mfma_f32_16x16x32_bf16 v[60:63], v[144:147], v[178:181], v[60:63]
	v_mfma_f32_16x16x32_bf16 v[60:63], v[148:151], v[182:185], v[60:63]
	v_mfma_f32_16x16x32_bf16 v[52:55], v[156:159], v[182:185], v[52:55]
	v_mfma_f32_16x16x32_bf16 v[52:55], v[152:155], v[178:181], v[52:55]
	v_mfma_f32_16x16x32_bf16 v[32:35], v[152:155], v[186:189], v[32:35]
	v_mfma_f32_16x16x32_bf16 v[32:35], v[156:159], v[212:215], v[32:35]
	v_mfma_f32_16x16x32_bf16 v[40:43], v[148:151], v[212:215], v[40:43]
	v_mfma_f32_16x16x32_bf16 v[40:43], v[144:147], v[186:189], v[40:43]
	v_mfma_f32_16x16x32_bf16 v[36:39], v[136:139], v[186:189], v[36:39]
	v_mfma_f32_16x16x32_bf16 v[36:39], v[140:143], v[212:215], v[36:39]
	v_mfma_f32_16x16x32_bf16 v[44:47], v[96:99], v[212:215], v[44:47]
	v_mfma_f32_16x16x32_bf16 v[44:47], v[88:91], v[186:189], v[44:47]
	s_setprio 0
	s_setprio 1
	v_mfma_f32_16x16x32_bf16 v[28:31], v[88:91], v[216:219], v[28:31]
	v_mfma_f32_16x16x32_bf16 v[28:31], v[96:99], v[220:223], v[28:31]
	v_mfma_f32_16x16x32_bf16 v[20:23], v[140:143], v[220:223], v[20:23]
	v_mfma_f32_16x16x32_bf16 v[20:23], v[136:139], v[216:219], v[20:23]
	v_mfma_f32_16x16x32_bf16 v[24:27], v[144:147], v[216:219], v[24:27]
	v_mfma_f32_16x16x32_bf16 v[24:27], v[148:151], v[220:223], v[24:27]
	v_mfma_f32_16x16x32_bf16 v[16:19], v[156:159], v[220:223], v[16:19]
	v_mfma_f32_16x16x32_bf16 v[16:19], v[152:155], v[216:219], v[16:19]
	v_mfma_f32_16x16x32_bf16 v[0:3], v[152:155], v[224:227], v[0:3]
	v_mfma_f32_16x16x32_bf16 v[0:3], v[156:159], v[228:231], v[0:3]
	v_mfma_f32_16x16x32_bf16 v[8:11], v[148:151], v[228:231], v[8:11]
	v_mfma_f32_16x16x32_bf16 v[8:11], v[144:147], v[224:227], v[8:11]
	v_mfma_f32_16x16x32_bf16 v[4:7], v[136:139], v[224:227], v[4:7]
	v_mfma_f32_16x16x32_bf16 v[4:7], v[140:143], v[228:231], v[4:7]
	s_setprio 3
	s_barrier
	v_mfma_f32_16x16x32_bf16 v[12:15], v[96:99], v[228:231], v[12:15]
	v_mfma_f32_16x16x32_bf16 v[12:15], v[88:91], v[224:227], v[12:15]
	s_setprio 0
	s_add_i32 s76, s76, 2
	s_add_u32 s62, s62, 0x100
	s_addc_u32 s63, s63, 0
	s_add_u32 s74, s74, 0x100
	s_addc_u32 s75, s75, 0
	s_cmp_gt_u32 s76, 29
	s_cbranch_scc0 .LBB0_719
	s_and_b64 vcc, exec, s[20:21]
	s_cbranch_vccz .LBB0_722
	s_barrier

; #define PG8_STAGE(bufoff, gbase, voff) do { _Pragma("unroll") for (int _i = 0; _i < 2; ++_i) \
;         __builtin_amdgcn_global_load_lds((const unsigned*)((const char*)(gbase) + (voff)[_i]), (PG8_LAS unsigned*)(lds + (bufoff) + ldsw + _i * 8192), 16, 0, 0); } while (0)
; #define PG8_LDA(dst, b, h) do { _Pragma("unroll") for (int m = 0; m < 4; ++m) _Pragma("unroll") for (int k = 0; k < 2; ++k) dst[m][k] = *(const PG8_LAS bf16x8*)(lds + PG8_SA(b, h) + aoff + m * 2048 + k * 1024); } while (0)
; #define PG8_LDB(dst, b, h) do { _Pragma("unroll") for (int n = 0; n < 2; ++n) _Pragma("unroll") for (int k = 0; k < 2; ++k) dst[n][k] = *(const PG8_LAS bf16x8*)(lds + PG8_SB(b, h) + boff + n * 2048 + k * 1024); } while (0)
; #define PG8_MMA(ai, bj, At, Bt) do { __builtin_amdgcn_s_setprio(1); _Pragma("unroll") for (int m = 0; m < 4; ++m) _Pragma("unroll") for (int n = 0; n < 2; ++n) _Pragma("unroll") for (int k = 0; k < 2; ++k) \
;         acc[ai][bj][m][n] = __builtin_amdgcn_mfma_f32_16x16x32_bf16(Bt[n][k], At[m][k], acc[ai][bj][m][n], 0, 0, 0); __builtin_amdgcn_s_setprio(0); } while (0)
; #define PG8_WAIT_V(n) asm volatile("s_waitcnt vmcnt(" #n ")" ::: "memory")
; #define PG8_WAIT_L(n) asm volatile("s_waitcnt lgkmcnt(" #n ")" ::: "memory")
; template <class Epi, class Sched, bool ALIGN_EPI = false, bool SP2 = false>
; __device__ __forceinline__ void gemm_phase(PG8_LAS unsigned char* lds, const Gemm g, const Sched& S, const Epi& E) {
;     ...
;             const bool last = (t == nt - 2);
;             const char* a1 = cA + (size_t)(t + 1) * kstep;
;             const char* a2 = last ? nA : cA + (size_t)(t + 2) * kstep; const char* b2 = last ? nB : cB + (size_t)(t + 2) * kstep;
;             const char* a3 = a2 + kstep; const char* b3 = b2 + kstep;
;             if (last && has_next) S.a_ready(nxt);
;             if constexpr (SP2) {
;             PG8_LDB(B0, 0, 0); PG8_LDB(B1, 0, 1); PG8_SCHED; PG8_LDA(At, 0, 0); PG8_STAGE(PG8_SA(1, 1), a1 + hstep, voffA);
;             PG8_WAIT_V(8); PG8_WAIT_L(0); PG8_BAR; PG8_MMA(0, 0, At, B0); PG8_MMA(0, 1, At, B1); PG8_BAR; PG8_SCHED;
;             PG8_LDA(At, 0, 1); PG8_STAGE(PG8_SB(0, 0), b2, voffB); PG8_STAGE(PG8_SB(0, 1), b2 + hstep, voffB); PG8_STAGE(PG8_SA(0, 0), a2, voffA);
;             PG8_WAIT_V(8); PG8_WAIT_L(0); PG8_BAR; PG8_MMA(1, 0, At, B0); PG8_MMA(1, 1, At, B1); PG8_BAR; PG8_SCHED;
.LBB0_774:
	ds_read_b128 v[136:139], v156
	ds_read_b128 v[140:143], v156 offset:1024
	ds_read_b128 v[172:175], v156 offset:2048
	ds_read_b128 v[176:179], v156 offset:3072
	ds_read_b128 v[180:183], v157
	ds_read_b128 v[184:187], v157 offset:1024
	ds_read_b128 v[208:211], v157 offset:2048
	ds_read_b128 v[212:215], v157 offset:3072
	s_add_u32 s42, s40, 0xfff80080
	s_addc_u32 s43, s41, -1
	s_cmp_eq_u32 s71, 28
	s_cselect_b32 s49, s23, s43
	s_cselect_b32 s48, s34, s42
	s_cselect_b32 s43, s21, s70
	s_cselect_b32 s42, s35, s69
	v_lshl_add_u64 v[188:189], s[40:41], 0, v[128:129]
	s_add_i32 m0, s11, 0xc000
	ds_read_b128 v[216:219], v158
	ds_read_b128 v[220:223], v158 offset:1024
	ds_read_b128 v[224:227], v158 offset:2048
	ds_read_b128 v[228:231], v158 offset:3072
	ds_read_b128 v[232:235], v158 offset:4096
	ds_read_b128 v[236:239], v158 offset:5120
	ds_read_b128 v[240:243], v158 offset:6144
	ds_read_b128 v[244:247], v158 offset:7168
	global_load_lds_dwordx4 v[188:189], off
	v_lshl_add_u64 v[188:189], s[40:41], 0, v[130:131]
	s_add_i32 m0, s11, 0xe000
	s_nop 0
	global_load_lds_dwordx4 v[188:189], off
	s_waitcnt vmcnt(8)
	s_waitcnt lgkmcnt(0)
	s_barrier
	s_setprio 1
	s_waitcnt lgkmcnt(0)
	v_mfma_f32_16x16x32_bf16 v[124:127], v[136:139], v[216:219], v[124:127]
	v_mfma_f32_16x16x32_bf16 v[124:127], v[140:143], v[220:223], v[124:127]
	v_mfma_f32_16x16x32_bf16 v[120:123], v[176:179], v[220:223], v[120:123]
	v_mfma_f32_16x16x32_bf16 v[120:123], v[172:175], v[216:219], v[120:123]
	v_mfma_f32_16x16x32_bf16 v[116:119], v[180:183], v[216:219], v[116:119]
	v_mfma_f32_16x16x32_bf16 v[116:119], v[184:187], v[220:223], v[116:119]
	v_mfma_f32_16x16x32_bf16 v[112:115], v[212:215], v[220:223], v[112:115]
	v_mfma_f32_16x16x32_bf16 v[112:115], v[208:211], v[216:219], v[112:115]
	v_mfma_f32_16x16x32_bf16 v[92:95], v[208:211], v[224:227], v[92:95]
	v_mfma_f32_16x16x32_bf16 v[92:95], v[212:215], v[228:231], v[92:95]
	v_mfma_f32_16x16x32_bf16 v[100:103], v[184:187], v[228:231], v[100:103]
	v_mfma_f32_16x16x32_bf16 v[100:103], v[180:183], v[224:227], v[100:103]
	v_mfma_f32_16x16x32_bf16 v[104:107], v[172:175], v[224:227], v[104:107]
	v_mfma_f32_16x16x32_bf16 v[104:107], v[176:179], v[228:231], v[104:107]
	v_mfma_f32_16x16x32_bf16 v[108:111], v[140:143], v[228:231], v[108:111]
	v_mfma_f32_16x16x32_bf16 v[108:111], v[136:139], v[224:227], v[108:111]
	s_setprio 0
	s_setprio 1
	v_mfma_f32_16x16x32_bf16 v[96:99], v[136:139], v[232:235], v[96:99]
	v_mfma_f32_16x16x32_bf16 v[96:99], v[140:143], v[236:239], v[96:99]
	v_mfma_f32_16x16x32_bf16 v[88:91], v[176:179], v[236:239], v[88:91]
	v_mfma_f32_16x16x32_bf16 v[88:91], v[172:175], v[232:235], v[88:91]
	v_mfma_f32_16x16x32_bf16 v[84:87], v[180:183], v[232:235], v[84:87]
	v_mfma_f32_16x16x32_bf16 v[84:87], v[184:187], v[236:239], v[84:87]
	v_mfma_f32_16x16x32_bf16 v[76:79], v[212:215], v[236:239], v[76:79]
	v_mfma_f32_16x16x32_bf16 v[76:79], v[208:211], v[232:235], v[76:79]
	v_mfma_f32_16x16x32_bf16 v[64:67], v[208:211], v[240:243], v[64:67]
	v_mfma_f32_16x16x32_bf16 v[64:67], v[212:215], v[244:247], v[64:67]
	v_mfma_f32_16x16x32_bf16 v[68:71], v[184:187], v[244:247], v[68:71]
	v_mfma_f32_16x16x32_bf16 v[68:71], v[180:183], v[240:243], v[68:71]
	v_mfma_f32_16x16x32_bf16 v[72:75], v[172:175], v[240:243], v[72:75]
	v_mfma_f32_16x16x32_bf16 v[72:75], v[176:179], v[244:247], v[72:75]
	s_setprio 3
	s_barrier
	v_mfma_f32_16x16x32_bf16 v[80:83], v[140:143], v[244:247], v[80:83]
	v_mfma_f32_16x16x32_bf16 v[80:83], v[136:139], v[240:243], v[80:83]
	s_setprio 0
	s_add_i32 s44, s64, s52
	v_lshl_add_u64 v[188:189], s[42:43], 0, v[166:167]
	s_mov_b32 m0, s44
	ds_read_b128 v[216:219], v158 offset:16384
	ds_read_b128 v[220:223], v158 offset:17408
	ds_read_b128 v[224:227], v158 offset:18432
	ds_read_b128 v[228:231], v158 offset:19456
	ds_read_b128 v[232:235], v158 offset:20480
	ds_read_b128 v[236:239], v158 offset:21504
	ds_read_b128 v[240:243], v158 offset:22528
	ds_read_b128 v[244:247], v158 offset:23552
	global_load_lds_dwordx4 v[188:189], off
	s_add_i32 m0, s44, 0x2000
	s_add_u32 s72, s42, 0x80000
	v_lshl_add_u64 v[200:201], s[42:43], 0, v[170:171]
	s_addc_u32 s73, s43, 0
	s_add_i32 s44, s65, s52
	global_load_lds_dwordx4 v[200:201], off
	v_lshl_add_u64 v[248:249], s[72:73], 0, v[166:167]
	s_mov_b32 m0, s44
	v_lshl_add_u64 v[250:251], s[48:49], 0, v[168:169]
	global_load_lds_dwordx4 v[248:249], off
	v_lshl_add_u64 v[248:249], s[72:73], 0, v[170:171]
	s_add_i32 m0, s44, 0x2000
	s_nop 0
	global_load_lds_dwordx4 v[248:249], off
	v_lshl_add_u64 v[248:249], s[48:49], 0, v[164:165]
	s_mov_b32 m0, s11
	s_nop 0
	global_load_lds_dwordx4 v[248:249], off
	s_mov_b32 m0, s58
	s_nop 0
	global_load_lds_dwordx4 v[250:251], off
	s_waitcnt vmcnt(8)
	s_waitcnt lgkmcnt(0)
	s_barrier
; #define PG8_STAGE(bufoff, gbase, voff) do { _Pragma("unroll") for (int _i = 0; _i < 2; ++_i) \
;         __builtin_amdgcn_global_load_lds((const unsigned*)((const char*)(gbase) + (voff)[_i]), (PG8_LAS unsigned*)(lds + (bufoff) + ldsw + _i * 8192), 16, 0, 0); } while (0)
; #define PG8_LDA(dst, b, h) do { _Pragma("unroll") for (int m = 0; m < 4; ++m) _Pragma("unroll") for (int k = 0; k < 2; ++k) dst[m][k] = *(const PG8_LAS bf16x8*)(lds + PG8_SA(b, h) + aoff + m * 2048 + k * 1024); } while (0)
; #define PG8_LDB(dst, b, h) do { _Pragma("unroll") for (int n = 0; n < 2; ++n) _Pragma("unroll") for (int k = 0; k < 2; ++k) dst[n][k] = *(const PG8_LAS bf16x8*)(lds + PG8_SB(b, h) + boff + n * 2048 + k * 1024); } while (0)
; #define PG8_MMA(ai, bj, At, Bt) do { __builtin_amdgcn_s_setprio(1); _Pragma("unroll") for (int m = 0; m < 4; ++m) _Pragma("unroll") for (int n = 0; n < 2; ++n) _Pragma("unroll") for (int k = 0; k < 2; ++k) \
;         acc[ai][bj][m][n] = __builtin_amdgcn_mfma_f32_16x16x32_bf16(Bt[n][k], At[m][k], acc[ai][bj][m][n], 0, 0, 0); __builtin_amdgcn_s_setprio(0); } while (0)
; #define PG8_WAIT_V(n) asm volatile("s_waitcnt vmcnt(" #n ")" ::: "memory")
; #define PG8_WAIT_L(n) asm volatile("s_waitcnt lgkmcnt(" #n ")" ::: "memory")
; #define PG8_BAR __builtin_amdgcn_s_barrier()
; #define PG8_SCHED __builtin_amdgcn_sched_barrier(0)
; template <class Epi, class Sched, bool ALIGN_EPI = false, bool SP2 = false>
; __device__ __forceinline__ void gemm_phase(PG8_LAS unsigned char* lds, const Gemm g, const Sched& S, const Epi& E) {
;     ...
;             PG8_WAIT_V(8); PG8_WAIT_L(0); PG8_BAR; PG8_MMA(1, 0, At, B0); PG8_MMA(1, 1, At, B1); PG8_BAR; PG8_SCHED;
;             PG8_LDB(B0, 1, 0); PG8_LDB(B1, 1, 1); PG8_SCHED; PG8_LDA(At, 1, 0); PG8_STAGE(PG8_SA(0, 1), a2 + hstep, voffA);
;             PG8_WAIT_V(8); PG8_WAIT_L(0); PG8_BAR; PG8_MMA(0, 0, At, B0); PG8_MMA(0, 1, At, B1); PG8_BAR; PG8_SCHED;
	s_setprio 1
	s_waitcnt lgkmcnt(0)
	v_mfma_f32_16x16x32_bf16 v[60:63], v[136:139], v[216:219], v[60:63]
	v_mfma_f32_16x16x32_bf16 v[60:63], v[140:143], v[220:223], v[60:63]
	v_mfma_f32_16x16x32_bf16 v[56:59], v[176:179], v[220:223], v[56:59]
	v_mfma_f32_16x16x32_bf16 v[56:59], v[172:175], v[216:219], v[56:59]
	v_mfma_f32_16x16x32_bf16 v[52:55], v[180:183], v[216:219], v[52:55]
	v_mfma_f32_16x16x32_bf16 v[52:55], v[184:187], v[220:223], v[52:55]
	v_mfma_f32_16x16x32_bf16 v[44:47], v[212:215], v[220:223], v[44:47]
	v_mfma_f32_16x16x32_bf16 v[44:47], v[208:211], v[216:219], v[44:47]
	v_mfma_f32_16x16x32_bf16 v[28:31], v[208:211], v[224:227], v[28:31]
	v_mfma_f32_16x16x32_bf16 v[28:31], v[212:215], v[228:231], v[28:31]
	v_mfma_f32_16x16x32_bf16 v[36:39], v[184:187], v[228:231], v[36:39]
	v_mfma_f32_16x16x32_bf16 v[36:39], v[180:183], v[224:227], v[36:39]
	v_mfma_f32_16x16x32_bf16 v[40:43], v[172:175], v[224:227], v[40:43]
	v_mfma_f32_16x16x32_bf16 v[40:43], v[176:179], v[228:231], v[40:43]
	v_mfma_f32_16x16x32_bf16 v[48:51], v[140:143], v[228:231], v[48:51]
	v_mfma_f32_16x16x32_bf16 v[48:51], v[136:139], v[224:227], v[48:51]
	s_setprio 0
	s_setprio 1
	v_mfma_f32_16x16x32_bf16 v[32:35], v[136:139], v[232:235], v[32:35]
	v_mfma_f32_16x16x32_bf16 v[32:35], v[140:143], v[236:239], v[32:35]
	v_mfma_f32_16x16x32_bf16 v[24:27], v[176:179], v[236:239], v[24:27]
	v_mfma_f32_16x16x32_bf16 v[24:27], v[172:175], v[232:235], v[24:27]
	v_mfma_f32_16x16x32_bf16 v[20:23], v[180:183], v[232:235], v[20:23]
	v_mfma_f32_16x16x32_bf16 v[20:23], v[184:187], v[236:239], v[20:23]
	v_mfma_f32_16x16x32_bf16 v[16:19], v[212:215], v[236:239], v[16:19]
	v_mfma_f32_16x16x32_bf16 v[16:19], v[208:211], v[232:235], v[16:19]
	v_mfma_f32_16x16x32_bf16 v[0:3], v[208:211], v[240:243], v[0:3]
	v_mfma_f32_16x16x32_bf16 v[0:3], v[212:215], v[244:247], v[0:3]
	v_mfma_f32_16x16x32_bf16 v[4:7], v[184:187], v[244:247], v[4:7]
	v_mfma_f32_16x16x32_bf16 v[4:7], v[180:183], v[240:243], v[4:7]
	v_mfma_f32_16x16x32_bf16 v[8:11], v[172:175], v[240:243], v[8:11]
	v_mfma_f32_16x16x32_bf16 v[8:11], v[176:179], v[244:247], v[8:11]
	s_setprio 3
	s_barrier
	v_mfma_f32_16x16x32_bf16 v[12:15], v[140:143], v[244:247], v[12:15]
	v_mfma_f32_16x16x32_bf16 v[12:15], v[136:139], v[240:243], v[12:15]
	s_setprio 0
	s_add_i32 s44, 0, 0x18000
	v_add_u32_e32 v144, s44, v146
	s_add_i32 s45, 0, 0x1c000
	ds_read_b128 v[136:139], v144
	ds_read_b128 v[140:143], v144 offset:1024
	ds_read_b128 v[172:175], v144 offset:2048
	ds_read_b128 v[176:179], v144 offset:3072
	v_add_u32_e32 v144, s45, v146
	ds_read_b128 v[180:183], v144
	ds_read_b128 v[184:187], v144 offset:1024
	ds_read_b128 v[208:211], v144 offset:2048
	ds_read_b128 v[212:215], v144 offset:3072
	s_add_u32 s48, s48, 0x80000
	s_addc_u32 s49, s49, 0
	s_mov_b32 m0, s59
	v_lshl_add_u64 v[252:253], s[48:49], 0, v[164:165]
	ds_read_b128 v[216:219], v158 offset:32768
	ds_read_b128 v[220:223], v158 offset:33792
	ds_read_b128 v[224:227], v158 offset:34816
	ds_read_b128 v[228:231], v158 offset:35840
	ds_read_b128 v[232:235], v158 offset:36864
	ds_read_b128 v[236:239], v158 offset:37888
	ds_read_b128 v[240:243], v158 offset:38912
	ds_read_b128 v[244:247], v158 offset:39936
	global_load_lds_dwordx4 v[252:253], off
	v_lshl_add_u64 v[252:253], s[48:49], 0, v[168:169]
	s_mov_b32 m0, s60
	s_nop 0
	global_load_lds_dwordx4 v[252:253], off
	s_waitcnt vmcnt(8)
	s_waitcnt lgkmcnt(0)
	s_barrier
	s_setprio 1
	s_waitcnt lgkmcnt(0)
	v_mfma_f32_16x16x32_bf16 v[124:127], v[136:139], v[216:219], v[124:127]
	v_mfma_f32_16x16x32_bf16 v[124:127], v[140:143], v[220:223], v[124:127]
	v_mfma_f32_16x16x32_bf16 v[120:123], v[176:179], v[220:223], v[120:123]
	v_mfma_f32_16x16x32_bf16 v[120:123], v[172:175], v[216:219], v[120:123]
	v_mfma_f32_16x16x32_bf16 v[116:119], v[180:183], v[216:219], v[116:119]
	v_mfma_f32_16x16x32_bf16 v[116:119], v[184:187], v[220:223], v[116:119]
	v_mfma_f32_16x16x32_bf16 v[112:115], v[212:215], v[220:223], v[112:115]
	v_mfma_f32_16x16x32_bf16 v[112:115], v[208:211], v[216:219], v[112:115]
	v_mfma_f32_16x16x32_bf16 v[92:95], v[208:211], v[224:227], v[92:95]
	v_mfma_f32_16x16x32_bf16 v[92:95], v[212:215], v[228:231], v[92:95]
	v_mfma_f32_16x16x32_bf16 v[100:103], v[184:187], v[228:231], v[100:103]
	v_mfma_f32_16x16x32_bf16 v[100:103], v[180:183], v[224:227], v[100:103]
	v_mfma_f32_16x16x32_bf16 v[104:107], v[172:175], v[224:227], v[104:107]
	v_mfma_f32_16x16x32_bf16 v[104:107], v[176:179], v[228:231], v[104:107]
	v_mfma_f32_16x16x32_bf16 v[108:111], v[140:143], v[228:231], v[108:111]
	v_mfma_f32_16x16x32_bf16 v[108:111], v[136:139], v[224:227], v[108:111]
	s_setprio 0
	s_setprio 1
	v_mfma_f32_16x16x32_bf16 v[96:99], v[136:139], v[232:235], v[96:99]
	v_mfma_f32_16x16x32_bf16 v[96:99], v[140:143], v[236:239], v[96:99]
	v_mfma_f32_16x16x32_bf16 v[88:91], v[176:179], v[236:239], v[88:91]
	v_mfma_f32_16x16x32_bf16 v[88:91], v[172:175], v[232:235], v[88:91]
	v_mfma_f32_16x16x32_bf16 v[84:87], v[180:183], v[232:235], v[84:87]
	v_mfma_f32_16x16x32_bf16 v[84:87], v[184:187], v[236:239], v[84:87]
	v_mfma_f32_16x16x32_bf16 v[76:79], v[212:215], v[236:239], v[76:79]
	v_mfma_f32_16x16x32_bf16 v[76:79], v[208:211], v[232:235], v[76:79]
	v_mfma_f32_16x16x32_bf16 v[64:67], v[208:211], v[240:243], v[64:67]
	v_mfma_f32_16x16x32_bf16 v[64:67], v[212:215], v[244:247], v[64:67]
	v_mfma_f32_16x16x32_bf16 v[68:71], v[184:187], v[244:247], v[68:71]
	v_mfma_f32_16x16x32_bf16 v[68:71], v[180:183], v[240:243], v[68:71]
	v_mfma_f32_16x16x32_bf16 v[72:75], v[172:175], v[240:243], v[72:75]
	v_mfma_f32_16x16x32_bf16 v[72:75], v[176:179], v[244:247], v[72:75]
	s_setprio 3
	s_barrier
; #define PG8_STAGE(bufoff, gbase, voff) do { _Pragma("unroll") for (int _i = 0; _i < 2; ++_i) \
;         __builtin_amdgcn_global_load_lds((const unsigned*)((const char*)(gbase) + (voff)[_i]), (PG8_LAS unsigned*)(lds + (bufoff) + ldsw + _i * 8192), 16, 0, 0); } while (0)
; #define PG8_LDA(dst, b, h) do { _Pragma("unroll") for (int m = 0; m < 4; ++m) _Pragma("unroll") for (int k = 0; k < 2; ++k) dst[m][k] = *(const PG8_LAS bf16x8*)(lds + PG8_SA(b, h) + aoff + m * 2048 + k * 1024); } while (0)
; #define PG8_MMA(ai, bj, At, Bt) do { __builtin_amdgcn_s_setprio(1); _Pragma("unroll") for (int m = 0; m < 4; ++m) _Pragma("unroll") for (int n = 0; n < 2; ++n) _Pragma("unroll") for (int k = 0; k < 2; ++k) \
;         acc[ai][bj][m][n] = __builtin_amdgcn_mfma_f32_16x16x32_bf16(Bt[n][k], At[m][k], acc[ai][bj][m][n], 0, 0, 0); __builtin_amdgcn_s_setprio(0); } while (0)
; #define PG8_WAIT_V(n) asm volatile("s_waitcnt vmcnt(" #n ")" ::: "memory")
; #define PG8_WAIT_L(n) asm volatile("s_waitcnt lgkmcnt(" #n ")" ::: "memory")
; #define PG8_BAR __builtin_amdgcn_s_barrier()
; #define PG8_SCHED __builtin_amdgcn_sched_barrier(0)
; template <class Epi, class Sched, bool ALIGN_EPI = false, bool SP2 = false>
; __device__ __forceinline__ void gemm_phase(PG8_LAS unsigned char* lds, const Gemm g, const Sched& S, const Epi& E) {
;     ...
;             PG8_WAIT_V(8); PG8_WAIT_L(0); PG8_BAR; PG8_MMA(0, 0, At, B0); PG8_MMA(0, 1, At, B1); PG8_BAR; PG8_SCHED;
;             PG8_LDA(At, 1, 1); PG8_STAGE(PG8_SB(1, 0), b3, voffB); PG8_STAGE(PG8_SB(1, 1), b3 + hstep, voffB); PG8_STAGE(PG8_SA(1, 0), a3, voffA);
;             PG8_WAIT_V(8); PG8_WAIT_L(0); PG8_BAR; PG8_MMA(1, 0, At, B0); PG8_MMA(1, 1, At, B1); PG8_BAR; PG8_SCHED;
;     ...
;         if constexpr (ALIGN_EPI) { if (wr == 0) PG8_BAR; }
	v_mfma_f32_16x16x32_bf16 v[80:83], v[140:143], v[244:247], v[80:83]
	v_mfma_f32_16x16x32_bf16 v[80:83], v[136:139], v[240:243], v[80:83]
	s_setprio 0
	s_add_i32 s44, s44, s52
	v_lshl_add_u64 v[188:189], v[188:189], 0, s[16:17]
	s_mov_b32 m0, s44
	ds_read_b128 v[216:219], v158 offset:49152
	ds_read_b128 v[220:223], v158 offset:50176
	ds_read_b128 v[224:227], v158 offset:51200
	ds_read_b128 v[228:231], v158 offset:52224
	ds_read_b128 v[232:235], v158 offset:53248
	ds_read_b128 v[236:239], v158 offset:54272
	ds_read_b128 v[240:243], v158 offset:55296
	ds_read_b128 v[244:247], v158 offset:56320
	global_load_lds_dwordx4 v[188:189], off
	s_add_i32 m0, s44, 0x2000
	s_add_u32 s42, s42, 0x80080
	v_lshl_add_u64 v[188:189], v[200:201], 0, s[16:17]
	s_addc_u32 s43, s43, 0
	s_add_i32 s44, s45, s52
	global_load_lds_dwordx4 v[188:189], off
	v_lshl_add_u64 v[188:189], s[42:43], 0, v[166:167]
	s_mov_b32 m0, s44
	s_nop 0
	global_load_lds_dwordx4 v[188:189], off
	v_lshl_add_u64 v[188:189], s[42:43], 0, v[170:171]
	s_add_i32 m0, s44, 0x2000
	s_nop 0
	global_load_lds_dwordx4 v[188:189], off
	v_lshl_add_u64 v[188:189], v[248:249], 0, s[16:17]
	s_mov_b32 m0, s62
	s_nop 0
	global_load_lds_dwordx4 v[188:189], off
	v_lshl_add_u64 v[188:189], v[250:251], 0, s[16:17]
	s_mov_b32 m0, s63
	s_nop 0
	global_load_lds_dwordx4 v[188:189], off
	s_waitcnt vmcnt(8)
	s_waitcnt lgkmcnt(0)
	s_barrier
	s_setprio 1
	s_waitcnt lgkmcnt(0)
	v_mfma_f32_16x16x32_bf16 v[60:63], v[136:139], v[216:219], v[60:63]
	v_mfma_f32_16x16x32_bf16 v[60:63], v[140:143], v[220:223], v[60:63]
	v_mfma_f32_16x16x32_bf16 v[56:59], v[176:179], v[220:223], v[56:59]
	v_mfma_f32_16x16x32_bf16 v[56:59], v[172:175], v[216:219], v[56:59]
	v_mfma_f32_16x16x32_bf16 v[52:55], v[180:183], v[216:219], v[52:55]
	v_mfma_f32_16x16x32_bf16 v[52:55], v[184:187], v[220:223], v[52:55]
	v_mfma_f32_16x16x32_bf16 v[44:47], v[212:215], v[220:223], v[44:47]
	v_mfma_f32_16x16x32_bf16 v[44:47], v[208:211], v[216:219], v[44:47]
	v_mfma_f32_16x16x32_bf16 v[28:31], v[208:211], v[224:227], v[28:31]
	v_mfma_f32_16x16x32_bf16 v[28:31], v[212:215], v[228:231], v[28:31]
	v_mfma_f32_16x16x32_bf16 v[36:39], v[184:187], v[228:231], v[36:39]
	v_mfma_f32_16x16x32_bf16 v[36:39], v[180:183], v[224:227], v[36:39]
	v_mfma_f32_16x16x32_bf16 v[40:43], v[172:175], v[224:227], v[40:43]
	v_mfma_f32_16x16x32_bf16 v[40:43], v[176:179], v[228:231], v[40:43]
	v_mfma_f32_16x16x32_bf16 v[48:51], v[140:143], v[228:231], v[48:51]
	v_mfma_f32_16x16x32_bf16 v[48:51], v[136:139], v[224:227], v[48:51]
	s_setprio 0
	s_setprio 1
	v_mfma_f32_16x16x32_bf16 v[32:35], v[136:139], v[232:235], v[32:35]
	v_mfma_f32_16x16x32_bf16 v[32:35], v[140:143], v[236:239], v[32:35]
	v_mfma_f32_16x16x32_bf16 v[24:27], v[176:179], v[236:239], v[24:27]
	v_mfma_f32_16x16x32_bf16 v[24:27], v[172:175], v[232:235], v[24:27]
	v_mfma_f32_16x16x32_bf16 v[20:23], v[180:183], v[232:235], v[20:23]
	v_mfma_f32_16x16x32_bf16 v[20:23], v[184:187], v[236:239], v[20:23]
	v_mfma_f32_16x16x32_bf16 v[16:19], v[212:215], v[236:239], v[16:19]
	v_mfma_f32_16x16x32_bf16 v[16:19], v[208:211], v[232:235], v[16:19]
	v_mfma_f32_16x16x32_bf16 v[0:3], v[208:211], v[240:243], v[0:3]
	v_mfma_f32_16x16x32_bf16 v[0:3], v[212:215], v[244:247], v[0:3]
	v_mfma_f32_16x16x32_bf16 v[4:7], v[184:187], v[244:247], v[4:7]
	v_mfma_f32_16x16x32_bf16 v[4:7], v[180:183], v[240:243], v[4:7]
	v_mfma_f32_16x16x32_bf16 v[8:11], v[172:175], v[240:243], v[8:11]
	v_mfma_f32_16x16x32_bf16 v[8:11], v[176:179], v[244:247], v[8:11]
	s_setprio 3
	s_barrier
	v_mfma_f32_16x16x32_bf16 v[12:15], v[140:143], v[244:247], v[12:15]
	v_mfma_f32_16x16x32_bf16 v[12:15], v[136:139], v[240:243], v[12:15]
	s_setprio 0
	s_add_i32 s71, s71, 2
	s_add_u32 s40, s40, 0x100
	s_addc_u32 s41, s41, 0
	s_add_u32 s69, s69, 0x100
	s_addc_u32 s70, s70, 0
	s_cmp_gt_u32 s71, 29
	s_cbranch_scc0 .LBB0_774
	s_and_b64 vcc, exec, s[18:19]
	s_cbranch_vccz .LBB0_777
	s_barrier

; #define PG8_STAGE(bufoff, gbase, voff) do { _Pragma("unroll") for (int _i = 0; _i < 2; ++_i) \
;         __builtin_amdgcn_global_load_lds((const unsigned*)((const char*)(gbase) + (voff)[_i]), (PG8_LAS unsigned*)(lds + (bufoff) + ldsw + _i * 8192), 16, 0, 0); } while (0)
; #define PG8_LDA(dst, b, h) do { _Pragma("unroll") for (int m = 0; m < 4; ++m) _Pragma("unroll") for (int k = 0; k < 2; ++k) dst[m][k] = *(const PG8_LAS bf16x8*)(lds + PG8_SA(b, h) + aoff + m * 2048 + k * 1024); } while (0)
; #define PG8_LDB(dst, b, h) do { _Pragma("unroll") for (int n = 0; n < 2; ++n) _Pragma("unroll") for (int k = 0; k < 2; ++k) dst[n][k] = *(const PG8_LAS bf16x8*)(lds + PG8_SB(b, h) + boff + n * 2048 + k * 1024); } while (0)
; #define PG8_MMA(ai, bj, At, Bt) do { __builtin_amdgcn_s_setprio(1); _Pragma("unroll") for (int m = 0; m < 4; ++m) _Pragma("unroll") for (int n = 0; n < 2; ++n) _Pragma("unroll") for (int k = 0; k < 2; ++k) \
;         acc[ai][bj][m][n] = __builtin_amdgcn_mfma_f32_16x16x32_bf16(Bt[n][k], At[m][k], acc[ai][bj][m][n], 0, 0, 0); __builtin_amdgcn_s_setprio(0); } while (0)
; #define PG8_WAIT_V(n) asm volatile("s_waitcnt vmcnt(" #n ")" ::: "memory")
; #define PG8_WAIT_L(n) asm volatile("s_waitcnt lgkmcnt(" #n ")" ::: "memory")
; #define PG8_BAR __builtin_amdgcn_s_barrier()
; template <class Epi, class Sched, bool ALIGN_EPI = false, bool SP2 = false>
; __device__ __forceinline__ void gemm_phase(PG8_LAS unsigned char* lds, const Gemm g, const Sched& S, const Epi& E) {
;     ...
;             const char* a1 = cA + (size_t)(t + 1) * kstep;
;             const char* a2 = last ? nA : cA + (size_t)(t + 2) * kstep; const char* b2 = last ? nB : cB + (size_t)(t + 2) * kstep;
;             const char* a3 = a2 + kstep; const char* b3 = b2 + kstep;
;             if (last && has_next) S.a_ready(nxt);
;             if constexpr (SP2) {
;             PG8_LDB(B0, 0, 0); PG8_LDB(B1, 0, 1); PG8_SCHED; PG8_LDA(At, 0, 0); PG8_STAGE(PG8_SA(1, 1), a1 + hstep, voffA);
;             PG8_WAIT_V(8); PG8_WAIT_L(0); PG8_BAR; PG8_MMA(0, 0, At, B0); PG8_MMA(0, 1, At, B1); PG8_BAR; PG8_SCHED;
;             PG8_LDA(At, 0, 1); PG8_STAGE(PG8_SB(0, 0), b2, voffB); PG8_STAGE(PG8_SB(0, 1), b2 + hstep, voffB); PG8_STAGE(PG8_SA(0, 0), a2, voffA);
;             PG8_WAIT_V(8); PG8_WAIT_L(0); PG8_BAR; PG8_MMA(1, 0, At, B0); PG8_MMA(1, 1, At, B1); PG8_BAR; PG8_SCHED;
.LBB0_837:
	ds_read_b128 v[134:137], v143
	ds_read_b128 v[146:149], v143 offset:1024
	ds_read_b128 v[150:153], v143 offset:2048
	ds_read_b128 v[154:157], v143 offset:3072
	ds_read_b128 v[172:175], v144
	ds_read_b128 v[176:179], v144 offset:1024
	ds_read_b128 v[180:183], v144 offset:2048
	ds_read_b128 v[184:187], v144 offset:3072
	s_add_u32 s44, s42, 0xffea0080
	s_addc_u32 s45, s43, -1
	s_cmpk_eq_i32 s75, 0x54
	s_cselect_b32 s53, s39, s45
	s_cselect_b32 s52, s38, s44
	s_cselect_b32 s49, s41, s35
	s_cselect_b32 s48, s40, s34
	v_lshl_add_u64 v[138:139], s[42:43], 0, v[128:129]
	s_add_i32 m0, s61, 0xc000
	ds_read_b128 v[208:211], v145
	ds_read_b128 v[212:215], v145 offset:1024
	ds_read_b128 v[216:219], v145 offset:2048
	ds_read_b128 v[220:223], v145 offset:3072
	ds_read_b128 v[224:227], v145 offset:4096
	ds_read_b128 v[228:231], v145 offset:5120
	ds_read_b128 v[232:235], v145 offset:6144
	ds_read_b128 v[236:239], v145 offset:7168
	global_load_lds_dwordx4 v[138:139], off
	v_lshl_add_u64 v[138:139], s[42:43], 0, v[130:131]
	s_add_i32 m0, s61, 0xe000
	s_nop 0
	global_load_lds_dwordx4 v[138:139], off
	s_waitcnt vmcnt(8)
	s_waitcnt lgkmcnt(0)
	s_barrier
	s_setprio 1
	s_waitcnt lgkmcnt(0)
	v_mfma_f32_16x16x32_bf16 v[124:127], v[134:137], v[208:211], v[124:127]
	v_mfma_f32_16x16x32_bf16 v[124:127], v[146:149], v[212:215], v[124:127]
	v_mfma_f32_16x16x32_bf16 v[120:123], v[154:157], v[212:215], v[120:123]
	v_mfma_f32_16x16x32_bf16 v[120:123], v[150:153], v[208:211], v[120:123]
	v_mfma_f32_16x16x32_bf16 v[108:111], v[172:175], v[208:211], v[108:111]
	v_mfma_f32_16x16x32_bf16 v[108:111], v[176:179], v[212:215], v[108:111]
	v_mfma_f32_16x16x32_bf16 v[104:107], v[184:187], v[212:215], v[104:107]
	v_mfma_f32_16x16x32_bf16 v[104:107], v[180:183], v[208:211], v[104:107]
	v_mfma_f32_16x16x32_bf16 v[96:99], v[180:183], v[216:219], v[96:99]
	v_mfma_f32_16x16x32_bf16 v[96:99], v[184:187], v[220:223], v[96:99]
	v_mfma_f32_16x16x32_bf16 v[100:103], v[176:179], v[220:223], v[100:103]
	v_mfma_f32_16x16x32_bf16 v[100:103], v[172:175], v[216:219], v[100:103]
	v_mfma_f32_16x16x32_bf16 v[112:115], v[150:153], v[216:219], v[112:115]
	v_mfma_f32_16x16x32_bf16 v[112:115], v[154:157], v[220:223], v[112:115]
	v_mfma_f32_16x16x32_bf16 v[116:119], v[146:149], v[220:223], v[116:119]
	v_mfma_f32_16x16x32_bf16 v[116:119], v[134:137], v[216:219], v[116:119]
	s_setprio 0
	s_setprio 1
	v_mfma_f32_16x16x32_bf16 v[92:95], v[134:137], v[224:227], v[92:95]
	v_mfma_f32_16x16x32_bf16 v[92:95], v[146:149], v[228:231], v[92:95]
	v_mfma_f32_16x16x32_bf16 v[88:91], v[154:157], v[228:231], v[88:91]
	v_mfma_f32_16x16x32_bf16 v[88:91], v[150:153], v[224:227], v[88:91]
	v_mfma_f32_16x16x32_bf16 v[76:79], v[172:175], v[224:227], v[76:79]
	v_mfma_f32_16x16x32_bf16 v[76:79], v[176:179], v[228:231], v[76:79]
	v_mfma_f32_16x16x32_bf16 v[72:75], v[184:187], v[228:231], v[72:75]
	v_mfma_f32_16x16x32_bf16 v[72:75], v[180:183], v[224:227], v[72:75]
	v_mfma_f32_16x16x32_bf16 v[64:67], v[180:183], v[232:235], v[64:67]
	v_mfma_f32_16x16x32_bf16 v[64:67], v[184:187], v[236:239], v[64:67]
	v_mfma_f32_16x16x32_bf16 v[68:71], v[176:179], v[236:239], v[68:71]
	v_mfma_f32_16x16x32_bf16 v[68:71], v[172:175], v[232:235], v[68:71]
	v_mfma_f32_16x16x32_bf16 v[80:83], v[150:153], v[232:235], v[80:83]
	v_mfma_f32_16x16x32_bf16 v[80:83], v[154:157], v[236:239], v[80:83]
	s_setprio 3
	s_barrier
	v_mfma_f32_16x16x32_bf16 v[84:87], v[146:149], v[236:239], v[84:87]
	v_mfma_f32_16x16x32_bf16 v[84:87], v[134:137], v[232:235], v[84:87]
	s_setprio 0
	s_add_i32 s44, s68, s60
	v_lshl_add_u64 v[138:139], s[48:49], 0, v[160:161]
	s_mov_b32 m0, s44
	ds_read_b128 v[208:211], v145 offset:16384
	ds_read_b128 v[212:215], v145 offset:17408
	ds_read_b128 v[216:219], v145 offset:18432
	ds_read_b128 v[220:223], v145 offset:19456
	ds_read_b128 v[224:227], v145 offset:20480
	ds_read_b128 v[228:231], v145 offset:21504
	ds_read_b128 v[232:235], v145 offset:22528
	ds_read_b128 v[236:239], v145 offset:23552
	global_load_lds_dwordx4 v[138:139], off
	s_add_i32 m0, s44, 0x2000
	s_add_u32 s76, s48, 0x160000
	v_lshl_add_u64 v[158:159], s[48:49], 0, v[162:163]
	s_addc_u32 s77, s49, 0
	s_add_i32 s44, s69, s60
	global_load_lds_dwordx4 v[158:159], off
	v_lshl_add_u64 v[188:189], s[76:77], 0, v[160:161]
	s_mov_b32 m0, s44
	v_lshl_add_u64 v[200:201], s[52:53], 0, v[162:163]
	global_load_lds_dwordx4 v[188:189], off
	v_lshl_add_u64 v[188:189], s[76:77], 0, v[162:163]
	s_add_i32 m0, s44, 0x2000
	s_nop 0
	global_load_lds_dwordx4 v[188:189], off
	v_lshl_add_u64 v[188:189], s[52:53], 0, v[160:161]
	s_mov_b32 m0, s61
	s_nop 0
	global_load_lds_dwordx4 v[188:189], off
	s_mov_b32 m0, s62
	s_nop 0
	global_load_lds_dwordx4 v[200:201], off
	s_waitcnt vmcnt(8)
	s_waitcnt lgkmcnt(0)
	s_barrier
; #define PG8_STAGE(bufoff, gbase, voff) do { _Pragma("unroll") for (int _i = 0; _i < 2; ++_i) \
;         __builtin_amdgcn_global_load_lds((const unsigned*)((const char*)(gbase) + (voff)[_i]), (PG8_LAS unsigned*)(lds + (bufoff) + ldsw + _i * 8192), 16, 0, 0); } while (0)
; #define PG8_LDA(dst, b, h) do { _Pragma("unroll") for (int m = 0; m < 4; ++m) _Pragma("unroll") for (int k = 0; k < 2; ++k) dst[m][k] = *(const PG8_LAS bf16x8*)(lds + PG8_SA(b, h) + aoff + m * 2048 + k * 1024); } while (0)
; #define PG8_LDB(dst, b, h) do { _Pragma("unroll") for (int n = 0; n < 2; ++n) _Pragma("unroll") for (int k = 0; k < 2; ++k) dst[n][k] = *(const PG8_LAS bf16x8*)(lds + PG8_SB(b, h) + boff + n * 2048 + k * 1024); } while (0)
; #define PG8_MMA(ai, bj, At, Bt) do { __builtin_amdgcn_s_setprio(1); _Pragma("unroll") for (int m = 0; m < 4; ++m) _Pragma("unroll") for (int n = 0; n < 2; ++n) _Pragma("unroll") for (int k = 0; k < 2; ++k) \
;         acc[ai][bj][m][n] = __builtin_amdgcn_mfma_f32_16x16x32_bf16(Bt[n][k], At[m][k], acc[ai][bj][m][n], 0, 0, 0); __builtin_amdgcn_s_setprio(0); } while (0)
; #define PG8_WAIT_V(n) asm volatile("s_waitcnt vmcnt(" #n ")" ::: "memory")
; #define PG8_WAIT_L(n) asm volatile("s_waitcnt lgkmcnt(" #n ")" ::: "memory")
; #define PG8_BAR __builtin_amdgcn_s_barrier()
; #define PG8_SCHED __builtin_amdgcn_sched_barrier(0)
; template <class Epi, class Sched, bool ALIGN_EPI = false, bool SP2 = false>
; __device__ __forceinline__ void gemm_phase(PG8_LAS unsigned char* lds, const Gemm g, const Sched& S, const Epi& E) {
;     ...
;             PG8_WAIT_V(8); PG8_WAIT_L(0); PG8_BAR; PG8_MMA(1, 0, At, B0); PG8_MMA(1, 1, At, B1); PG8_BAR; PG8_SCHED;
;             PG8_LDB(B0, 1, 0); PG8_LDB(B1, 1, 1); PG8_SCHED; PG8_LDA(At, 1, 0); PG8_STAGE(PG8_SA(0, 1), a2 + hstep, voffA);
;             PG8_WAIT_V(8); PG8_WAIT_L(0); PG8_BAR; PG8_MMA(0, 0, At, B0); PG8_MMA(0, 1, At, B1); PG8_BAR; PG8_SCHED;
	s_setprio 1
	s_waitcnt lgkmcnt(0)
	v_mfma_f32_16x16x32_bf16 v[60:63], v[134:137], v[208:211], v[60:63]
	v_mfma_f32_16x16x32_bf16 v[60:63], v[146:149], v[212:215], v[60:63]
	v_mfma_f32_16x16x32_bf16 v[56:59], v[154:157], v[212:215], v[56:59]
	v_mfma_f32_16x16x32_bf16 v[56:59], v[150:153], v[208:211], v[56:59]
	v_mfma_f32_16x16x32_bf16 v[44:47], v[172:175], v[208:211], v[44:47]
	v_mfma_f32_16x16x32_bf16 v[44:47], v[176:179], v[212:215], v[44:47]
	v_mfma_f32_16x16x32_bf16 v[40:43], v[184:187], v[212:215], v[40:43]
	v_mfma_f32_16x16x32_bf16 v[40:43], v[180:183], v[208:211], v[40:43]
	v_mfma_f32_16x16x32_bf16 v[32:35], v[180:183], v[216:219], v[32:35]
	v_mfma_f32_16x16x32_bf16 v[32:35], v[184:187], v[220:223], v[32:35]
	v_mfma_f32_16x16x32_bf16 v[36:39], v[176:179], v[220:223], v[36:39]
	v_mfma_f32_16x16x32_bf16 v[36:39], v[172:175], v[216:219], v[36:39]
	v_mfma_f32_16x16x32_bf16 v[48:51], v[150:153], v[216:219], v[48:51]
	v_mfma_f32_16x16x32_bf16 v[48:51], v[154:157], v[220:223], v[48:51]
	v_mfma_f32_16x16x32_bf16 v[52:55], v[146:149], v[220:223], v[52:55]
	v_mfma_f32_16x16x32_bf16 v[52:55], v[134:137], v[216:219], v[52:55]
	s_setprio 0
	s_setprio 1
	v_mfma_f32_16x16x32_bf16 v[28:31], v[134:137], v[224:227], v[28:31]
	v_mfma_f32_16x16x32_bf16 v[28:31], v[146:149], v[228:231], v[28:31]
	v_mfma_f32_16x16x32_bf16 v[24:27], v[154:157], v[228:231], v[24:27]
	v_mfma_f32_16x16x32_bf16 v[24:27], v[150:153], v[224:227], v[24:27]
	v_mfma_f32_16x16x32_bf16 v[12:15], v[172:175], v[224:227], v[12:15]
	v_mfma_f32_16x16x32_bf16 v[12:15], v[176:179], v[228:231], v[12:15]
	v_mfma_f32_16x16x32_bf16 v[8:11], v[184:187], v[228:231], v[8:11]
	v_mfma_f32_16x16x32_bf16 v[8:11], v[180:183], v[224:227], v[8:11]
	v_mfma_f32_16x16x32_bf16 v[0:3], v[180:183], v[232:235], v[0:3]
	v_mfma_f32_16x16x32_bf16 v[0:3], v[184:187], v[236:239], v[0:3]
	v_mfma_f32_16x16x32_bf16 v[4:7], v[176:179], v[236:239], v[4:7]
	v_mfma_f32_16x16x32_bf16 v[4:7], v[172:175], v[232:235], v[4:7]
	v_mfma_f32_16x16x32_bf16 v[16:19], v[150:153], v[232:235], v[16:19]
	v_mfma_f32_16x16x32_bf16 v[16:19], v[154:157], v[236:239], v[16:19]
	s_setprio 3
	s_barrier
	v_mfma_f32_16x16x32_bf16 v[20:23], v[146:149], v[236:239], v[20:23]
	v_mfma_f32_16x16x32_bf16 v[20:23], v[134:137], v[232:235], v[20:23]
	s_setprio 0
	s_add_i32 s44, 0, 0x18000
	s_add_i32 s45, 0, 0x1c000
	v_add_u32_e32 v154, s44, v141
	v_add_u32_e32 v165, s45, v141
	ds_read_b128 v[134:137], v154
	ds_read_b128 v[146:149], v154 offset:1024
	ds_read_b128 v[150:153], v154 offset:2048
	ds_read_b128 v[154:157], v154 offset:3072
	ds_read_b128 v[172:175], v165
	ds_read_b128 v[176:179], v165 offset:1024
	ds_read_b128 v[180:183], v165 offset:2048
	ds_read_b128 v[184:187], v165 offset:3072
	s_add_u32 s52, s52, 0x160000
	s_addc_u32 s53, s53, 0
	s_mov_b32 m0, s63
	v_lshl_add_u64 v[240:241], s[52:53], 0, v[160:161]
	ds_read_b128 v[208:211], v145 offset:32768
	ds_read_b128 v[212:215], v145 offset:33792
	ds_read_b128 v[216:219], v145 offset:34816
	ds_read_b128 v[220:223], v145 offset:35840
	ds_read_b128 v[224:227], v145 offset:36864
	ds_read_b128 v[228:231], v145 offset:37888
	ds_read_b128 v[232:235], v145 offset:38912
	ds_read_b128 v[236:239], v145 offset:39936
	global_load_lds_dwordx4 v[240:241], off
	v_lshl_add_u64 v[240:241], s[52:53], 0, v[162:163]
	s_mov_b32 m0, s64
	s_nop 0
	global_load_lds_dwordx4 v[240:241], off
	s_waitcnt vmcnt(8)
	s_waitcnt lgkmcnt(0)
	s_barrier
	s_setprio 1
	s_waitcnt lgkmcnt(0)
	v_mfma_f32_16x16x32_bf16 v[124:127], v[134:137], v[208:211], v[124:127]
	v_mfma_f32_16x16x32_bf16 v[124:127], v[146:149], v[212:215], v[124:127]
	v_mfma_f32_16x16x32_bf16 v[120:123], v[154:157], v[212:215], v[120:123]
	v_mfma_f32_16x16x32_bf16 v[120:123], v[150:153], v[208:211], v[120:123]
	v_mfma_f32_16x16x32_bf16 v[108:111], v[172:175], v[208:211], v[108:111]
	v_mfma_f32_16x16x32_bf16 v[108:111], v[176:179], v[212:215], v[108:111]
	v_mfma_f32_16x16x32_bf16 v[104:107], v[184:187], v[212:215], v[104:107]
	v_mfma_f32_16x16x32_bf16 v[104:107], v[180:183], v[208:211], v[104:107]
	v_mfma_f32_16x16x32_bf16 v[96:99], v[180:183], v[216:219], v[96:99]
	v_mfma_f32_16x16x32_bf16 v[96:99], v[184:187], v[220:223], v[96:99]
	v_mfma_f32_16x16x32_bf16 v[100:103], v[176:179], v[220:223], v[100:103]
	v_mfma_f32_16x16x32_bf16 v[100:103], v[172:175], v[216:219], v[100:103]
	v_mfma_f32_16x16x32_bf16 v[112:115], v[150:153], v[216:219], v[112:115]
	v_mfma_f32_16x16x32_bf16 v[112:115], v[154:157], v[220:223], v[112:115]
	v_mfma_f32_16x16x32_bf16 v[116:119], v[146:149], v[220:223], v[116:119]
	v_mfma_f32_16x16x32_bf16 v[116:119], v[134:137], v[216:219], v[116:119]
	s_setprio 0
	s_setprio 1
	v_mfma_f32_16x16x32_bf16 v[92:95], v[134:137], v[224:227], v[92:95]
	v_mfma_f32_16x16x32_bf16 v[92:95], v[146:149], v[228:231], v[92:95]
	v_mfma_f32_16x16x32_bf16 v[88:91], v[154:157], v[228:231], v[88:91]
	v_mfma_f32_16x16x32_bf16 v[88:91], v[150:153], v[224:227], v[88:91]
	v_mfma_f32_16x16x32_bf16 v[76:79], v[172:175], v[224:227], v[76:79]
	v_mfma_f32_16x16x32_bf16 v[76:79], v[176:179], v[228:231], v[76:79]
	v_mfma_f32_16x16x32_bf16 v[72:75], v[184:187], v[228:231], v[72:75]
	v_mfma_f32_16x16x32_bf16 v[72:75], v[180:183], v[224:227], v[72:75]
	v_mfma_f32_16x16x32_bf16 v[64:67], v[180:183], v[232:235], v[64:67]
	v_mfma_f32_16x16x32_bf16 v[64:67], v[184:187], v[236:239], v[64:67]
	v_mfma_f32_16x16x32_bf16 v[68:71], v[176:179], v[236:239], v[68:71]
	v_mfma_f32_16x16x32_bf16 v[68:71], v[172:175], v[232:235], v[68:71]
	v_mfma_f32_16x16x32_bf16 v[80:83], v[150:153], v[232:235], v[80:83]
	v_mfma_f32_16x16x32_bf16 v[80:83], v[154:157], v[236:239], v[80:83]
	s_setprio 3
	s_barrier
; #define PG8_STAGE(bufoff, gbase, voff) do { _Pragma("unroll") for (int _i = 0; _i < 2; ++_i) \
;         __builtin_amdgcn_global_load_lds((const unsigned*)((const char*)(gbase) + (voff)[_i]), (PG8_LAS unsigned*)(lds + (bufoff) + ldsw + _i * 8192), 16, 0, 0); } while (0)
; #define PG8_LDA(dst, b, h) do { _Pragma("unroll") for (int m = 0; m < 4; ++m) _Pragma("unroll") for (int k = 0; k < 2; ++k) dst[m][k] = *(const PG8_LAS bf16x8*)(lds + PG8_SA(b, h) + aoff + m * 2048 + k * 1024); } while (0)
; #define PG8_MMA(ai, bj, At, Bt) do { __builtin_amdgcn_s_setprio(1); _Pragma("unroll") for (int m = 0; m < 4; ++m) _Pragma("unroll") for (int n = 0; n < 2; ++n) _Pragma("unroll") for (int k = 0; k < 2; ++k) \
;         acc[ai][bj][m][n] = __builtin_amdgcn_mfma_f32_16x16x32_bf16(Bt[n][k], At[m][k], acc[ai][bj][m][n], 0, 0, 0); __builtin_amdgcn_s_setprio(0); } while (0)
; #define PG8_WAIT_V(n) asm volatile("s_waitcnt vmcnt(" #n ")" ::: "memory")
; #define PG8_WAIT_L(n) asm volatile("s_waitcnt lgkmcnt(" #n ")" ::: "memory")
; #define PG8_BAR __builtin_amdgcn_s_barrier()
; #define PG8_SCHED __builtin_amdgcn_sched_barrier(0)
; template <class Epi, class Sched, bool ALIGN_EPI = false, bool SP2 = false>
; __device__ __forceinline__ void gemm_phase(PG8_LAS unsigned char* lds, const Gemm g, const Sched& S, const Epi& E) {
;     ...
;         for (int t = 0; t < nt; t += 2) {
;     ...
;             PG8_LDA(At, 1, 1); PG8_STAGE(PG8_SB(1, 0), b3, voffB); PG8_STAGE(PG8_SB(1, 1), b3 + hstep, voffB); PG8_STAGE(PG8_SA(1, 0), a3, voffA);
;             PG8_WAIT_V(8); PG8_WAIT_L(0); PG8_BAR; PG8_MMA(1, 0, At, B0); PG8_MMA(1, 1, At, B1); PG8_BAR; PG8_SCHED;
	v_mfma_f32_16x16x32_bf16 v[84:87], v[146:149], v[236:239], v[84:87]
	v_mfma_f32_16x16x32_bf16 v[84:87], v[134:137], v[232:235], v[84:87]
	s_setprio 0
	s_add_i32 s44, s44, s60
	v_lshl_add_u64 v[138:139], v[138:139], 0, s[16:17]
	s_mov_b32 m0, s44
	ds_read_b128 v[208:211], v145 offset:49152
	ds_read_b128 v[212:215], v145 offset:50176
	ds_read_b128 v[216:219], v145 offset:51200
	ds_read_b128 v[220:223], v145 offset:52224
	ds_read_b128 v[224:227], v145 offset:53248
	ds_read_b128 v[228:231], v145 offset:54272
	ds_read_b128 v[232:235], v145 offset:55296
	ds_read_b128 v[236:239], v145 offset:56320
	global_load_lds_dwordx4 v[138:139], off
	s_add_i32 m0, s44, 0x2000
	s_add_u32 s48, s48, 0x160080
	v_lshl_add_u64 v[138:139], v[158:159], 0, s[16:17]
	s_addc_u32 s49, s49, 0
	s_add_i32 s44, s45, s60
	global_load_lds_dwordx4 v[138:139], off
	v_lshl_add_u64 v[138:139], s[48:49], 0, v[160:161]
	s_mov_b32 m0, s44
	s_nop 0
	global_load_lds_dwordx4 v[138:139], off
	v_lshl_add_u64 v[138:139], s[48:49], 0, v[162:163]
	s_add_i32 m0, s44, 0x2000
	s_nop 0
	global_load_lds_dwordx4 v[138:139], off
	v_lshl_add_u64 v[138:139], v[188:189], 0, s[16:17]
	s_mov_b32 m0, s65
	s_nop 0
	global_load_lds_dwordx4 v[138:139], off
	v_lshl_add_u64 v[138:139], v[200:201], 0, s[16:17]
	s_mov_b32 m0, s66
	s_nop 0
	global_load_lds_dwordx4 v[138:139], off
	s_waitcnt vmcnt(8)
	s_waitcnt lgkmcnt(0)
	s_barrier
	s_setprio 1
	s_waitcnt lgkmcnt(0)
	v_mfma_f32_16x16x32_bf16 v[60:63], v[134:137], v[208:211], v[60:63]
	v_mfma_f32_16x16x32_bf16 v[60:63], v[146:149], v[212:215], v[60:63]
	v_mfma_f32_16x16x32_bf16 v[56:59], v[154:157], v[212:215], v[56:59]
	v_mfma_f32_16x16x32_bf16 v[56:59], v[150:153], v[208:211], v[56:59]
	v_mfma_f32_16x16x32_bf16 v[44:47], v[172:175], v[208:211], v[44:47]
	v_mfma_f32_16x16x32_bf16 v[44:47], v[176:179], v[212:215], v[44:47]
	v_mfma_f32_16x16x32_bf16 v[40:43], v[184:187], v[212:215], v[40:43]
	v_mfma_f32_16x16x32_bf16 v[40:43], v[180:183], v[208:211], v[40:43]
	v_mfma_f32_16x16x32_bf16 v[32:35], v[180:183], v[216:219], v[32:35]
	v_mfma_f32_16x16x32_bf16 v[32:35], v[184:187], v[220:223], v[32:35]
	v_mfma_f32_16x16x32_bf16 v[36:39], v[176:179], v[220:223], v[36:39]
	v_mfma_f32_16x16x32_bf16 v[36:39], v[172:175], v[216:219], v[36:39]
	v_mfma_f32_16x16x32_bf16 v[48:51], v[150:153], v[216:219], v[48:51]
	v_mfma_f32_16x16x32_bf16 v[48:51], v[154:157], v[220:223], v[48:51]
	v_mfma_f32_16x16x32_bf16 v[52:55], v[146:149], v[220:223], v[52:55]
	v_mfma_f32_16x16x32_bf16 v[52:55], v[134:137], v[216:219], v[52:55]
	s_setprio 0
	s_setprio 1
	v_mfma_f32_16x16x32_bf16 v[28:31], v[134:137], v[224:227], v[28:31]
	v_mfma_f32_16x16x32_bf16 v[28:31], v[146:149], v[228:231], v[28:31]
	v_mfma_f32_16x16x32_bf16 v[24:27], v[154:157], v[228:231], v[24:27]
	v_mfma_f32_16x16x32_bf16 v[24:27], v[150:153], v[224:227], v[24:27]
	v_mfma_f32_16x16x32_bf16 v[12:15], v[172:175], v[224:227], v[12:15]
	v_mfma_f32_16x16x32_bf16 v[12:15], v[176:179], v[228:231], v[12:15]
	v_mfma_f32_16x16x32_bf16 v[8:11], v[184:187], v[228:231], v[8:11]
	v_mfma_f32_16x16x32_bf16 v[8:11], v[180:183], v[224:227], v[8:11]
	v_mfma_f32_16x16x32_bf16 v[0:3], v[180:183], v[232:235], v[0:3]
	v_mfma_f32_16x16x32_bf16 v[0:3], v[184:187], v[236:239], v[0:3]
	v_mfma_f32_16x16x32_bf16 v[4:7], v[176:179], v[236:239], v[4:7]
	v_mfma_f32_16x16x32_bf16 v[4:7], v[172:175], v[232:235], v[4:7]
	v_mfma_f32_16x16x32_bf16 v[16:19], v[150:153], v[232:235], v[16:19]
	v_mfma_f32_16x16x32_bf16 v[16:19], v[154:157], v[236:239], v[16:19]
	s_setprio 3
	s_barrier
	v_mfma_f32_16x16x32_bf16 v[20:23], v[146:149], v[236:239], v[20:23]
	v_mfma_f32_16x16x32_bf16 v[20:23], v[134:137], v[232:235], v[20:23]
	s_setprio 0
	s_add_i32 s75, s75, 2
	s_add_u32 s42, s42, 0x100
	s_addc_u32 s43, s43, 0
	s_add_u32 s34, s34, 0x100
	s_addc_u32 s35, s35, 0
	s_cmpk_gt_u32 s75, 0x55
	s_cbranch_scc0 .LBB0_837
	s_and_b64 vcc, exec, s[18:19]
	s_cbranch_vccz .LBB0_840
	s_barrier

; #define PG8_STAGE(bufoff, gbase, voff) do { _Pragma("unroll") for (int _i = 0; _i < 2; ++_i) \
;         __builtin_amdgcn_global_load_lds((const unsigned*)((const char*)(gbase) + (voff)[_i]), (PG8_LAS unsigned*)(lds + (bufoff) + ldsw + _i * 8192), 16, 0, 0); } while (0)
; #define PG8_LDA(dst, b, h) do { _Pragma("unroll") for (int m = 0; m < 4; ++m) _Pragma("unroll") for (int k = 0; k < 2; ++k) dst[m][k] = *(const PG8_LAS bf16x8*)(lds + PG8_SA(b, h) + aoff + m * 2048 + k * 1024); } while (0)
; #define PG8_LDB(dst, b, h) do { _Pragma("unroll") for (int n = 0; n < 2; ++n) _Pragma("unroll") for (int k = 0; k < 2; ++k) dst[n][k] = *(const PG8_LAS bf16x8*)(lds + PG8_SB(b, h) + boff + n * 2048 + k * 1024); } while (0)
; #define PG8_MMA(ai, bj, At, Bt) do { __builtin_amdgcn_s_setprio(1); _Pragma("unroll") for (int m = 0; m < 4; ++m) _Pragma("unroll") for (int n = 0; n < 2; ++n) _Pragma("unroll") for (int k = 0; k < 2; ++k) \
;         acc[ai][bj][m][n] = __builtin_amdgcn_mfma_f32_16x16x32_bf16(Bt[n][k], At[m][k], acc[ai][bj][m][n], 0, 0, 0); __builtin_amdgcn_s_setprio(0); } while (0)
; #define PG8_WAIT_V(n) asm volatile("s_waitcnt vmcnt(" #n ")" ::: "memory")
; #define PG8_WAIT_L(n) asm volatile("s_waitcnt lgkmcnt(" #n ")" ::: "memory")
; #define PG8_BAR __builtin_amdgcn_s_barrier()
; template <class Epi, class Sched, bool ALIGN_EPI = false, bool SP2 = false>
; __device__ __forceinline__ void gemm_phase(PG8_LAS unsigned char* lds, const Gemm g, const Sched& S, const Epi& E) {
;     ...
;             const char* a1 = cA + (size_t)(t + 1) * kstep;
;             const char* a2 = last ? nA : cA + (size_t)(t + 2) * kstep; const char* b2 = last ? nB : cB + (size_t)(t + 2) * kstep;
;             const char* a3 = a2 + kstep; const char* b3 = b2 + kstep;
;             if (last && has_next) S.a_ready(nxt);
;             if constexpr (SP2) {
;             PG8_LDB(B0, 0, 0); PG8_LDB(B1, 0, 1); PG8_SCHED; PG8_LDA(At, 0, 0); PG8_STAGE(PG8_SA(1, 1), a1 + hstep, voffA);
;             PG8_WAIT_V(8); PG8_WAIT_L(0); PG8_BAR; PG8_MMA(0, 0, At, B0); PG8_MMA(0, 1, At, B1); PG8_BAR; PG8_SCHED;
;             PG8_LDA(At, 0, 1); PG8_STAGE(PG8_SB(0, 0), b2, voffB); PG8_STAGE(PG8_SB(0, 1), b2 + hstep, voffB); PG8_STAGE(PG8_SA(0, 0), a2, voffA);
;             PG8_WAIT_V(8); PG8_WAIT_L(0); PG8_BAR; PG8_MMA(1, 0, At, B0); PG8_MMA(1, 1, At, B1); PG8_BAR; PG8_SCHED;
.LBB0_880:
	ds_read_b128 v[136:139], v156
	ds_read_b128 v[140:143], v156 offset:1024
	ds_read_b128 v[172:175], v156 offset:2048
	ds_read_b128 v[176:179], v156 offset:3072
	ds_read_b128 v[180:183], v157
	ds_read_b128 v[184:187], v157 offset:1024
	ds_read_b128 v[196:199], v157 offset:2048
	ds_read_b128 v[208:211], v157 offset:3072
	s_add_u32 s40, s38, 0xfff80080
	s_addc_u32 s41, s39, -1
	s_cmp_eq_u32 s63, 28
	s_cselect_b32 s43, s19, s41
	s_cselect_b32 s42, s34, s40
	s_cselect_b32 s41, s21, s62
	s_cselect_b32 s40, s35, s61
	v_lshl_add_u64 v[188:189], s[38:39], 0, v[128:129]
	s_add_i32 m0, s7, 0xc000
	ds_read_b128 v[212:215], v158
	ds_read_b128 v[216:219], v158 offset:1024
	ds_read_b128 v[220:223], v158 offset:2048
	ds_read_b128 v[224:227], v158 offset:3072
	ds_read_b128 v[228:231], v158 offset:4096
	ds_read_b128 v[232:235], v158 offset:5120
	ds_read_b128 v[236:239], v158 offset:6144
	ds_read_b128 v[240:243], v158 offset:7168
	global_load_lds_dwordx4 v[188:189], off
	v_lshl_add_u64 v[188:189], s[38:39], 0, v[130:131]
	s_add_i32 m0, s7, 0xe000
	s_nop 0
	global_load_lds_dwordx4 v[188:189], off
	s_waitcnt vmcnt(8)
	s_waitcnt lgkmcnt(0)
	s_barrier
	s_setprio 1
	s_waitcnt lgkmcnt(0)
	v_mfma_f32_16x16x32_bf16 v[124:127], v[136:139], v[212:215], v[124:127]
	v_mfma_f32_16x16x32_bf16 v[124:127], v[140:143], v[216:219], v[124:127]
	v_mfma_f32_16x16x32_bf16 v[120:123], v[176:179], v[216:219], v[120:123]
	v_mfma_f32_16x16x32_bf16 v[120:123], v[172:175], v[212:215], v[120:123]
	v_mfma_f32_16x16x32_bf16 v[116:119], v[180:183], v[212:215], v[116:119]
	v_mfma_f32_16x16x32_bf16 v[116:119], v[184:187], v[216:219], v[116:119]
	v_mfma_f32_16x16x32_bf16 v[112:115], v[208:211], v[216:219], v[112:115]
	v_mfma_f32_16x16x32_bf16 v[112:115], v[196:199], v[212:215], v[112:115]
	v_mfma_f32_16x16x32_bf16 v[92:95], v[196:199], v[220:223], v[92:95]
	v_mfma_f32_16x16x32_bf16 v[92:95], v[208:211], v[224:227], v[92:95]
	v_mfma_f32_16x16x32_bf16 v[100:103], v[184:187], v[224:227], v[100:103]
	v_mfma_f32_16x16x32_bf16 v[100:103], v[180:183], v[220:223], v[100:103]
	v_mfma_f32_16x16x32_bf16 v[104:107], v[172:175], v[220:223], v[104:107]
	v_mfma_f32_16x16x32_bf16 v[104:107], v[176:179], v[224:227], v[104:107]
	v_mfma_f32_16x16x32_bf16 v[108:111], v[140:143], v[224:227], v[108:111]
	v_mfma_f32_16x16x32_bf16 v[108:111], v[136:139], v[220:223], v[108:111]
	s_setprio 0
	s_setprio 1
	v_mfma_f32_16x16x32_bf16 v[96:99], v[136:139], v[228:231], v[96:99]
	v_mfma_f32_16x16x32_bf16 v[96:99], v[140:143], v[232:235], v[96:99]
	v_mfma_f32_16x16x32_bf16 v[88:91], v[176:179], v[232:235], v[88:91]
	v_mfma_f32_16x16x32_bf16 v[88:91], v[172:175], v[228:231], v[88:91]
	v_mfma_f32_16x16x32_bf16 v[84:87], v[180:183], v[228:231], v[84:87]
	v_mfma_f32_16x16x32_bf16 v[84:87], v[184:187], v[232:235], v[84:87]
	v_mfma_f32_16x16x32_bf16 v[76:79], v[208:211], v[232:235], v[76:79]
	v_mfma_f32_16x16x32_bf16 v[76:79], v[196:199], v[228:231], v[76:79]
	v_mfma_f32_16x16x32_bf16 v[64:67], v[196:199], v[236:239], v[64:67]
	v_mfma_f32_16x16x32_bf16 v[64:67], v[208:211], v[240:243], v[64:67]
	v_mfma_f32_16x16x32_bf16 v[68:71], v[184:187], v[240:243], v[68:71]
	v_mfma_f32_16x16x32_bf16 v[68:71], v[180:183], v[236:239], v[68:71]
	v_mfma_f32_16x16x32_bf16 v[72:75], v[172:175], v[236:239], v[72:75]
	v_mfma_f32_16x16x32_bf16 v[72:75], v[176:179], v[240:243], v[72:75]
	s_setprio 3
	s_barrier
	v_mfma_f32_16x16x32_bf16 v[80:83], v[140:143], v[240:243], v[80:83]
	v_mfma_f32_16x16x32_bf16 v[80:83], v[136:139], v[236:239], v[80:83]
	s_setprio 0
	s_add_i32 s44, s52, s33
	v_lshl_add_u64 v[188:189], s[40:41], 0, v[166:167]
	s_mov_b32 m0, s44
	ds_read_b128 v[212:215], v158 offset:16384
	ds_read_b128 v[216:219], v158 offset:17408
	ds_read_b128 v[220:223], v158 offset:18432
	ds_read_b128 v[224:227], v158 offset:19456
	ds_read_b128 v[228:231], v158 offset:20480
	ds_read_b128 v[232:235], v158 offset:21504
	ds_read_b128 v[236:239], v158 offset:22528
	ds_read_b128 v[240:243], v158 offset:23552
	global_load_lds_dwordx4 v[188:189], off
	s_add_i32 m0, s44, 0x2000
	s_add_u32 s64, s40, 0x80000
	v_lshl_add_u64 v[200:201], s[40:41], 0, v[170:171]
	s_addc_u32 s65, s41, 0
	s_add_i32 s44, s53, s33
	global_load_lds_dwordx4 v[200:201], off
	v_lshl_add_u64 v[244:245], s[64:65], 0, v[166:167]
	s_mov_b32 m0, s44
	v_lshl_add_u64 v[246:247], s[42:43], 0, v[168:169]
	global_load_lds_dwordx4 v[244:245], off
	v_lshl_add_u64 v[244:245], s[64:65], 0, v[170:171]
	s_add_i32 m0, s44, 0x2000
	s_nop 0
	global_load_lds_dwordx4 v[244:245], off
	v_lshl_add_u64 v[244:245], s[42:43], 0, v[164:165]
	s_mov_b32 m0, s7
	s_nop 0
	global_load_lds_dwordx4 v[244:245], off
	s_mov_b32 m0, s37
	s_nop 0
	global_load_lds_dwordx4 v[246:247], off
	s_waitcnt vmcnt(8)
	s_waitcnt lgkmcnt(0)
	s_barrier
; #define PG8_STAGE(bufoff, gbase, voff) do { _Pragma("unroll") for (int _i = 0; _i < 2; ++_i) \
;         __builtin_amdgcn_global_load_lds((const unsigned*)((const char*)(gbase) + (voff)[_i]), (PG8_LAS unsigned*)(lds + (bufoff) + ldsw + _i * 8192), 16, 0, 0); } while (0)
; #define PG8_LDA(dst, b, h) do { _Pragma("unroll") for (int m = 0; m < 4; ++m) _Pragma("unroll") for (int k = 0; k < 2; ++k) dst[m][k] = *(const PG8_LAS bf16x8*)(lds + PG8_SA(b, h) + aoff + m * 2048 + k * 1024); } while (0)
; #define PG8_LDB(dst, b, h) do { _Pragma("unroll") for (int n = 0; n < 2; ++n) _Pragma("unroll") for (int k = 0; k < 2; ++k) dst[n][k] = *(const PG8_LAS bf16x8*)(lds + PG8_SB(b, h) + boff + n * 2048 + k * 1024); } while (0)
; #define PG8_MMA(ai, bj, At, Bt) do { __builtin_amdgcn_s_setprio(1); _Pragma("unroll") for (int m = 0; m < 4; ++m) _Pragma("unroll") for (int n = 0; n < 2; ++n) _Pragma("unroll") for (int k = 0; k < 2; ++k) \
;         acc[ai][bj][m][n] = __builtin_amdgcn_mfma_f32_16x16x32_bf16(Bt[n][k], At[m][k], acc[ai][bj][m][n], 0, 0, 0); __builtin_amdgcn_s_setprio(0); } while (0)
; #define PG8_WAIT_V(n) asm volatile("s_waitcnt vmcnt(" #n ")" ::: "memory")
; #define PG8_WAIT_L(n) asm volatile("s_waitcnt lgkmcnt(" #n ")" ::: "memory")
; #define PG8_BAR __builtin_amdgcn_s_barrier()
; #define PG8_SCHED __builtin_amdgcn_sched_barrier(0)
; template <class Epi, class Sched, bool ALIGN_EPI = false, bool SP2 = false>
; __device__ __forceinline__ void gemm_phase(PG8_LAS unsigned char* lds, const Gemm g, const Sched& S, const Epi& E) {
;     ...
;             PG8_WAIT_V(8); PG8_WAIT_L(0); PG8_BAR; PG8_MMA(1, 0, At, B0); PG8_MMA(1, 1, At, B1); PG8_BAR; PG8_SCHED;
;             PG8_LDB(B0, 1, 0); PG8_LDB(B1, 1, 1); PG8_SCHED; PG8_LDA(At, 1, 0); PG8_STAGE(PG8_SA(0, 1), a2 + hstep, voffA);
;             PG8_WAIT_V(8); PG8_WAIT_L(0); PG8_BAR; PG8_MMA(0, 0, At, B0); PG8_MMA(0, 1, At, B1); PG8_BAR; PG8_SCHED;
	s_setprio 1
	s_waitcnt lgkmcnt(0)
	v_mfma_f32_16x16x32_bf16 v[60:63], v[136:139], v[212:215], v[60:63]
	v_mfma_f32_16x16x32_bf16 v[60:63], v[140:143], v[216:219], v[60:63]
	v_mfma_f32_16x16x32_bf16 v[56:59], v[176:179], v[216:219], v[56:59]
	v_mfma_f32_16x16x32_bf16 v[56:59], v[172:175], v[212:215], v[56:59]
	v_mfma_f32_16x16x32_bf16 v[52:55], v[180:183], v[212:215], v[52:55]
	v_mfma_f32_16x16x32_bf16 v[52:55], v[184:187], v[216:219], v[52:55]
	v_mfma_f32_16x16x32_bf16 v[44:47], v[208:211], v[216:219], v[44:47]
	v_mfma_f32_16x16x32_bf16 v[44:47], v[196:199], v[212:215], v[44:47]
	v_mfma_f32_16x16x32_bf16 v[28:31], v[196:199], v[220:223], v[28:31]
	v_mfma_f32_16x16x32_bf16 v[28:31], v[208:211], v[224:227], v[28:31]
	v_mfma_f32_16x16x32_bf16 v[36:39], v[184:187], v[224:227], v[36:39]
	v_mfma_f32_16x16x32_bf16 v[36:39], v[180:183], v[220:223], v[36:39]
	v_mfma_f32_16x16x32_bf16 v[40:43], v[172:175], v[220:223], v[40:43]
	v_mfma_f32_16x16x32_bf16 v[40:43], v[176:179], v[224:227], v[40:43]
	v_mfma_f32_16x16x32_bf16 v[48:51], v[140:143], v[224:227], v[48:51]
	v_mfma_f32_16x16x32_bf16 v[48:51], v[136:139], v[220:223], v[48:51]
	s_setprio 0
	s_setprio 1
	v_mfma_f32_16x16x32_bf16 v[32:35], v[136:139], v[228:231], v[32:35]
	v_mfma_f32_16x16x32_bf16 v[32:35], v[140:143], v[232:235], v[32:35]
	v_mfma_f32_16x16x32_bf16 v[24:27], v[176:179], v[232:235], v[24:27]
	v_mfma_f32_16x16x32_bf16 v[24:27], v[172:175], v[228:231], v[24:27]
	v_mfma_f32_16x16x32_bf16 v[20:23], v[180:183], v[228:231], v[20:23]
	v_mfma_f32_16x16x32_bf16 v[20:23], v[184:187], v[232:235], v[20:23]
	v_mfma_f32_16x16x32_bf16 v[16:19], v[208:211], v[232:235], v[16:19]
	v_mfma_f32_16x16x32_bf16 v[16:19], v[196:199], v[228:231], v[16:19]
	v_mfma_f32_16x16x32_bf16 v[0:3], v[196:199], v[236:239], v[0:3]
	v_mfma_f32_16x16x32_bf16 v[0:3], v[208:211], v[240:243], v[0:3]
	v_mfma_f32_16x16x32_bf16 v[4:7], v[184:187], v[240:243], v[4:7]
	v_mfma_f32_16x16x32_bf16 v[4:7], v[180:183], v[236:239], v[4:7]
	v_mfma_f32_16x16x32_bf16 v[8:11], v[172:175], v[236:239], v[8:11]
	v_mfma_f32_16x16x32_bf16 v[8:11], v[176:179], v[240:243], v[8:11]
	s_setprio 3
	s_barrier
	v_mfma_f32_16x16x32_bf16 v[12:15], v[140:143], v[240:243], v[12:15]
	v_mfma_f32_16x16x32_bf16 v[12:15], v[136:139], v[236:239], v[12:15]
	s_setprio 0
	s_add_i32 s44, 0, 0x18000
	v_add_u32_e32 v144, s44, v146
	s_add_i32 s45, 0, 0x1c000
	ds_read_b128 v[136:139], v144
	ds_read_b128 v[140:143], v144 offset:1024
	ds_read_b128 v[172:175], v144 offset:2048
	ds_read_b128 v[176:179], v144 offset:3072
	v_add_u32_e32 v144, s45, v146
	ds_read_b128 v[180:183], v144
	ds_read_b128 v[184:187], v144 offset:1024
	ds_read_b128 v[196:199], v144 offset:2048
	ds_read_b128 v[208:211], v144 offset:3072
	s_add_u32 s42, s42, 0x80000
	s_addc_u32 s43, s43, 0
	s_mov_b32 m0, s48
	v_lshl_add_u64 v[248:249], s[42:43], 0, v[164:165]
	ds_read_b128 v[212:215], v158 offset:32768
	ds_read_b128 v[216:219], v158 offset:33792
	ds_read_b128 v[220:223], v158 offset:34816
	ds_read_b128 v[224:227], v158 offset:35840
	ds_read_b128 v[228:231], v158 offset:36864
	ds_read_b128 v[232:235], v158 offset:37888
	ds_read_b128 v[236:239], v158 offset:38912
	ds_read_b128 v[240:243], v158 offset:39936
	global_load_lds_dwordx4 v[248:249], off
	v_lshl_add_u64 v[248:249], s[42:43], 0, v[168:169]
	s_mov_b32 m0, s49
	s_nop 0
	global_load_lds_dwordx4 v[248:249], off
	s_waitcnt vmcnt(8)
	s_waitcnt lgkmcnt(0)
	s_barrier
	s_setprio 1
	s_waitcnt lgkmcnt(0)
	v_mfma_f32_16x16x32_bf16 v[124:127], v[136:139], v[212:215], v[124:127]
	v_mfma_f32_16x16x32_bf16 v[124:127], v[140:143], v[216:219], v[124:127]
	v_mfma_f32_16x16x32_bf16 v[120:123], v[176:179], v[216:219], v[120:123]
	v_mfma_f32_16x16x32_bf16 v[120:123], v[172:175], v[212:215], v[120:123]
	v_mfma_f32_16x16x32_bf16 v[116:119], v[180:183], v[212:215], v[116:119]
	v_mfma_f32_16x16x32_bf16 v[116:119], v[184:187], v[216:219], v[116:119]
	v_mfma_f32_16x16x32_bf16 v[112:115], v[208:211], v[216:219], v[112:115]
	v_mfma_f32_16x16x32_bf16 v[112:115], v[196:199], v[212:215], v[112:115]
	v_mfma_f32_16x16x32_bf16 v[92:95], v[196:199], v[220:223], v[92:95]
	v_mfma_f32_16x16x32_bf16 v[92:95], v[208:211], v[224:227], v[92:95]
	v_mfma_f32_16x16x32_bf16 v[100:103], v[184:187], v[224:227], v[100:103]
	v_mfma_f32_16x16x32_bf16 v[100:103], v[180:183], v[220:223], v[100:103]
	v_mfma_f32_16x16x32_bf16 v[104:107], v[172:175], v[220:223], v[104:107]
	v_mfma_f32_16x16x32_bf16 v[104:107], v[176:179], v[224:227], v[104:107]
	v_mfma_f32_16x16x32_bf16 v[108:111], v[140:143], v[224:227], v[108:111]
	v_mfma_f32_16x16x32_bf16 v[108:111], v[136:139], v[220:223], v[108:111]
	s_setprio 0
	s_setprio 1
	v_mfma_f32_16x16x32_bf16 v[96:99], v[136:139], v[228:231], v[96:99]
	v_mfma_f32_16x16x32_bf16 v[96:99], v[140:143], v[232:235], v[96:99]
	v_mfma_f32_16x16x32_bf16 v[88:91], v[176:179], v[232:235], v[88:91]
	v_mfma_f32_16x16x32_bf16 v[88:91], v[172:175], v[228:231], v[88:91]
	v_mfma_f32_16x16x32_bf16 v[84:87], v[180:183], v[228:231], v[84:87]
	v_mfma_f32_16x16x32_bf16 v[84:87], v[184:187], v[232:235], v[84:87]
	v_mfma_f32_16x16x32_bf16 v[76:79], v[208:211], v[232:235], v[76:79]
	v_mfma_f32_16x16x32_bf16 v[76:79], v[196:199], v[228:231], v[76:79]
	v_mfma_f32_16x16x32_bf16 v[64:67], v[196:199], v[236:239], v[64:67]
	v_mfma_f32_16x16x32_bf16 v[64:67], v[208:211], v[240:243], v[64:67]
	v_mfma_f32_16x16x32_bf16 v[68:71], v[184:187], v[240:243], v[68:71]
	v_mfma_f32_16x16x32_bf16 v[68:71], v[180:183], v[236:239], v[68:71]
	v_mfma_f32_16x16x32_bf16 v[72:75], v[172:175], v[236:239], v[72:75]
	v_mfma_f32_16x16x32_bf16 v[72:75], v[176:179], v[240:243], v[72:75]
	s_setprio 3
	s_barrier
; #define PG8_STAGE(bufoff, gbase, voff) do { _Pragma("unroll") for (int _i = 0; _i < 2; ++_i) \
;         __builtin_amdgcn_global_load_lds((const unsigned*)((const char*)(gbase) + (voff)[_i]), (PG8_LAS unsigned*)(lds + (bufoff) + ldsw + _i * 8192), 16, 0, 0); } while (0)
; #define PG8_LDA(dst, b, h) do { _Pragma("unroll") for (int m = 0; m < 4; ++m) _Pragma("unroll") for (int k = 0; k < 2; ++k) dst[m][k] = *(const PG8_LAS bf16x8*)(lds + PG8_SA(b, h) + aoff + m * 2048 + k * 1024); } while (0)
; #define PG8_MMA(ai, bj, At, Bt) do { __builtin_amdgcn_s_setprio(1); _Pragma("unroll") for (int m = 0; m < 4; ++m) _Pragma("unroll") for (int n = 0; n < 2; ++n) _Pragma("unroll") for (int k = 0; k < 2; ++k) \
;         acc[ai][bj][m][n] = __builtin_amdgcn_mfma_f32_16x16x32_bf16(Bt[n][k], At[m][k], acc[ai][bj][m][n], 0, 0, 0); __builtin_amdgcn_s_setprio(0); } while (0)
; #define PG8_WAIT_V(n) asm volatile("s_waitcnt vmcnt(" #n ")" ::: "memory")
; #define PG8_WAIT_L(n) asm volatile("s_waitcnt lgkmcnt(" #n ")" ::: "memory")
; #define PG8_BAR __builtin_amdgcn_s_barrier()
; #define PG8_SCHED __builtin_amdgcn_sched_barrier(0)
; template <class Epi, class Sched, bool ALIGN_EPI = false, bool SP2 = false>
; __device__ __forceinline__ void gemm_phase(PG8_LAS unsigned char* lds, const Gemm g, const Sched& S, const Epi& E) {
;     ...
;         for (int t = 0; t < nt; t += 2) {
;     ...
;             PG8_LDA(At, 1, 1); PG8_STAGE(PG8_SB(1, 0), b3, voffB); PG8_STAGE(PG8_SB(1, 1), b3 + hstep, voffB); PG8_STAGE(PG8_SA(1, 0), a3, voffA);
;             PG8_WAIT_V(8); PG8_WAIT_L(0); PG8_BAR; PG8_MMA(1, 0, At, B0); PG8_MMA(1, 1, At, B1); PG8_BAR; PG8_SCHED;
	v_mfma_f32_16x16x32_bf16 v[80:83], v[140:143], v[240:243], v[80:83]
	v_mfma_f32_16x16x32_bf16 v[80:83], v[136:139], v[236:239], v[80:83]
	s_setprio 0
	s_add_i32 s42, s44, s33
	v_lshl_add_u64 v[188:189], v[188:189], 0, s[14:15]
	s_mov_b32 m0, s42
	ds_read_b128 v[212:215], v158 offset:49152
	ds_read_b128 v[216:219], v158 offset:50176
	ds_read_b128 v[220:223], v158 offset:51200
	ds_read_b128 v[224:227], v158 offset:52224
	ds_read_b128 v[228:231], v158 offset:53248
	ds_read_b128 v[232:235], v158 offset:54272
	ds_read_b128 v[236:239], v158 offset:55296
	ds_read_b128 v[240:243], v158 offset:56320
	global_load_lds_dwordx4 v[188:189], off
	s_add_i32 m0, s42, 0x2000
	s_add_u32 s40, s40, 0x80080
	v_lshl_add_u64 v[188:189], v[200:201], 0, s[14:15]
	s_addc_u32 s41, s41, 0
	s_add_i32 s42, s45, s33
	global_load_lds_dwordx4 v[188:189], off
	v_lshl_add_u64 v[188:189], s[40:41], 0, v[166:167]
	s_mov_b32 m0, s42
	s_nop 0
	global_load_lds_dwordx4 v[188:189], off
	v_lshl_add_u64 v[188:189], s[40:41], 0, v[170:171]
	s_add_i32 m0, s42, 0x2000
	s_nop 0
	global_load_lds_dwordx4 v[188:189], off
	v_lshl_add_u64 v[188:189], v[244:245], 0, s[14:15]
	s_mov_b32 m0, s50
	s_nop 0
	global_load_lds_dwordx4 v[188:189], off
	v_lshl_add_u64 v[188:189], v[246:247], 0, s[14:15]
	s_mov_b32 m0, s51
	s_nop 0
	global_load_lds_dwordx4 v[188:189], off
	s_waitcnt vmcnt(8)
	s_waitcnt lgkmcnt(0)
	s_barrier
	s_setprio 1
	s_waitcnt lgkmcnt(0)
	v_mfma_f32_16x16x32_bf16 v[60:63], v[136:139], v[212:215], v[60:63]
	v_mfma_f32_16x16x32_bf16 v[60:63], v[140:143], v[216:219], v[60:63]
	v_mfma_f32_16x16x32_bf16 v[56:59], v[176:179], v[216:219], v[56:59]
	v_mfma_f32_16x16x32_bf16 v[56:59], v[172:175], v[212:215], v[56:59]
	v_mfma_f32_16x16x32_bf16 v[52:55], v[180:183], v[212:215], v[52:55]
	v_mfma_f32_16x16x32_bf16 v[52:55], v[184:187], v[216:219], v[52:55]
	v_mfma_f32_16x16x32_bf16 v[44:47], v[208:211], v[216:219], v[44:47]
	v_mfma_f32_16x16x32_bf16 v[44:47], v[196:199], v[212:215], v[44:47]
	v_mfma_f32_16x16x32_bf16 v[28:31], v[196:199], v[220:223], v[28:31]
	v_mfma_f32_16x16x32_bf16 v[28:31], v[208:211], v[224:227], v[28:31]
	v_mfma_f32_16x16x32_bf16 v[36:39], v[184:187], v[224:227], v[36:39]
	v_mfma_f32_16x16x32_bf16 v[36:39], v[180:183], v[220:223], v[36:39]
	v_mfma_f32_16x16x32_bf16 v[40:43], v[172:175], v[220:223], v[40:43]
	v_mfma_f32_16x16x32_bf16 v[40:43], v[176:179], v[224:227], v[40:43]
	v_mfma_f32_16x16x32_bf16 v[48:51], v[140:143], v[224:227], v[48:51]
	v_mfma_f32_16x16x32_bf16 v[48:51], v[136:139], v[220:223], v[48:51]
	s_setprio 0
	s_setprio 1
	v_mfma_f32_16x16x32_bf16 v[32:35], v[136:139], v[228:231], v[32:35]
	v_mfma_f32_16x16x32_bf16 v[32:35], v[140:143], v[232:235], v[32:35]
	v_mfma_f32_16x16x32_bf16 v[24:27], v[176:179], v[232:235], v[24:27]
	v_mfma_f32_16x16x32_bf16 v[24:27], v[172:175], v[228:231], v[24:27]
	v_mfma_f32_16x16x32_bf16 v[20:23], v[180:183], v[228:231], v[20:23]
	v_mfma_f32_16x16x32_bf16 v[20:23], v[184:187], v[232:235], v[20:23]
	v_mfma_f32_16x16x32_bf16 v[16:19], v[208:211], v[232:235], v[16:19]
	v_mfma_f32_16x16x32_bf16 v[16:19], v[196:199], v[228:231], v[16:19]
	v_mfma_f32_16x16x32_bf16 v[0:3], v[196:199], v[236:239], v[0:3]
	v_mfma_f32_16x16x32_bf16 v[0:3], v[208:211], v[240:243], v[0:3]
	v_mfma_f32_16x16x32_bf16 v[4:7], v[184:187], v[240:243], v[4:7]
	v_mfma_f32_16x16x32_bf16 v[4:7], v[180:183], v[236:239], v[4:7]
	v_mfma_f32_16x16x32_bf16 v[8:11], v[172:175], v[236:239], v[8:11]
	v_mfma_f32_16x16x32_bf16 v[8:11], v[176:179], v[240:243], v[8:11]
	s_setprio 3
	s_barrier
	v_mfma_f32_16x16x32_bf16 v[12:15], v[140:143], v[240:243], v[12:15]
	v_mfma_f32_16x16x32_bf16 v[12:15], v[136:139], v[236:239], v[12:15]
	s_setprio 0
	s_add_i32 s63, s63, 2
	s_add_u32 s38, s38, 0x100
	s_addc_u32 s39, s39, 0
	s_add_u32 s61, s61, 0x100
	s_addc_u32 s62, s62, 0
	s_cmp_gt_u32 s63, 29
	s_cbranch_scc0 .LBB0_880
	s_and_b64 vcc, exec, s[16:17]
	s_cbranch_vccz .LBB0_883
	s_barrier

; #define PG8_STAGE(bufoff, gbase, voff) do { _Pragma("unroll") for (int _i = 0; _i < 2; ++_i) \
;         __builtin_amdgcn_global_load_lds((const unsigned*)((const char*)(gbase) + (voff)[_i]), (PG8_LAS unsigned*)(lds + (bufoff) + ldsw + _i * 8192), 16, 0, 0); } while (0)
; #define PG8_LDA(dst, b, h) do { _Pragma("unroll") for (int m = 0; m < 4; ++m) _Pragma("unroll") for (int k = 0; k < 2; ++k) dst[m][k] = *(const PG8_LAS bf16x8*)(lds + PG8_SA(b, h) + aoff + m * 2048 + k * 1024); } while (0)
; #define PG8_LDB(dst, b, h) do { _Pragma("unroll") for (int n = 0; n < 2; ++n) _Pragma("unroll") for (int k = 0; k < 2; ++k) dst[n][k] = *(const PG8_LAS bf16x8*)(lds + PG8_SB(b, h) + boff + n * 2048 + k * 1024); } while (0)
; #define PG8_MMA(ai, bj, At, Bt) do { __builtin_amdgcn_s_setprio(1); _Pragma("unroll") for (int m = 0; m < 4; ++m) _Pragma("unroll") for (int n = 0; n < 2; ++n) _Pragma("unroll") for (int k = 0; k < 2; ++k) \
;         acc[ai][bj][m][n] = __builtin_amdgcn_mfma_f32_16x16x32_bf16(Bt[n][k], At[m][k], acc[ai][bj][m][n], 0, 0, 0); __builtin_amdgcn_s_setprio(0); } while (0)
; #define PG8_WAIT_V(n) asm volatile("s_waitcnt vmcnt(" #n ")" ::: "memory")
; #define PG8_WAIT_L(n) asm volatile("s_waitcnt lgkmcnt(" #n ")" ::: "memory")
; #define PG8_BAR __builtin_amdgcn_s_barrier()
; template <class Epi, class Sched, bool ALIGN_EPI = false, bool SP2 = false>
; __device__ __forceinline__ void gemm_phase(PG8_LAS unsigned char* lds, const Gemm g, const Sched& S, const Epi& E) {
;     ...
;             const char* a1 = cA + (size_t)(t + 1) * kstep;
;             const char* a2 = last ? nA : cA + (size_t)(t + 2) * kstep; const char* b2 = last ? nB : cB + (size_t)(t + 2) * kstep;
;             const char* a3 = a2 + kstep; const char* b3 = b2 + kstep;
;             if (last && has_next) S.a_ready(nxt);
;             if constexpr (SP2) {
;             PG8_LDB(B0, 0, 0); PG8_LDB(B1, 0, 1); PG8_SCHED; PG8_LDA(At, 0, 0); PG8_STAGE(PG8_SA(1, 1), a1 + hstep, voffA);
;             PG8_WAIT_V(8); PG8_WAIT_L(0); PG8_BAR; PG8_MMA(0, 0, At, B0); PG8_MMA(0, 1, At, B1); PG8_BAR; PG8_SCHED;
;             PG8_LDA(At, 0, 1); PG8_STAGE(PG8_SB(0, 0), b2, voffB); PG8_STAGE(PG8_SB(0, 1), b2 + hstep, voffB); PG8_STAGE(PG8_SA(0, 0), a2, voffA);
;             PG8_WAIT_V(8); PG8_WAIT_L(0); PG8_BAR; PG8_MMA(1, 0, At, B0); PG8_MMA(1, 1, At, B1); PG8_BAR; PG8_SCHED;
.LBB0_937:
	ds_read_b128 v[128:131], v199
	ds_read_b128 v[132:135], v199 offset:1024
	ds_read_b128 v[136:139], v199 offset:2048
	ds_read_b128 v[140:143], v199 offset:3072
	ds_read_b128 v[150:153], v200
	ds_read_b128 v[154:157], v200 offset:1024
	ds_read_b128 v[164:167], v200 offset:2048
	ds_read_b128 v[168:171], v200 offset:3072
	s_add_u32 s22, s20, 0xffea0080
	s_addc_u32 s23, s21, -1
	s_cmpk_eq_i32 s49, 0x54
	s_cselect_b32 s25, s17, s23
	s_cselect_b32 s24, s16, s22
	s_cselect_b32 s23, s19, s48
	s_cselect_b32 s22, s18, s47
	v_lshl_add_u64 v[158:159], s[20:21], 0, v[144:145]
	s_add_i32 m0, s31, 0xc000
	ds_read_b128 v[172:175], v201
	ds_read_b128 v[176:179], v201 offset:1024
	ds_read_b128 v[180:183], v201 offset:2048
	ds_read_b128 v[184:187], v201 offset:3072
	ds_read_b128 v[188:191], v201 offset:4096
	ds_read_b128 v[204:207], v201 offset:5120
	ds_read_b128 v[208:211], v201 offset:6144
	ds_read_b128 v[212:215], v201 offset:7168
	global_load_lds_dwordx4 v[158:159], off
	v_lshl_add_u64 v[158:159], s[20:21], 0, v[146:147]
	s_add_i32 m0, s31, 0xe000
	s_nop 0
	global_load_lds_dwordx4 v[158:159], off
	s_waitcnt vmcnt(8)
	s_waitcnt lgkmcnt(0)
	s_barrier
	s_setprio 1
	s_waitcnt lgkmcnt(0)
	v_mfma_f32_16x16x32_bf16 v[124:127], v[128:131], v[172:175], v[124:127]
	v_mfma_f32_16x16x32_bf16 v[124:127], v[132:135], v[176:179], v[124:127]
	v_mfma_f32_16x16x32_bf16 v[120:123], v[140:143], v[176:179], v[120:123]
	v_mfma_f32_16x16x32_bf16 v[120:123], v[136:139], v[172:175], v[120:123]
	v_mfma_f32_16x16x32_bf16 v[116:119], v[150:153], v[172:175], v[116:119]
	v_mfma_f32_16x16x32_bf16 v[116:119], v[154:157], v[176:179], v[116:119]
	v_mfma_f32_16x16x32_bf16 v[112:115], v[168:171], v[176:179], v[112:115]
	v_mfma_f32_16x16x32_bf16 v[112:115], v[164:167], v[172:175], v[112:115]
	v_mfma_f32_16x16x32_bf16 v[96:99], v[164:167], v[180:183], v[96:99]
	v_mfma_f32_16x16x32_bf16 v[96:99], v[168:171], v[184:187], v[96:99]
	v_mfma_f32_16x16x32_bf16 v[100:103], v[154:157], v[184:187], v[100:103]
	v_mfma_f32_16x16x32_bf16 v[100:103], v[150:153], v[180:183], v[100:103]
	v_mfma_f32_16x16x32_bf16 v[104:107], v[136:139], v[180:183], v[104:107]
	v_mfma_f32_16x16x32_bf16 v[104:107], v[140:143], v[184:187], v[104:107]
	v_mfma_f32_16x16x32_bf16 v[108:111], v[132:135], v[184:187], v[108:111]
	v_mfma_f32_16x16x32_bf16 v[108:111], v[128:131], v[180:183], v[108:111]
	s_setprio 0
	s_setprio 1
	v_mfma_f32_16x16x32_bf16 v[92:95], v[128:131], v[188:191], v[92:95]
	v_mfma_f32_16x16x32_bf16 v[92:95], v[132:135], v[204:207], v[92:95]
	v_mfma_f32_16x16x32_bf16 v[88:91], v[140:143], v[204:207], v[88:91]
	v_mfma_f32_16x16x32_bf16 v[88:91], v[136:139], v[188:191], v[88:91]
	v_mfma_f32_16x16x32_bf16 v[84:87], v[150:153], v[188:191], v[84:87]
	v_mfma_f32_16x16x32_bf16 v[84:87], v[154:157], v[204:207], v[84:87]
	v_mfma_f32_16x16x32_bf16 v[80:83], v[168:171], v[204:207], v[80:83]
	v_mfma_f32_16x16x32_bf16 v[80:83], v[164:167], v[188:191], v[80:83]
	v_mfma_f32_16x16x32_bf16 v[64:67], v[164:167], v[208:211], v[64:67]
	v_mfma_f32_16x16x32_bf16 v[64:67], v[168:171], v[212:215], v[64:67]
	v_mfma_f32_16x16x32_bf16 v[68:71], v[154:157], v[212:215], v[68:71]
	v_mfma_f32_16x16x32_bf16 v[68:71], v[150:153], v[208:211], v[68:71]
	v_mfma_f32_16x16x32_bf16 v[72:75], v[136:139], v[208:211], v[72:75]
	v_mfma_f32_16x16x32_bf16 v[72:75], v[140:143], v[212:215], v[72:75]
	s_setprio 3
	s_barrier
	v_mfma_f32_16x16x32_bf16 v[76:79], v[132:135], v[212:215], v[76:79]
	v_mfma_f32_16x16x32_bf16 v[76:79], v[128:131], v[208:211], v[76:79]
	s_setprio 0
	s_add_i32 s50, s41, s30
	v_lshl_add_u64 v[158:159], s[22:23], 0, v[160:161]
	s_mov_b32 m0, s50
	ds_read_b128 v[172:175], v201 offset:16384
	ds_read_b128 v[176:179], v201 offset:17408
	ds_read_b128 v[180:183], v201 offset:18432
	ds_read_b128 v[184:187], v201 offset:19456
	ds_read_b128 v[188:191], v201 offset:20480
	ds_read_b128 v[204:207], v201 offset:21504
	ds_read_b128 v[208:211], v201 offset:22528
	ds_read_b128 v[212:215], v201 offset:23552
	global_load_lds_dwordx4 v[158:159], off
	s_add_i32 m0, s50, 0x2000
	s_add_u32 s50, s22, 0x160000
	v_lshl_add_u64 v[192:193], s[22:23], 0, v[162:163]
	s_addc_u32 s51, s23, 0
	s_add_i32 s52, s42, s30
	global_load_lds_dwordx4 v[192:193], off
	v_lshl_add_u64 v[216:217], s[50:51], 0, v[160:161]
	s_mov_b32 m0, s52
	v_lshl_add_u64 v[218:219], s[24:25], 0, v[162:163]
	global_load_lds_dwordx4 v[216:217], off
	v_lshl_add_u64 v[216:217], s[50:51], 0, v[162:163]
	s_add_i32 m0, s52, 0x2000
	s_nop 0
	global_load_lds_dwordx4 v[216:217], off
	v_lshl_add_u64 v[216:217], s[24:25], 0, v[160:161]
	s_mov_b32 m0, s31
	s_nop 0
	global_load_lds_dwordx4 v[216:217], off
	s_mov_b32 m0, s33
	s_nop 0
	global_load_lds_dwordx4 v[218:219], off
	s_waitcnt vmcnt(8)
	s_waitcnt lgkmcnt(0)
	s_barrier
; #define PG8_STAGE(bufoff, gbase, voff) do { _Pragma("unroll") for (int _i = 0; _i < 2; ++_i) \
;         __builtin_amdgcn_global_load_lds((const unsigned*)((const char*)(gbase) + (voff)[_i]), (PG8_LAS unsigned*)(lds + (bufoff) + ldsw + _i * 8192), 16, 0, 0); } while (0)
; #define PG8_LDA(dst, b, h) do { _Pragma("unroll") for (int m = 0; m < 4; ++m) _Pragma("unroll") for (int k = 0; k < 2; ++k) dst[m][k] = *(const PG8_LAS bf16x8*)(lds + PG8_SA(b, h) + aoff + m * 2048 + k * 1024); } while (0)
; #define PG8_LDB(dst, b, h) do { _Pragma("unroll") for (int n = 0; n < 2; ++n) _Pragma("unroll") for (int k = 0; k < 2; ++k) dst[n][k] = *(const PG8_LAS bf16x8*)(lds + PG8_SB(b, h) + boff + n * 2048 + k * 1024); } while (0)
; #define PG8_MMA(ai, bj, At, Bt) do { __builtin_amdgcn_s_setprio(1); _Pragma("unroll") for (int m = 0; m < 4; ++m) _Pragma("unroll") for (int n = 0; n < 2; ++n) _Pragma("unroll") for (int k = 0; k < 2; ++k) \
;         acc[ai][bj][m][n] = __builtin_amdgcn_mfma_f32_16x16x32_bf16(Bt[n][k], At[m][k], acc[ai][bj][m][n], 0, 0, 0); __builtin_amdgcn_s_setprio(0); } while (0)
; #define PG8_WAIT_V(n) asm volatile("s_waitcnt vmcnt(" #n ")" ::: "memory")
; #define PG8_WAIT_L(n) asm volatile("s_waitcnt lgkmcnt(" #n ")" ::: "memory")
; #define PG8_BAR __builtin_amdgcn_s_barrier()
; #define PG8_SCHED __builtin_amdgcn_sched_barrier(0)
; template <class Epi, class Sched, bool ALIGN_EPI = false, bool SP2 = false>
; __device__ __forceinline__ void gemm_phase(PG8_LAS unsigned char* lds, const Gemm g, const Sched& S, const Epi& E) {
;     ...
;             PG8_WAIT_V(8); PG8_WAIT_L(0); PG8_BAR; PG8_MMA(1, 0, At, B0); PG8_MMA(1, 1, At, B1); PG8_BAR; PG8_SCHED;
;             PG8_LDB(B0, 1, 0); PG8_LDB(B1, 1, 1); PG8_SCHED; PG8_LDA(At, 1, 0); PG8_STAGE(PG8_SA(0, 1), a2 + hstep, voffA);
;             PG8_WAIT_V(8); PG8_WAIT_L(0); PG8_BAR; PG8_MMA(0, 0, At, B0); PG8_MMA(0, 1, At, B1); PG8_BAR; PG8_SCHED;
	s_setprio 1
	s_waitcnt lgkmcnt(0)
	v_mfma_f32_16x16x32_bf16 v[60:63], v[128:131], v[172:175], v[60:63]
	v_mfma_f32_16x16x32_bf16 v[60:63], v[132:135], v[176:179], v[60:63]
	v_mfma_f32_16x16x32_bf16 v[56:59], v[140:143], v[176:179], v[56:59]
	v_mfma_f32_16x16x32_bf16 v[56:59], v[136:139], v[172:175], v[56:59]
	v_mfma_f32_16x16x32_bf16 v[52:55], v[150:153], v[172:175], v[52:55]
	v_mfma_f32_16x16x32_bf16 v[52:55], v[154:157], v[176:179], v[52:55]
	v_mfma_f32_16x16x32_bf16 v[48:51], v[168:171], v[176:179], v[48:51]
	v_mfma_f32_16x16x32_bf16 v[48:51], v[164:167], v[172:175], v[48:51]
	v_mfma_f32_16x16x32_bf16 v[32:35], v[164:167], v[180:183], v[32:35]
	v_mfma_f32_16x16x32_bf16 v[32:35], v[168:171], v[184:187], v[32:35]
	v_mfma_f32_16x16x32_bf16 v[36:39], v[154:157], v[184:187], v[36:39]
	v_mfma_f32_16x16x32_bf16 v[36:39], v[150:153], v[180:183], v[36:39]
	v_mfma_f32_16x16x32_bf16 v[40:43], v[136:139], v[180:183], v[40:43]
	v_mfma_f32_16x16x32_bf16 v[40:43], v[140:143], v[184:187], v[40:43]
	v_mfma_f32_16x16x32_bf16 v[44:47], v[132:135], v[184:187], v[44:47]
	v_mfma_f32_16x16x32_bf16 v[44:47], v[128:131], v[180:183], v[44:47]
	s_setprio 0
	s_setprio 1
	v_mfma_f32_16x16x32_bf16 v[28:31], v[128:131], v[188:191], v[28:31]
	v_mfma_f32_16x16x32_bf16 v[28:31], v[132:135], v[204:207], v[28:31]
	v_mfma_f32_16x16x32_bf16 v[24:27], v[140:143], v[204:207], v[24:27]
	v_mfma_f32_16x16x32_bf16 v[24:27], v[136:139], v[188:191], v[24:27]
	v_mfma_f32_16x16x32_bf16 v[20:23], v[150:153], v[188:191], v[20:23]
	v_mfma_f32_16x16x32_bf16 v[20:23], v[154:157], v[204:207], v[20:23]
	v_mfma_f32_16x16x32_bf16 v[16:19], v[168:171], v[204:207], v[16:19]
	v_mfma_f32_16x16x32_bf16 v[16:19], v[164:167], v[188:191], v[16:19]
	v_mfma_f32_16x16x32_bf16 v[0:3], v[164:167], v[208:211], v[0:3]
	v_mfma_f32_16x16x32_bf16 v[0:3], v[168:171], v[212:215], v[0:3]
	v_mfma_f32_16x16x32_bf16 v[4:7], v[154:157], v[212:215], v[4:7]
	v_mfma_f32_16x16x32_bf16 v[4:7], v[150:153], v[208:211], v[4:7]
	v_mfma_f32_16x16x32_bf16 v[8:11], v[136:139], v[208:211], v[8:11]
	v_mfma_f32_16x16x32_bf16 v[8:11], v[140:143], v[212:215], v[8:11]
	s_setprio 3
	s_barrier
	v_mfma_f32_16x16x32_bf16 v[12:15], v[132:135], v[212:215], v[12:15]
	v_mfma_f32_16x16x32_bf16 v[12:15], v[128:131], v[208:211], v[12:15]
	s_setprio 0
	s_add_i32 s50, 0, 0x18000
	s_add_i32 s51, 0, 0x1c000
	v_add_u32_e32 v140, s50, v196
	v_add_u32_e32 v168, s51, v196
	ds_read_b128 v[128:131], v140
	ds_read_b128 v[132:135], v140 offset:1024
	ds_read_b128 v[136:139], v140 offset:2048
	ds_read_b128 v[140:143], v140 offset:3072
	ds_read_b128 v[150:153], v168
	ds_read_b128 v[154:157], v168 offset:1024
	ds_read_b128 v[164:167], v168 offset:2048
	ds_read_b128 v[168:171], v168 offset:3072
	s_add_u32 s24, s24, 0x160000
	s_addc_u32 s25, s25, 0
	s_mov_b32 m0, s34
	v_lshl_add_u64 v[220:221], s[24:25], 0, v[160:161]
	ds_read_b128 v[172:175], v201 offset:32768
	ds_read_b128 v[176:179], v201 offset:33792
	ds_read_b128 v[180:183], v201 offset:34816
	ds_read_b128 v[184:187], v201 offset:35840
	ds_read_b128 v[188:191], v201 offset:36864
	ds_read_b128 v[204:207], v201 offset:37888
	ds_read_b128 v[208:211], v201 offset:38912
	ds_read_b128 v[212:215], v201 offset:39936
	global_load_lds_dwordx4 v[220:221], off
	v_lshl_add_u64 v[220:221], s[24:25], 0, v[162:163]
	s_mov_b32 m0, s35
	s_nop 0
	global_load_lds_dwordx4 v[220:221], off
	s_waitcnt vmcnt(8)
	s_waitcnt lgkmcnt(0)
	s_barrier
	s_setprio 1
	s_waitcnt lgkmcnt(0)
	v_mfma_f32_16x16x32_bf16 v[124:127], v[128:131], v[172:175], v[124:127]
	v_mfma_f32_16x16x32_bf16 v[124:127], v[132:135], v[176:179], v[124:127]
	v_mfma_f32_16x16x32_bf16 v[120:123], v[140:143], v[176:179], v[120:123]
	v_mfma_f32_16x16x32_bf16 v[120:123], v[136:139], v[172:175], v[120:123]
	v_mfma_f32_16x16x32_bf16 v[116:119], v[150:153], v[172:175], v[116:119]
	v_mfma_f32_16x16x32_bf16 v[116:119], v[154:157], v[176:179], v[116:119]
	v_mfma_f32_16x16x32_bf16 v[112:115], v[168:171], v[176:179], v[112:115]
	v_mfma_f32_16x16x32_bf16 v[112:115], v[164:167], v[172:175], v[112:115]
	v_mfma_f32_16x16x32_bf16 v[96:99], v[164:167], v[180:183], v[96:99]
	v_mfma_f32_16x16x32_bf16 v[96:99], v[168:171], v[184:187], v[96:99]
	v_mfma_f32_16x16x32_bf16 v[100:103], v[154:157], v[184:187], v[100:103]
	v_mfma_f32_16x16x32_bf16 v[100:103], v[150:153], v[180:183], v[100:103]
	v_mfma_f32_16x16x32_bf16 v[104:107], v[136:139], v[180:183], v[104:107]
	v_mfma_f32_16x16x32_bf16 v[104:107], v[140:143], v[184:187], v[104:107]
	v_mfma_f32_16x16x32_bf16 v[108:111], v[132:135], v[184:187], v[108:111]
	v_mfma_f32_16x16x32_bf16 v[108:111], v[128:131], v[180:183], v[108:111]
	s_setprio 0
	s_setprio 1
	v_mfma_f32_16x16x32_bf16 v[92:95], v[128:131], v[188:191], v[92:95]
	v_mfma_f32_16x16x32_bf16 v[92:95], v[132:135], v[204:207], v[92:95]
	v_mfma_f32_16x16x32_bf16 v[88:91], v[140:143], v[204:207], v[88:91]
	v_mfma_f32_16x16x32_bf16 v[88:91], v[136:139], v[188:191], v[88:91]
	v_mfma_f32_16x16x32_bf16 v[84:87], v[150:153], v[188:191], v[84:87]
	v_mfma_f32_16x16x32_bf16 v[84:87], v[154:157], v[204:207], v[84:87]
	v_mfma_f32_16x16x32_bf16 v[80:83], v[168:171], v[204:207], v[80:83]
	v_mfma_f32_16x16x32_bf16 v[80:83], v[164:167], v[188:191], v[80:83]
	v_mfma_f32_16x16x32_bf16 v[64:67], v[164:167], v[208:211], v[64:67]
	v_mfma_f32_16x16x32_bf16 v[64:67], v[168:171], v[212:215], v[64:67]
	v_mfma_f32_16x16x32_bf16 v[68:71], v[154:157], v[212:215], v[68:71]
	v_mfma_f32_16x16x32_bf16 v[68:71], v[150:153], v[208:211], v[68:71]
	v_mfma_f32_16x16x32_bf16 v[72:75], v[136:139], v[208:211], v[72:75]
	v_mfma_f32_16x16x32_bf16 v[72:75], v[140:143], v[212:215], v[72:75]
	s_setprio 3
	s_barrier
; #define PG8_STAGE(bufoff, gbase, voff) do { _Pragma("unroll") for (int _i = 0; _i < 2; ++_i) \
;         __builtin_amdgcn_global_load_lds((const unsigned*)((const char*)(gbase) + (voff)[_i]), (PG8_LAS unsigned*)(lds + (bufoff) + ldsw + _i * 8192), 16, 0, 0); } while (0)
; #define PG8_LDA(dst, b, h) do { _Pragma("unroll") for (int m = 0; m < 4; ++m) _Pragma("unroll") for (int k = 0; k < 2; ++k) dst[m][k] = *(const PG8_LAS bf16x8*)(lds + PG8_SA(b, h) + aoff + m * 2048 + k * 1024); } while (0)
; #define PG8_MMA(ai, bj, At, Bt) do { __builtin_amdgcn_s_setprio(1); _Pragma("unroll") for (int m = 0; m < 4; ++m) _Pragma("unroll") for (int n = 0; n < 2; ++n) _Pragma("unroll") for (int k = 0; k < 2; ++k) \
;         acc[ai][bj][m][n] = __builtin_amdgcn_mfma_f32_16x16x32_bf16(Bt[n][k], At[m][k], acc[ai][bj][m][n], 0, 0, 0); __builtin_amdgcn_s_setprio(0); } while (0)
; #define PG8_WAIT_V(n) asm volatile("s_waitcnt vmcnt(" #n ")" ::: "memory")
; #define PG8_WAIT_L(n) asm volatile("s_waitcnt lgkmcnt(" #n ")" ::: "memory")
; #define PG8_BAR __builtin_amdgcn_s_barrier()
; #define PG8_SCHED __builtin_amdgcn_sched_barrier(0)
; template <class Epi, class Sched, bool ALIGN_EPI = false, bool SP2 = false>
; __device__ __forceinline__ void gemm_phase(PG8_LAS unsigned char* lds, const Gemm g, const Sched& S, const Epi& E) {
;     ...
;         for (int t = 0; t < nt; t += 2) {
;     ...
;             PG8_LDA(At, 1, 1); PG8_STAGE(PG8_SB(1, 0), b3, voffB); PG8_STAGE(PG8_SB(1, 1), b3 + hstep, voffB); PG8_STAGE(PG8_SA(1, 0), a3, voffA);
;             PG8_WAIT_V(8); PG8_WAIT_L(0); PG8_BAR; PG8_MMA(1, 0, At, B0); PG8_MMA(1, 1, At, B1); PG8_BAR; PG8_SCHED;
	v_mfma_f32_16x16x32_bf16 v[76:79], v[132:135], v[212:215], v[76:79]
	v_mfma_f32_16x16x32_bf16 v[76:79], v[128:131], v[208:211], v[76:79]
	s_setprio 0
	s_add_i32 s24, s50, s30
	v_lshl_add_u64 v[158:159], v[158:159], 0, s[12:13]
	s_mov_b32 m0, s24
	ds_read_b128 v[172:175], v201 offset:49152
	ds_read_b128 v[176:179], v201 offset:50176
	ds_read_b128 v[180:183], v201 offset:51200
	ds_read_b128 v[184:187], v201 offset:52224
	ds_read_b128 v[188:191], v201 offset:53248
	ds_read_b128 v[204:207], v201 offset:54272
	ds_read_b128 v[208:211], v201 offset:55296
	ds_read_b128 v[212:215], v201 offset:56320
	global_load_lds_dwordx4 v[158:159], off
	s_add_i32 m0, s24, 0x2000
	s_add_u32 s22, s22, 0x160080
	v_lshl_add_u64 v[158:159], v[192:193], 0, s[12:13]
	s_addc_u32 s23, s23, 0
	s_add_i32 s24, s51, s30
	global_load_lds_dwordx4 v[158:159], off
	v_lshl_add_u64 v[158:159], s[22:23], 0, v[160:161]
	s_mov_b32 m0, s24
	s_nop 0
	global_load_lds_dwordx4 v[158:159], off
	v_lshl_add_u64 v[158:159], s[22:23], 0, v[162:163]
	s_add_i32 m0, s24, 0x2000
	s_nop 0
	global_load_lds_dwordx4 v[158:159], off
	v_lshl_add_u64 v[158:159], v[216:217], 0, s[12:13]
	s_mov_b32 m0, s39
	s_nop 0
	global_load_lds_dwordx4 v[158:159], off
	v_lshl_add_u64 v[158:159], v[218:219], 0, s[12:13]
	s_mov_b32 m0, s40
	s_nop 0
	global_load_lds_dwordx4 v[158:159], off
	s_waitcnt vmcnt(8)
	s_waitcnt lgkmcnt(0)
	s_barrier
	s_setprio 1
	s_waitcnt lgkmcnt(0)
	v_mfma_f32_16x16x32_bf16 v[60:63], v[128:131], v[172:175], v[60:63]
	v_mfma_f32_16x16x32_bf16 v[60:63], v[132:135], v[176:179], v[60:63]
	v_mfma_f32_16x16x32_bf16 v[56:59], v[140:143], v[176:179], v[56:59]
	v_mfma_f32_16x16x32_bf16 v[56:59], v[136:139], v[172:175], v[56:59]
	v_mfma_f32_16x16x32_bf16 v[52:55], v[150:153], v[172:175], v[52:55]
	v_mfma_f32_16x16x32_bf16 v[52:55], v[154:157], v[176:179], v[52:55]
	v_mfma_f32_16x16x32_bf16 v[48:51], v[168:171], v[176:179], v[48:51]
	v_mfma_f32_16x16x32_bf16 v[48:51], v[164:167], v[172:175], v[48:51]
	v_mfma_f32_16x16x32_bf16 v[32:35], v[164:167], v[180:183], v[32:35]
	v_mfma_f32_16x16x32_bf16 v[32:35], v[168:171], v[184:187], v[32:35]
	v_mfma_f32_16x16x32_bf16 v[36:39], v[154:157], v[184:187], v[36:39]
	v_mfma_f32_16x16x32_bf16 v[36:39], v[150:153], v[180:183], v[36:39]
	v_mfma_f32_16x16x32_bf16 v[40:43], v[136:139], v[180:183], v[40:43]
	v_mfma_f32_16x16x32_bf16 v[40:43], v[140:143], v[184:187], v[40:43]
	v_mfma_f32_16x16x32_bf16 v[44:47], v[132:135], v[184:187], v[44:47]
	v_mfma_f32_16x16x32_bf16 v[44:47], v[128:131], v[180:183], v[44:47]
	s_setprio 0
	s_setprio 1
	v_mfma_f32_16x16x32_bf16 v[28:31], v[128:131], v[188:191], v[28:31]
	v_mfma_f32_16x16x32_bf16 v[28:31], v[132:135], v[204:207], v[28:31]
	v_mfma_f32_16x16x32_bf16 v[24:27], v[140:143], v[204:207], v[24:27]
	v_mfma_f32_16x16x32_bf16 v[24:27], v[136:139], v[188:191], v[24:27]
	v_mfma_f32_16x16x32_bf16 v[20:23], v[150:153], v[188:191], v[20:23]
	v_mfma_f32_16x16x32_bf16 v[20:23], v[154:157], v[204:207], v[20:23]
	v_mfma_f32_16x16x32_bf16 v[16:19], v[168:171], v[204:207], v[16:19]
	v_mfma_f32_16x16x32_bf16 v[16:19], v[164:167], v[188:191], v[16:19]
	v_mfma_f32_16x16x32_bf16 v[0:3], v[164:167], v[208:211], v[0:3]
	v_mfma_f32_16x16x32_bf16 v[0:3], v[168:171], v[212:215], v[0:3]
	v_mfma_f32_16x16x32_bf16 v[4:7], v[154:157], v[212:215], v[4:7]
	v_mfma_f32_16x16x32_bf16 v[4:7], v[150:153], v[208:211], v[4:7]
	v_mfma_f32_16x16x32_bf16 v[8:11], v[136:139], v[208:211], v[8:11]
	v_mfma_f32_16x16x32_bf16 v[8:11], v[140:143], v[212:215], v[8:11]
	s_setprio 3
	s_barrier
	v_mfma_f32_16x16x32_bf16 v[12:15], v[132:135], v[212:215], v[12:15]
	v_mfma_f32_16x16x32_bf16 v[12:15], v[128:131], v[208:211], v[12:15]
	s_setprio 0
	s_add_i32 s49, s49, 2
	s_add_u32 s20, s20, 0x100
	s_addc_u32 s21, s21, 0
	s_add_u32 s47, s47, 0x100
	s_addc_u32 s48, s48, 0
	s_cmpk_gt_u32 s49, 0x55
	s_cbranch_scc0 .LBB0_937
	s_and_b64 vcc, exec, s[14:15]
	s_cbranch_vccz .LBB0_940
	s_barrier
